# De-serialised the raw tile loads of both GLA units (issue all 16-byte loads, one wait, then the LDS writes) on top of the previous version
# speedup vs baseline: 1.0087x; 1.0060x over previous
; #define LAS __attribute__((address_space(3)))
; #define LAS __attribute__((address_space(3)))
; template <int MODE>
; DI void gla4_unit(const bf16_t* z, float* ST, float* DEC, bf16_t* Y, const float* aw_g, const float* ab_g, const float* ng, ldsp lds, int tid, int u) {
;     ...
;         for (int i = 0; i < NM * 4; ++i) {
;             const int pi = tid + 512 * i, mh = pi >> 9, mat = mh >> 2, head = mh & 3, row = (pi >> 3) & 63, pc = pi & 7;
;             const int col = (MODE ? (mat == 0 ? C_GQ : (mat == 1 ? C_GK : C_GV)) : (mat == 0 ? C_GK : C_GV)) + head * 64 + pc * 8;
;             const int reg = MODE ? mat * 9216 : (mat == 0 ? 0 : G4_R2);
;             *(LAS u32x4*)(lds + head * G4_HEAD + reg + row * 144 + pc * 16) = *(const u32x4*)(z + (size_t)(tok0 + row) * ZLD + col);
;         }
.LBB0_407:
	s_or_b64 exec, exec, s[0:1]
	s_add_i32 s0, s6, 0
	s_add_i32 s0, s0, 0x20010
	v_mov_b32_e32 v0, s0
	s_waitcnt lgkmcnt(0)
	s_barrier
	ds_read_b32 v0, v0
	s_movk_i32 s0, 0xbf
	s_waitcnt lgkmcnt(0)
	v_cmp_lt_i32_e32 vcc, s0, v0
	v_readfirstlane_b32 s28, v0
	s_mov_b64 s[0:1], -1
	s_cbranch_vccnz .LBB0_402
	v_mov_b32_e32 v80, v136
	s_cmpk_gt_i32 s28, 0x7f
	v_and_b32_e32 v81, 15, v80
	v_and_b32_e32 v178, 63, v80
	v_bfe_u32 v177, v80, 4, 2
	s_cbranch_scc0 .LBB0_410
	s_add_i32 s30, s28, s83
	v_ashrrev_i32_e32 v14, 11, v80
	s_add_i32 s0, s30, 0xffffff80
	v_cmp_eq_u32_e32 vcc, 1, v14
	s_lshl_b32 s29, s0, 6
	v_bfe_u32 v4, v80, 3, 6
	v_and_b32_e32 v5, 7, v80
	v_bfe_u32 v15, v80, 9, 2
	v_cndmask_b32_e32 v7, v200, v201, vcc
	v_cmp_lt_u32_e32 vcc, s94, v80
	v_lshlrev_b32_e32 v6, 3, v5
	v_or_b32_e32 v0, s29, v4
	v_cndmask_b32_e32 v8, v202, v7, vcc
	v_lshlrev_b32_e32 v7, 6, v15
	v_mul_lo_u32 v156, v0, s52
	v_or3_b32 v8, v6, v8, v7
	v_lshl_add_u64 v[0:1], v[156:157], 1, s[70:71]
	v_lshlrev_b32_e32 v156, 1, v8
	v_lshl_add_u64 v[8:9], v[0:1], 0, v[156:157]
	s_barrier
	global_load_dwordx4 v[86:89], v[8:9], off
	v_mad_u32_u24 v8, v15, s5, 0
	v_mul_u32_u24_e32 v4, 0x90, v4
	v_lshlrev_b32_e32 v5, 4, v5
	v_mad_i32_i24 v9, v14, s95, v8
	v_add3_u32 v9, v9, v4, v5
	s_movk_i32 s1, 0xf800
	s_lshr_b32 s0, s0, 5
	v_ashrrev_i32_e32 v2, 7, v80
	s_and_b32 s0, s0, 12
	v_mov_b64_e32 v[32:33], s[70:71]
	v_add_u32_e32 v28, s0, v2
	v_lshlrev_b32_e32 v34, 6, v2
	v_bfe_u32 v29, v80, 6, 1
	v_mul_lo_u32 v3, v2, s5
	v_lshlrev_b32_e32 v2, 8, v2
	v_mov_b32_e32 v142, v9
	v_add_u32_e32 v9, 0x200, v80
	v_ashrrev_i32_e32 v10, 11, v9
	v_cmp_eq_u32_e32 vcc, 1, v10
	v_bfe_u32 v14, v9, 9, 2
	v_mul_i32_i24_e32 v15, 0x2400, v10
	v_cndmask_b32_e32 v11, v200, v201, vcc
	v_cmp_lt_u32_e32 vcc, s94, v9
	s_nop 1
	v_cndmask_b32_e32 v9, v202, v11, vcc
	v_lshlrev_b32_e32 v11, 6, v14
	v_or3_b32 v9, v9, v11, v6
	v_lshlrev_b32_e32 v156, 1, v9
	v_lshl_add_u64 v[10:11], v[0:1], 0, v[156:157]
	global_load_dwordx4 v[90:93], v[10:11], off
	v_mul_u32_u24_e32 v9, 0x6c00, v14
	v_add3_u32 v9, 0, v9, v15
	v_add3_u32 v9, v9, v4, v5
	v_mov_b32_e32 v143, v9
	v_add_u32_e32 v9, 0x400, v80
	v_ashrrev_i32_e32 v10, 11, v9
	v_cmp_eq_u32_e32 vcc, 1, v10
	v_bfe_u32 v14, v9, 9, 2
	v_mul_i32_i24_e32 v15, 0x2400, v10
	v_cndmask_b32_e32 v11, v200, v201, vcc
	v_cmp_lt_u32_e32 vcc, s94, v9
	s_nop 1
	v_cndmask_b32_e32 v9, v202, v11, vcc
	v_lshlrev_b32_e32 v11, 6, v14
	v_or3_b32 v9, v9, v11, v6
	v_lshlrev_b32_e32 v156, 1, v9
	v_lshl_add_u64 v[10:11], v[0:1], 0, v[156:157]
	global_load_dwordx4 v[94:97], v[10:11], off
	v_mul_u32_u24_e32 v9, 0x6c00, v14
	v_add3_u32 v9, 0, v9, v15
	v_add3_u32 v9, v9, v4, v5
	v_mov_b32_e32 v144, v9
	v_add_u32_e32 v9, 0x600, v80
	v_ashrrev_i32_e32 v10, 11, v9
	v_cmp_eq_u32_e32 vcc, 1, v10
	v_bfe_u32 v14, v9, 9, 2
	v_mul_i32_i24_e32 v15, 0x2400, v10
	v_cndmask_b32_e32 v11, v200, v201, vcc
	v_cmp_lt_u32_e32 vcc, s94, v9
	s_nop 1
	v_cndmask_b32_e32 v9, v202, v11, vcc
	v_lshlrev_b32_e32 v11, 6, v14
	v_or3_b32 v9, v9, v11, v6
	v_lshlrev_b32_e32 v156, 1, v9
	v_lshl_add_u64 v[10:11], v[0:1], 0, v[156:157]
	global_load_dwordx4 v[98:101], v[10:11], off
	v_mul_u32_u24_e32 v9, 0x6c00, v14
	v_add3_u32 v9, 0, v9, v15
	v_add3_u32 v9, v9, v4, v5
	v_mov_b32_e32 v145, v9
	v_add_u32_e32 v9, 0x800, v80
	v_ashrrev_i32_e32 v9, 11, v9
	v_cmp_eq_u32_e32 vcc, 1, v9
	v_mad_i32_i24 v9, v9, s95, v8
	v_add3_u32 v9, v9, v4, v5
	v_cndmask_b32_e32 v10, v200, v201, vcc
	v_cmp_gt_u32_e32 vcc, s1, v80
	s_nop 1
	v_cndmask_b32_e32 v10, v202, v10, vcc
	v_or3_b32 v10, v6, v10, v7
	v_lshlrev_b32_e32 v156, 1, v10
	v_lshl_add_u64 v[10:11], v[0:1], 0, v[156:157]
	global_load_dwordx4 v[102:105], v[10:11], off
	v_mov_b32_e32 v146, v9
	v_add_u32_e32 v9, 0xa00, v80
	v_ashrrev_i32_e32 v10, 11, v9
	v_cmp_eq_u32_e32 vcc, 1, v10
	v_bfe_u32 v14, v9, 9, 2
	v_mul_i32_i24_e32 v15, 0x2400, v10
	v_cndmask_b32_e32 v11, v200, v201, vcc
	v_cmp_lt_u32_e32 vcc, s94, v9
	s_nop 1
	v_cndmask_b32_e32 v9, v202, v11, vcc
	v_lshlrev_b32_e32 v11, 6, v14
	v_or3_b32 v9, v9, v11, v6
	v_lshlrev_b32_e32 v156, 1, v9
	v_lshl_add_u64 v[10:11], v[0:1], 0, v[156:157]
	global_load_dwordx4 v[106:109], v[10:11], off
	v_mul_u32_u24_e32 v9, 0x6c00, v14
	v_add3_u32 v9, 0, v9, v15
	v_add3_u32 v9, v9, v4, v5
	v_mov_b32_e32 v147, v9
	v_add_u32_e32 v9, 0xc00, v80
	v_ashrrev_i32_e32 v10, 11, v9
	v_cmp_eq_u32_e32 vcc, 1, v10
	v_bfe_u32 v14, v9, 9, 2
	v_mul_i32_i24_e32 v15, 0x2400, v10
	v_cndmask_b32_e32 v11, v200, v201, vcc
	v_cmp_lt_u32_e32 vcc, s94, v9
	s_nop 1
	v_cndmask_b32_e32 v9, v202, v11, vcc
	v_lshlrev_b32_e32 v11, 6, v14
	v_or3_b32 v9, v9, v11, v6
	v_lshlrev_b32_e32 v156, 1, v9
	v_lshl_add_u64 v[10:11], v[0:1], 0, v[156:157]
	global_load_dwordx4 v[110:113], v[10:11], off
	v_mul_u32_u24_e32 v9, 0x6c00, v14
	v_add3_u32 v9, 0, v9, v15
	v_add3_u32 v9, v9, v4, v5
	v_mov_b32_e32 v148, v9
	v_add_u32_e32 v9, 0xe00, v80
	v_ashrrev_i32_e32 v10, 11, v9
	v_cmp_eq_u32_e32 vcc, 1, v10
	v_bfe_u32 v14, v9, 9, 2
	v_mul_i32_i24_e32 v15, 0x2400, v10
	v_cndmask_b32_e32 v11, v200, v201, vcc
	v_cmp_lt_u32_e32 vcc, s94, v9
	s_nop 1
	v_cndmask_b32_e32 v9, v202, v11, vcc
	v_lshlrev_b32_e32 v11, 6, v14
	v_or3_b32 v9, v9, v11, v6
	v_lshlrev_b32_e32 v156, 1, v9
	v_lshl_add_u64 v[10:11], v[0:1], 0, v[156:157]
	global_load_dwordx4 v[120:123], v[10:11], off
	v_mul_u32_u24_e32 v9, 0x6c00, v14
	v_add3_u32 v9, 0, v9, v15
	v_add3_u32 v9, v9, v4, v5
	v_mov_b32_e32 v149, v9
	v_add_u32_e32 v9, 0x1000, v80
	v_ashrrev_i32_e32 v14, 11, v9
	v_cmp_eq_u32_e32 vcc, 1, v14
	s_nop 1
	v_cndmask_b32_e32 v10, v200, v201, vcc
	v_cmp_lt_u32_e32 vcc, s94, v9
	s_nop 1
	v_cndmask_b32_e32 v9, v202, v10, vcc
	v_or3_b32 v7, v6, v9, v7
; #define LAS __attribute__((address_space(3)))
; #define LAS __attribute__((address_space(3)))
; DI float bflo(unsigned v) { return __uint_as_float(v << 16); }
; DI float bfhi(unsigned v) { return __uint_as_float(v & 0xffff0000u); }
; DI float log_sigmoid_fast(float x) { return fminf(x, 0.f) - __logf(1.0f + __expf(-fabsf(x))); }
; template <int MODE>
; DI void gla4_unit(const bf16_t* z, float* ST, float* DEC, bf16_t* Y, const float* aw_g, const float* ab_g, const float* ng, ldsp lds, int tid, int u) {
;     ...
;         for (int i = 0; i < NM * 4; ++i) {
;             const int pi = tid + 512 * i, mh = pi >> 9, mat = mh >> 2, head = mh & 3, row = (pi >> 3) & 63, pc = pi & 7;
;             const int col = (MODE ? (mat == 0 ? C_GQ : (mat == 1 ? C_GK : C_GV)) : (mat == 0 ? C_GK : C_GV)) + head * 64 + pc * 8;
;             const int reg = MODE ? mat * 9216 : (mat == 0 ? 0 : G4_R2);
;             *(LAS u32x4*)(lds + head * G4_HEAD + reg + row * 144 + pc * 16) = *(const u32x4*)(z + (size_t)(tok0 + row) * ZLD + col);
;         }
;         const int idx = tid * 2, t = idx >> 4, r = idx & 15;
;         const unsigned v = *(const unsigned*)(z + (size_t)(tok0 + t) * ZLD + C_GA + r);
;         alr[t * 16 + r] = bflo(v); alr[t * 16 + r + 1] = bfhi(v);
;     }
;     float aw[16];
; #pragma unroll
;     for (int r = 0; r < 16; ++r) aw[r] = aw_g[r * 256 + hd * 64 + d];
;     const float ab = ab_g[hd * 64 + d];
;     __syncthreads();
;     float bc[32];
;     {
;         float run = 0.f;
; #pragma unroll
;         for (int i = 0; i < 32; ++i) {
;             const int t = 32 * half + i;
;             float al = ab;
; #pragma unroll
;             for (int r = 0; r < 16; ++r) al += alr[t * 16 + r] * aw[r];
;             run += log_sigmoid_fast(al) * (1.0f / 16.0f);
;             bc[i] = run;
;         }
	v_lshlrev_b32_e32 v156, 1, v7
	v_lshl_add_u64 v[10:11], v[0:1], 0, v[156:157]
	global_load_dwordx4 v[124:127], v[10:11], off
	v_mad_i32_i24 v7, v14, s95, v8
	v_add3_u32 v7, v7, v4, v5
	v_mov_b32_e32 v150, v7
	v_add_u32_e32 v7, 0x1200, v80
	v_ashrrev_i32_e32 v8, 11, v7
	v_cmp_eq_u32_e32 vcc, 1, v8
	v_bfe_u32 v12, v7, 9, 2
	v_mul_i32_i24_e32 v13, 0x2400, v8
	v_cndmask_b32_e32 v9, v200, v201, vcc
	v_cmp_lt_u32_e32 vcc, s94, v7
	s_nop 1
	v_cndmask_b32_e32 v7, v202, v9, vcc
	v_lshlrev_b32_e32 v9, 6, v12
	v_or3_b32 v7, v7, v9, v6
	v_lshlrev_b32_e32 v156, 1, v7
	v_lshl_add_u64 v[8:9], v[0:1], 0, v[156:157]
	global_load_dwordx4 v[128:131], v[8:9], off
	v_mul_u32_u24_e32 v7, 0x6c00, v12
	v_add3_u32 v7, 0, v7, v13
	v_add3_u32 v7, v7, v4, v5
	v_mov_b32_e32 v151, v7
	v_add_u32_e32 v7, 0x1400, v80
	v_ashrrev_i32_e32 v8, 11, v7
	v_cmp_eq_u32_e32 vcc, 1, v8
	v_bfe_u32 v12, v7, 9, 2
	v_mul_i32_i24_e32 v13, 0x2400, v8
	v_cndmask_b32_e32 v9, v200, v201, vcc
	v_cmp_lt_u32_e32 vcc, s94, v7
	s_nop 1
	v_cndmask_b32_e32 v7, v202, v9, vcc
	v_lshlrev_b32_e32 v9, 6, v12
	v_or3_b32 v7, v7, v9, v6
	v_lshlrev_b32_e32 v156, 1, v7
	v_lshl_add_u64 v[8:9], v[0:1], 0, v[156:157]
	global_load_dwordx4 v[132:135], v[8:9], off
	v_mul_u32_u24_e32 v7, 0x6c00, v12
	v_add3_u32 v7, 0, v7, v13
	v_add3_u32 v7, v7, v4, v5
	v_mov_b32_e32 v152, v7
	v_add_u32_e32 v7, 0x1600, v80
	v_ashrrev_i32_e32 v8, 11, v7
	v_cmp_eq_u32_e32 vcc, 1, v8
	v_bfe_u32 v10, v7, 9, 2
	v_mul_i32_i24_e32 v11, 0x2400, v8
	v_cndmask_b32_e32 v9, v200, v201, vcc
	v_cmp_lt_u32_e32 vcc, s94, v7
	s_nop 1
	v_cndmask_b32_e32 v7, v202, v9, vcc
	v_lshlrev_b32_e32 v9, 6, v10
	v_or3_b32 v6, v7, v9, v6
	v_lshlrev_b32_e32 v156, 1, v6
	v_lshl_add_u64 v[0:1], v[0:1], 0, v[156:157]
	global_load_dwordx4 v[138:141], v[0:1], off
	v_mul_u32_u24_e32 v0, 0x6c00, v10
	v_add3_u32 v0, 0, v0, v11
	v_add3_u32 v0, v0, v4, v5
	v_ashrrev_i32_e32 v4, 3, v80
	v_mov_b32_e32 v153, v0
	v_lshlrev_b32_e32 v0, 1, v80
	v_and_b32_e32 v5, 14, v0
	v_add_u32_e32 v0, s29, v4
	v_mad_i64_i32 v[0:1], s[0:1], v0, s97, v[32:33]
	v_lshlrev_b32_e32 v156, 1, v5
	v_lshl_add_u64 v[0:1], v[0:1], 0, v[156:157]
	v_add_co_u32_e32 v0, vcc, s33, v0
	v_lshlrev_b32_e32 v4, 6, v4
	s_nop 0
	v_addc_co_u32_e32 v1, vcc, 0, v1, vcc
	global_load_dword v1, v[0:1], off offset:2560
	v_lshlrev_b32_e32 v5, 2, v5
	v_add3_u32 v4, s98, v4, v5
	v_lshlrev_b32_e32 v156, 5, v177
	s_waitcnt vmcnt(0)
	ds_write_b128 v142, v[86:89]
	ds_write_b128 v143, v[90:93]
	ds_write_b128 v144, v[94:97]
	ds_write_b128 v145, v[98:101]
	ds_write_b128 v146, v[102:105]
	ds_write_b128 v147, v[106:109]
	ds_write_b128 v148, v[110:113]
	ds_write_b128 v149, v[120:123]
	ds_write_b128 v150, v[124:127]
	ds_write_b128 v151, v[128:131]
	ds_write_b128 v152, v[132:135]
	ds_write_b128 v153, v[138:141]
	v_lshlrev_b32_e32 v0, 16, v1
	v_and_b32_e32 v1, 0xffff0000, v1
	ds_write_b64 v4, v[0:1]
	v_or_b32_e32 v0, v34, v178
	v_ashrrev_i32_e32 v1, 31, v0
	v_lshlrev_b64 v[20:21], 2, v[0:1]
	v_lshl_add_u64 v[4:5], s[24:25], 0, v[20:21]
	v_add_co_u32_e32 v6, vcc, s33, v4
	v_lshl_add_u64 v[20:21], s[2:3], 0, v[20:21]
	s_nop 0
	v_addc_co_u32_e32 v7, vcc, 0, v5, vcc
	v_add_co_u32_e32 v10, vcc, s88, v4
	global_load_dword v16, v[4:5], off
	global_load_dword v17, v[4:5], off offset:1024
	global_load_dword v18, v[4:5], off offset:2048
	global_load_dword v19, v[4:5], off offset:3072
	v_addc_co_u32_e32 v11, vcc, 0, v5, vcc
	v_add_co_u32_e32 v22, vcc, s99, v4
	global_load_dword v12, v[10:11], off offset:-4096
	global_load_dword v13, v[6:7], off offset:1024
	global_load_dword v14, v[6:7], off offset:2048
	global_load_dword v15, v[6:7], off offset:3072
	s_nop 0
	global_load_dword v7, v[10:11], off
	global_load_dword v8, v[10:11], off offset:1024
	global_load_dword v9, v[10:11], off offset:2048
	s_nop 0
	global_load_dword v10, v[10:11], off offset:3072
	v_addc_co_u32_e32 v23, vcc, 0, v5, vcc
	global_load_dword v6, v[22:23], off
	global_load_dword v5, v[22:23], off offset:1024
	global_load_dword v4, v[22:23], off offset:2048
	global_load_dword v1, v[22:23], off offset:3072
	global_load_dword v11, v[20:21], off
	v_lshl_add_u32 v21, v29, 11, s98
	s_waitcnt lgkmcnt(0)
	s_barrier
	ds_read_b128 v[22:25], v21
	ds_read_b128 v[36:39], v21 offset:16
	ds_read_b128 v[40:43], v21 offset:32
	ds_read_b128 v[44:47], v21 offset:48
	s_waitcnt vmcnt(0) lgkmcnt(3)
	v_fma_f32 v20, v16, v22, v11
	v_fmac_f32_e32 v20, v17, v23
	v_fmac_f32_e32 v20, v18, v24
	v_fmac_f32_e32 v20, v19, v25
	s_waitcnt lgkmcnt(2)
	v_fmac_f32_e32 v20, v12, v36
	v_fmac_f32_e32 v20, v13, v37
	v_fmac_f32_e32 v20, v14, v38
	v_fmac_f32_e32 v20, v15, v39
	s_waitcnt lgkmcnt(1)
	v_fmac_f32_e32 v20, v7, v40
	v_fmac_f32_e32 v20, v8, v41
	v_fmac_f32_e32 v20, v9, v42
	v_fmac_f32_e32 v20, v10, v43
	s_waitcnt lgkmcnt(0)
	v_fmac_f32_e32 v20, v6, v44
	v_fmac_f32_e32 v20, v5, v45
	v_fmac_f32_e32 v20, v4, v46
	v_fmac_f32_e32 v20, v1, v47
	v_min_f32_e32 v22, 0, v20
	v_mul_f32_e64 v20, |v20|, s46
	v_exp_f32_e32 v20, v20
	ds_read_b128 v[36:39], v21 offset:256
	v_add_f32_e32 v20, 1.0, v20
	v_cmp_gt_f32_e32 vcc, s47, v20
	s_nop 1
	v_cndmask_b32_e64 v23, 0, 32, vcc
	v_ldexp_f32 v20, v20, v23
	v_log_f32_e32 v20, v20
	s_nop 0
	v_mul_f32_e32 v23, 0x3f317217, v20
	v_fma_f32 v23, v20, s4, -v23
	v_fmac_f32_e32 v23, 0x3377d1cf, v20
	v_fmac_f32_e32 v23, 0x3f317217, v20
	v_cmp_lt_f32_e64 s[0:1], |v20|, s90
	s_nop 1
	v_cndmask_b32_e64 v20, v20, v23, s[0:1]
	v_cndmask_b32_e32 v23, 0, v203, vcc
	v_sub_f32_e32 v20, v20, v23
	v_sub_f32_e32 v20, v22, v20
	ds_read_b128 v[22:25], v21 offset:64
	v_fma_f32 v20, v20, s79, 0
	s_waitcnt lgkmcnt(0)
	v_fma_f32 v26, v16, v22, v11
	v_fmac_f32_e32 v26, v17, v23
	v_fmac_f32_e32 v26, v18, v24
	v_fmac_f32_e32 v26, v19, v25
	ds_read_b128 v[22:25], v21 offset:80
	s_waitcnt lgkmcnt(0)
; DI float log_sigmoid_fast(float x) { return fminf(x, 0.f) - __logf(1.0f + __expf(-fabsf(x))); }
; template <int MODE>
; DI void gla4_unit(const bf16_t* z, float* ST, float* DEC, bf16_t* Y, const float* aw_g, const float* ab_g, const float* ng, ldsp lds, int tid, int u) {
;     ...
;         float run = 0.f;
; #pragma unroll
;         for (int i = 0; i < 32; ++i) {
;             const int t = 32 * half + i;
;             float al = ab;
; #pragma unroll
;             for (int r = 0; r < 16; ++r) al += alr[t * 16 + r] * aw[r];
;             run += log_sigmoid_fast(al) * (1.0f / 16.0f);
;             bc[i] = run;
;         }
	v_fmac_f32_e32 v26, v12, v22
	v_fmac_f32_e32 v26, v13, v23
	v_fmac_f32_e32 v26, v14, v24
	v_fmac_f32_e32 v26, v15, v25
	ds_read_b128 v[22:25], v21 offset:96
	s_waitcnt lgkmcnt(0)
	v_fmac_f32_e32 v26, v7, v22
	v_fmac_f32_e32 v26, v8, v23
	v_fmac_f32_e32 v26, v9, v24
	v_fmac_f32_e32 v26, v10, v25
	ds_read_b128 v[22:25], v21 offset:112
	s_waitcnt lgkmcnt(0)
	v_fmac_f32_e32 v26, v6, v22
	v_fmac_f32_e32 v26, v5, v23
	v_fmac_f32_e32 v26, v4, v24
	v_fmac_f32_e32 v26, v1, v25
	v_mul_f32_e64 v23, |v26|, s46
	v_exp_f32_e32 v23, v23
	v_min_f32_e32 v22, 0, v26
	v_add_f32_e32 v23, 1.0, v23
	v_cmp_gt_f32_e32 vcc, s47, v23
	s_nop 1
	v_cndmask_b32_e64 v24, 0, 32, vcc
	v_ldexp_f32 v23, v23, v24
	v_log_f32_e32 v23, v23
	s_nop 0
	v_mul_f32_e32 v24, 0x3f317217, v23
	v_fma_f32 v24, v23, s4, -v24
	v_fmac_f32_e32 v24, 0x3377d1cf, v23
	v_fmac_f32_e32 v24, 0x3f317217, v23
	v_cmp_lt_f32_e64 s[0:1], |v23|, s90
	s_nop 1
	v_cndmask_b32_e64 v23, v23, v24, s[0:1]
	v_cndmask_b32_e32 v24, 0, v203, vcc
	v_sub_f32_e32 v23, v23, v24
	ds_read_b128 v[24:27], v21 offset:128
	v_sub_f32_e32 v22, v22, v23
	v_fmamk_f32 v22, v22, 0x3d800000, v20
	s_waitcnt lgkmcnt(0)
	v_fma_f32 v23, v16, v24, v11
	v_fmac_f32_e32 v23, v17, v25
	v_fmac_f32_e32 v23, v18, v26
	v_fmac_f32_e32 v23, v19, v27
	ds_read_b128 v[24:27], v21 offset:144
	s_waitcnt lgkmcnt(0)
	v_fmac_f32_e32 v23, v12, v24
	v_fmac_f32_e32 v23, v13, v25
	v_fmac_f32_e32 v23, v14, v26
	v_fmac_f32_e32 v23, v15, v27
	ds_read_b128 v[24:27], v21 offset:160
	s_waitcnt lgkmcnt(0)
	v_fmac_f32_e32 v23, v7, v24
	v_fmac_f32_e32 v23, v8, v25
	v_fmac_f32_e32 v23, v9, v26
	v_fmac_f32_e32 v23, v10, v27
	ds_read_b128 v[24:27], v21 offset:176
	s_waitcnt lgkmcnt(0)
	v_fmac_f32_e32 v23, v6, v24
	v_fmac_f32_e32 v23, v5, v25
	v_fmac_f32_e32 v23, v4, v26
	v_fmac_f32_e32 v23, v1, v27
	v_min_f32_e32 v24, 0, v23
	v_mul_f32_e64 v23, |v23|, s46
	v_exp_f32_e32 v23, v23
	s_nop 0
	v_add_f32_e32 v23, 1.0, v23
	v_cmp_gt_f32_e32 vcc, s47, v23
	s_nop 1
	v_cndmask_b32_e64 v25, 0, 32, vcc
	v_ldexp_f32 v23, v23, v25
	v_log_f32_e32 v23, v23
	s_nop 0
	v_mul_f32_e32 v25, 0x3f317217, v23
	v_fma_f32 v25, v23, s4, -v25
	v_fmac_f32_e32 v25, 0x3377d1cf, v23
	v_fmac_f32_e32 v25, 0x3f317217, v23
	v_cmp_lt_f32_e64 s[0:1], |v23|, s90
	s_nop 1
	v_cndmask_b32_e64 v23, v23, v25, s[0:1]
	v_cndmask_b32_e32 v25, 0, v203, vcc
	v_sub_f32_e32 v23, v23, v25
	v_sub_f32_e32 v23, v24, v23
	ds_read_b128 v[24:27], v21 offset:192
	v_fmamk_f32 v23, v23, 0x3d800000, v22
	s_waitcnt lgkmcnt(0)
	v_fma_f32 v30, v16, v24, v11
	v_fmac_f32_e32 v30, v17, v25
	v_fmac_f32_e32 v30, v18, v26
	v_fmac_f32_e32 v30, v19, v27
	ds_read_b128 v[24:27], v21 offset:208
	s_waitcnt lgkmcnt(0)
	v_fmac_f32_e32 v30, v12, v24
	v_fmac_f32_e32 v30, v13, v25
	v_fmac_f32_e32 v30, v14, v26
	v_fmac_f32_e32 v30, v15, v27
	ds_read_b128 v[24:27], v21 offset:224
	s_waitcnt lgkmcnt(0)
	v_fmac_f32_e32 v30, v7, v24
	v_fmac_f32_e32 v30, v8, v25
	v_fmac_f32_e32 v30, v9, v26
	v_fmac_f32_e32 v30, v10, v27
	ds_read_b128 v[24:27], v21 offset:240
	s_waitcnt lgkmcnt(0)
	v_fmac_f32_e32 v30, v6, v24
	v_fmac_f32_e32 v30, v5, v25
	v_fmac_f32_e32 v30, v4, v26
	v_fmac_f32_e32 v30, v1, v27
	v_mul_f32_e64 v25, |v30|, s46
	v_exp_f32_e32 v25, v25
	v_min_f32_e32 v24, 0, v30
	v_add_f32_e32 v25, 1.0, v25
	v_cmp_gt_f32_e32 vcc, s47, v25
	s_nop 1
	v_cndmask_b32_e64 v26, 0, 32, vcc
	v_ldexp_f32 v25, v25, v26
	v_log_f32_e32 v25, v25
	s_nop 0
	v_mul_f32_e32 v26, 0x3f317217, v25
	v_fma_f32 v26, v25, s4, -v26
	v_fmac_f32_e32 v26, 0x3377d1cf, v25
	v_fmac_f32_e32 v26, 0x3f317217, v25
	v_cmp_lt_f32_e64 s[0:1], |v25|, s90
	s_nop 1
	v_cndmask_b32_e64 v25, v25, v26, s[0:1]
	v_cndmask_b32_e32 v26, 0, v203, vcc
	v_sub_f32_e32 v25, v25, v26
	v_sub_f32_e32 v24, v24, v25
	v_fma_f32 v25, v16, v36, v11
	v_fmac_f32_e32 v25, v17, v37
	v_fmac_f32_e32 v25, v18, v38
	v_fmac_f32_e32 v25, v19, v39
	ds_read_b128 v[36:39], v21 offset:272
	v_fmamk_f32 v24, v24, 0x3d800000, v23
	s_waitcnt lgkmcnt(0)
	v_fmac_f32_e32 v25, v12, v36
	v_fmac_f32_e32 v25, v13, v37
	v_fmac_f32_e32 v25, v14, v38
	v_fmac_f32_e32 v25, v15, v39
	ds_read_b128 v[36:39], v21 offset:288
	s_waitcnt lgkmcnt(0)
	v_fmac_f32_e32 v25, v7, v36
	v_fmac_f32_e32 v25, v8, v37
	v_fmac_f32_e32 v25, v9, v38
	v_fmac_f32_e32 v25, v10, v39
	ds_read_b128 v[36:39], v21 offset:304
	s_waitcnt lgkmcnt(0)
	v_fmac_f32_e32 v25, v6, v36
	v_fmac_f32_e32 v25, v5, v37
	v_fmac_f32_e32 v25, v4, v38
	v_fmac_f32_e32 v25, v1, v39
	v_min_f32_e32 v26, 0, v25
	v_mul_f32_e64 v25, |v25|, s46
	v_exp_f32_e32 v25, v25
	ds_read_b128 v[36:39], v21 offset:320
	v_add_f32_e32 v25, 1.0, v25
	v_cmp_gt_f32_e32 vcc, s47, v25
	s_nop 1
	v_cndmask_b32_e64 v27, 0, 32, vcc
	v_ldexp_f32 v25, v25, v27
	v_log_f32_e32 v25, v25
	s_nop 0
	v_mul_f32_e32 v27, 0x3f317217, v25
	v_fma_f32 v27, v25, s4, -v27
	v_fmac_f32_e32 v27, 0x3377d1cf, v25
	v_fmac_f32_e32 v27, 0x3f317217, v25
	v_cmp_lt_f32_e64 s[0:1], |v25|, s90
	s_nop 1
	v_cndmask_b32_e64 v25, v25, v27, s[0:1]
	v_cndmask_b32_e32 v27, 0, v203, vcc
	v_sub_f32_e32 v25, v25, v27
	v_sub_f32_e32 v25, v26, v25
	s_waitcnt lgkmcnt(0)
	v_fma_f32 v26, v16, v36, v11
	v_fmac_f32_e32 v26, v17, v37
	v_fmac_f32_e32 v26, v18, v38
	v_fmac_f32_e32 v26, v19, v39
	ds_read_b128 v[36:39], v21 offset:336
	v_fmamk_f32 v25, v25, 0x3d800000, v24
	s_waitcnt lgkmcnt(0)
	v_fmac_f32_e32 v26, v12, v36
	v_fmac_f32_e32 v26, v13, v37
	v_fmac_f32_e32 v26, v14, v38
	v_fmac_f32_e32 v26, v15, v39
	ds_read_b128 v[36:39], v21 offset:352
	s_waitcnt lgkmcnt(0)
	v_fmac_f32_e32 v26, v7, v36
	v_fmac_f32_e32 v26, v8, v37
	v_fmac_f32_e32 v26, v9, v38
	v_fmac_f32_e32 v26, v10, v39
	ds_read_b128 v[36:39], v21 offset:368
	s_waitcnt lgkmcnt(0)
; DI float log_sigmoid_fast(float x) { return fminf(x, 0.f) - __logf(1.0f + __expf(-fabsf(x))); }
; template <int MODE>
; DI void gla4_unit(const bf16_t* z, float* ST, float* DEC, bf16_t* Y, const float* aw_g, const float* ab_g, const float* ng, ldsp lds, int tid, int u) {
;     ...
;         float run = 0.f;
; #pragma unroll
;         for (int i = 0; i < 32; ++i) {
;             const int t = 32 * half + i;
;             float al = ab;
; #pragma unroll
;             for (int r = 0; r < 16; ++r) al += alr[t * 16 + r] * aw[r];
;             run += log_sigmoid_fast(al) * (1.0f / 16.0f);
;             bc[i] = run;
;         }
	v_fmac_f32_e32 v26, v6, v36
	v_fmac_f32_e32 v26, v5, v37
	v_fmac_f32_e32 v26, v4, v38
	v_fmac_f32_e32 v26, v1, v39
	v_min_f32_e32 v27, 0, v26
	v_mul_f32_e64 v26, |v26|, s46
	v_exp_f32_e32 v26, v26
	ds_read_b128 v[36:39], v21 offset:384
	v_add_f32_e32 v26, 1.0, v26
	v_cmp_gt_f32_e32 vcc, s47, v26
	s_nop 1
	v_cndmask_b32_e64 v30, 0, 32, vcc
	v_ldexp_f32 v26, v26, v30
	v_log_f32_e32 v26, v26
	s_nop 0
	v_mul_f32_e32 v30, 0x3f317217, v26
	v_fma_f32 v30, v26, s4, -v30
	v_fmac_f32_e32 v30, 0x3377d1cf, v26
	v_fmac_f32_e32 v30, 0x3f317217, v26
	v_cmp_lt_f32_e64 s[0:1], |v26|, s90
	s_nop 1
	v_cndmask_b32_e64 v26, v26, v30, s[0:1]
	v_cndmask_b32_e32 v30, 0, v203, vcc
	v_sub_f32_e32 v26, v26, v30
	v_sub_f32_e32 v26, v27, v26
	s_waitcnt lgkmcnt(0)
	v_fma_f32 v27, v16, v36, v11
	v_fmac_f32_e32 v27, v17, v37
	v_fmac_f32_e32 v27, v18, v38
	v_fmac_f32_e32 v27, v19, v39
	ds_read_b128 v[36:39], v21 offset:400
	v_fmamk_f32 v26, v26, 0x3d800000, v25
	s_waitcnt lgkmcnt(0)
	v_fmac_f32_e32 v27, v12, v36
	v_fmac_f32_e32 v27, v13, v37
	v_fmac_f32_e32 v27, v14, v38
	v_fmac_f32_e32 v27, v15, v39
	ds_read_b128 v[36:39], v21 offset:416
	s_waitcnt lgkmcnt(0)
	v_fmac_f32_e32 v27, v7, v36
	v_fmac_f32_e32 v27, v8, v37
	v_fmac_f32_e32 v27, v9, v38
	v_fmac_f32_e32 v27, v10, v39
	ds_read_b128 v[36:39], v21 offset:432
	s_waitcnt lgkmcnt(0)
	v_fmac_f32_e32 v27, v6, v36
	v_fmac_f32_e32 v27, v5, v37
	v_fmac_f32_e32 v27, v4, v38
	v_fmac_f32_e32 v27, v1, v39
	v_min_f32_e32 v30, 0, v27
	v_mul_f32_e64 v27, |v27|, s46
	v_exp_f32_e32 v27, v27
	ds_read_b128 v[36:39], v21 offset:448
	v_add_f32_e32 v27, 1.0, v27
	v_cmp_gt_f32_e32 vcc, s47, v27
	s_nop 1
	v_cndmask_b32_e64 v31, 0, 32, vcc
	v_ldexp_f32 v27, v27, v31
	v_log_f32_e32 v27, v27
	s_nop 0
	v_mul_f32_e32 v31, 0x3f317217, v27
	v_fma_f32 v31, v27, s4, -v31
	v_fmac_f32_e32 v31, 0x3377d1cf, v27
	v_fmac_f32_e32 v31, 0x3f317217, v27
	v_cmp_lt_f32_e64 s[0:1], |v27|, s90
	s_nop 1
	v_cndmask_b32_e64 v27, v27, v31, s[0:1]
	v_cndmask_b32_e32 v31, 0, v203, vcc
	v_sub_f32_e32 v27, v27, v31
	v_sub_f32_e32 v27, v30, v27
	s_waitcnt lgkmcnt(0)
	v_fma_f32 v30, v16, v36, v11
	v_fmac_f32_e32 v30, v17, v37
	v_fmac_f32_e32 v30, v18, v38
	v_fmac_f32_e32 v30, v19, v39
	ds_read_b128 v[36:39], v21 offset:464
	v_fmamk_f32 v27, v27, 0x3d800000, v26
	s_waitcnt lgkmcnt(0)
	v_fmac_f32_e32 v30, v12, v36
	v_fmac_f32_e32 v30, v13, v37
	v_fmac_f32_e32 v30, v14, v38
	v_fmac_f32_e32 v30, v15, v39
	ds_read_b128 v[36:39], v21 offset:480
	s_waitcnt lgkmcnt(0)
	v_fmac_f32_e32 v30, v7, v36
	v_fmac_f32_e32 v30, v8, v37
	v_fmac_f32_e32 v30, v9, v38
	v_fmac_f32_e32 v30, v10, v39
	ds_read_b128 v[36:39], v21 offset:496
	s_waitcnt lgkmcnt(0)
	v_fmac_f32_e32 v30, v6, v36
	v_fmac_f32_e32 v30, v5, v37
	v_fmac_f32_e32 v30, v4, v38
	v_fmac_f32_e32 v30, v1, v39
	v_min_f32_e32 v31, 0, v30
	v_mul_f32_e64 v30, |v30|, s46
	v_exp_f32_e32 v30, v30
	ds_read_b128 v[36:39], v21 offset:512
	v_add_f32_e32 v30, 1.0, v30
	v_cmp_gt_f32_e32 vcc, s47, v30
	s_nop 1
	v_cndmask_b32_e64 v35, 0, 32, vcc
	v_ldexp_f32 v30, v30, v35
	v_log_f32_e32 v30, v30
	s_nop 0
	v_mul_f32_e32 v35, 0x3f317217, v30
	v_fma_f32 v35, v30, s4, -v35
	v_fmac_f32_e32 v35, 0x3377d1cf, v30
	v_fmac_f32_e32 v35, 0x3f317217, v30
	v_cmp_lt_f32_e64 s[0:1], |v30|, s90
	s_nop 1
	v_cndmask_b32_e64 v30, v30, v35, s[0:1]
	v_cndmask_b32_e32 v35, 0, v203, vcc
	v_sub_f32_e32 v30, v30, v35
	v_sub_f32_e32 v30, v31, v30
	s_waitcnt lgkmcnt(0)
	v_fma_f32 v31, v16, v36, v11
	v_fmac_f32_e32 v31, v17, v37
	v_fmac_f32_e32 v31, v18, v38
	v_fmac_f32_e32 v31, v19, v39
	ds_read_b128 v[36:39], v21 offset:528
	v_fmamk_f32 v30, v30, 0x3d800000, v27
	s_waitcnt lgkmcnt(0)
	v_fmac_f32_e32 v31, v12, v36
	v_fmac_f32_e32 v31, v13, v37
	v_fmac_f32_e32 v31, v14, v38
	v_fmac_f32_e32 v31, v15, v39
	ds_read_b128 v[36:39], v21 offset:544
	s_waitcnt lgkmcnt(0)
	v_fmac_f32_e32 v31, v7, v36
	v_fmac_f32_e32 v31, v8, v37
	v_fmac_f32_e32 v31, v9, v38
	v_fmac_f32_e32 v31, v10, v39
	ds_read_b128 v[36:39], v21 offset:560
	s_waitcnt lgkmcnt(0)
	v_fmac_f32_e32 v31, v6, v36
	v_fmac_f32_e32 v31, v5, v37
	v_fmac_f32_e32 v31, v4, v38
	v_fmac_f32_e32 v31, v1, v39
	v_min_f32_e32 v35, 0, v31
	v_mul_f32_e64 v31, |v31|, s46
	v_exp_f32_e32 v31, v31
	s_nop 0
	v_add_f32_e32 v31, 1.0, v31
	v_cmp_gt_f32_e32 vcc, s47, v31
	s_nop 1
	v_cndmask_b32_e64 v36, 0, 32, vcc
	v_ldexp_f32 v31, v31, v36
	v_log_f32_e32 v31, v31
	s_nop 0
	v_mul_f32_e32 v36, 0x3f317217, v31
	v_fma_f32 v36, v31, s4, -v36
	v_fmac_f32_e32 v36, 0x3377d1cf, v31
	v_fmac_f32_e32 v36, 0x3f317217, v31
	v_cmp_lt_f32_e64 s[0:1], |v31|, s90
	s_nop 1
	v_cndmask_b32_e64 v31, v31, v36, s[0:1]
	v_cndmask_b32_e32 v36, 0, v203, vcc
	v_sub_f32_e32 v31, v31, v36
	ds_read_b128 v[36:39], v21 offset:576
	v_sub_f32_e32 v31, v35, v31
	v_fmamk_f32 v31, v31, 0x3d800000, v30
	s_waitcnt lgkmcnt(0)
	v_fma_f32 v35, v16, v36, v11
	v_fmac_f32_e32 v35, v17, v37
	v_fmac_f32_e32 v35, v18, v38
	v_fmac_f32_e32 v35, v19, v39
	ds_read_b128 v[36:39], v21 offset:592
	s_waitcnt lgkmcnt(0)
	v_fmac_f32_e32 v35, v12, v36
	v_fmac_f32_e32 v35, v13, v37
	v_fmac_f32_e32 v35, v14, v38
	v_fmac_f32_e32 v35, v15, v39
	ds_read_b128 v[36:39], v21 offset:608
	s_waitcnt lgkmcnt(0)
	v_fmac_f32_e32 v35, v7, v36
	v_fmac_f32_e32 v35, v8, v37
	v_fmac_f32_e32 v35, v9, v38
	v_fmac_f32_e32 v35, v10, v39
	ds_read_b128 v[36:39], v21 offset:624
	s_waitcnt lgkmcnt(0)
; DI float log_sigmoid_fast(float x) { return fminf(x, 0.f) - __logf(1.0f + __expf(-fabsf(x))); }
; template <int MODE>
; DI void gla4_unit(const bf16_t* z, float* ST, float* DEC, bf16_t* Y, const float* aw_g, const float* ab_g, const float* ng, ldsp lds, int tid, int u) {
;     ...
;         float run = 0.f;
; #pragma unroll
;         for (int i = 0; i < 32; ++i) {
;             const int t = 32 * half + i;
;             float al = ab;
; #pragma unroll
;             for (int r = 0; r < 16; ++r) al += alr[t * 16 + r] * aw[r];
;             run += log_sigmoid_fast(al) * (1.0f / 16.0f);
;             bc[i] = run;
;         }
	v_fmac_f32_e32 v35, v6, v36
	v_fmac_f32_e32 v35, v5, v37
	v_fmac_f32_e32 v35, v4, v38
	v_fmac_f32_e32 v35, v1, v39
	v_min_f32_e32 v36, 0, v35
	v_mul_f32_e64 v35, |v35|, s46
	v_exp_f32_e32 v35, v35
	s_nop 0
	v_add_f32_e32 v35, 1.0, v35
	v_cmp_gt_f32_e32 vcc, s47, v35
	s_nop 1
	v_cndmask_b32_e64 v37, 0, 32, vcc
	v_ldexp_f32 v35, v35, v37
	v_log_f32_e32 v35, v35
	s_nop 0
	v_mul_f32_e32 v37, 0x3f317217, v35
	v_fma_f32 v37, v35, s4, -v37
	v_fmac_f32_e32 v37, 0x3377d1cf, v35
	v_fmac_f32_e32 v37, 0x3f317217, v35
	v_cmp_lt_f32_e64 s[0:1], |v35|, s90
	s_nop 1
	v_cndmask_b32_e64 v35, v35, v37, s[0:1]
	v_cndmask_b32_e32 v37, 0, v203, vcc
	v_sub_f32_e32 v35, v35, v37
	v_sub_f32_e32 v35, v36, v35
	ds_read_b128 v[36:39], v21 offset:640
	v_fmamk_f32 v35, v35, 0x3d800000, v31
	s_waitcnt lgkmcnt(0)
	v_fma_f32 v40, v16, v36, v11
	v_fmac_f32_e32 v40, v17, v37
	v_fmac_f32_e32 v40, v18, v38
	v_fmac_f32_e32 v40, v19, v39
	ds_read_b128 v[36:39], v21 offset:656
	s_waitcnt lgkmcnt(0)
	v_fmac_f32_e32 v40, v12, v36
	v_fmac_f32_e32 v40, v13, v37
	v_fmac_f32_e32 v40, v14, v38
	v_fmac_f32_e32 v40, v15, v39
	ds_read_b128 v[36:39], v21 offset:672
	s_waitcnt lgkmcnt(0)
	v_fmac_f32_e32 v40, v7, v36
	v_fmac_f32_e32 v40, v8, v37
	v_fmac_f32_e32 v40, v9, v38
	v_fmac_f32_e32 v40, v10, v39
	ds_read_b128 v[36:39], v21 offset:688
	s_waitcnt lgkmcnt(0)
	v_fmac_f32_e32 v40, v6, v36
	v_fmac_f32_e32 v40, v5, v37
	v_fmac_f32_e32 v40, v4, v38
	v_fmac_f32_e32 v40, v1, v39
	v_mul_f32_e64 v37, |v40|, s46
	v_exp_f32_e32 v37, v37
	v_min_f32_e32 v36, 0, v40
	v_add_f32_e32 v37, 1.0, v37
	v_cmp_gt_f32_e32 vcc, s47, v37
	s_nop 1
	v_cndmask_b32_e64 v38, 0, 32, vcc
	v_ldexp_f32 v37, v37, v38
	v_log_f32_e32 v37, v37
	s_nop 0
	v_mul_f32_e32 v38, 0x3f317217, v37
	v_fma_f32 v38, v37, s4, -v38
	v_fmac_f32_e32 v38, 0x3377d1cf, v37
	v_fmac_f32_e32 v38, 0x3f317217, v37
	v_cmp_lt_f32_e64 s[0:1], |v37|, s90
	s_nop 1
	v_cndmask_b32_e64 v37, v37, v38, s[0:1]
	v_cndmask_b32_e32 v38, 0, v203, vcc
	v_sub_f32_e32 v37, v37, v38
	ds_read_b128 v[38:41], v21 offset:704
	v_sub_f32_e32 v36, v36, v37
	v_fmamk_f32 v36, v36, 0x3d800000, v35
	s_waitcnt lgkmcnt(0)
	v_fma_f32 v37, v16, v38, v11
	v_fmac_f32_e32 v37, v17, v39
	v_fmac_f32_e32 v37, v18, v40
	v_fmac_f32_e32 v37, v19, v41
	ds_read_b128 v[38:41], v21 offset:720
	s_waitcnt lgkmcnt(0)
	v_fmac_f32_e32 v37, v12, v38
	v_fmac_f32_e32 v37, v13, v39
	v_fmac_f32_e32 v37, v14, v40
	v_fmac_f32_e32 v37, v15, v41
	ds_read_b128 v[38:41], v21 offset:736
	s_waitcnt lgkmcnt(0)
	v_fmac_f32_e32 v37, v7, v38
	v_fmac_f32_e32 v37, v8, v39
	v_fmac_f32_e32 v37, v9, v40
	v_fmac_f32_e32 v37, v10, v41
	ds_read_b128 v[38:41], v21 offset:752
	s_waitcnt lgkmcnt(0)
	v_fmac_f32_e32 v37, v6, v38
	v_fmac_f32_e32 v37, v5, v39
	v_fmac_f32_e32 v37, v4, v40
	v_fmac_f32_e32 v37, v1, v41
	v_min_f32_e32 v38, 0, v37
	v_mul_f32_e64 v37, |v37|, s46
	v_exp_f32_e32 v37, v37
	s_nop 0
	v_add_f32_e32 v37, 1.0, v37
	v_cmp_gt_f32_e32 vcc, s47, v37
	s_nop 1
	v_cndmask_b32_e64 v39, 0, 32, vcc
	v_ldexp_f32 v37, v37, v39
	v_log_f32_e32 v37, v37
	s_nop 0
	v_mul_f32_e32 v39, 0x3f317217, v37
	v_fma_f32 v39, v37, s4, -v39
	v_fmac_f32_e32 v39, 0x3377d1cf, v37
	v_fmac_f32_e32 v39, 0x3f317217, v37
	v_cmp_lt_f32_e64 s[0:1], |v37|, s90
	s_nop 1
	v_cndmask_b32_e64 v37, v37, v39, s[0:1]
	v_cndmask_b32_e32 v39, 0, v203, vcc
	v_sub_f32_e32 v37, v37, v39
	v_sub_f32_e32 v37, v38, v37
	ds_read_b128 v[38:41], v21 offset:768
	v_fmamk_f32 v37, v37, 0x3d800000, v36
	s_waitcnt lgkmcnt(0)
	v_fma_f32 v42, v16, v38, v11
	v_fmac_f32_e32 v42, v17, v39
	v_fmac_f32_e32 v42, v18, v40
	v_fmac_f32_e32 v42, v19, v41
	ds_read_b128 v[38:41], v21 offset:784
	s_waitcnt lgkmcnt(0)
	v_fmac_f32_e32 v42, v12, v38
	v_fmac_f32_e32 v42, v13, v39
	v_fmac_f32_e32 v42, v14, v40
	v_fmac_f32_e32 v42, v15, v41
	ds_read_b128 v[38:41], v21 offset:800
	s_waitcnt lgkmcnt(0)
	v_fmac_f32_e32 v42, v7, v38
	v_fmac_f32_e32 v42, v8, v39
	v_fmac_f32_e32 v42, v9, v40
	v_fmac_f32_e32 v42, v10, v41
	ds_read_b128 v[38:41], v21 offset:816
	s_waitcnt lgkmcnt(0)
	v_fmac_f32_e32 v42, v6, v38
	v_fmac_f32_e32 v42, v5, v39
	v_fmac_f32_e32 v42, v4, v40
	v_fmac_f32_e32 v42, v1, v41
	v_mul_f32_e64 v39, |v42|, s46
	v_exp_f32_e32 v39, v39
	v_min_f32_e32 v38, 0, v42
	v_add_f32_e32 v39, 1.0, v39
	v_cmp_gt_f32_e32 vcc, s47, v39
	s_nop 1
	v_cndmask_b32_e64 v40, 0, 32, vcc
	v_ldexp_f32 v39, v39, v40
	v_log_f32_e32 v39, v39
	s_nop 0
	v_mul_f32_e32 v40, 0x3f317217, v39
	v_fma_f32 v40, v39, s4, -v40
	v_fmac_f32_e32 v40, 0x3377d1cf, v39
	v_fmac_f32_e32 v40, 0x3f317217, v39
	v_cmp_lt_f32_e64 s[0:1], |v39|, s90
	s_nop 1
	v_cndmask_b32_e64 v39, v39, v40, s[0:1]
	v_cndmask_b32_e32 v40, 0, v203, vcc
	v_sub_f32_e32 v39, v39, v40
	ds_read_b128 v[40:43], v21 offset:832
	v_sub_f32_e32 v38, v38, v39
	v_fmamk_f32 v38, v38, 0x3d800000, v37
	s_waitcnt lgkmcnt(0)
	v_fma_f32 v39, v16, v40, v11
	v_fmac_f32_e32 v39, v17, v41
	v_fmac_f32_e32 v39, v18, v42
	v_fmac_f32_e32 v39, v19, v43
	ds_read_b128 v[40:43], v21 offset:848
	s_waitcnt lgkmcnt(0)
	v_fmac_f32_e32 v39, v12, v40
	v_fmac_f32_e32 v39, v13, v41
	v_fmac_f32_e32 v39, v14, v42
	v_fmac_f32_e32 v39, v15, v43
	ds_read_b128 v[40:43], v21 offset:864
	s_waitcnt lgkmcnt(0)
	v_fmac_f32_e32 v39, v7, v40
	v_fmac_f32_e32 v39, v8, v41
	v_fmac_f32_e32 v39, v9, v42
	v_fmac_f32_e32 v39, v10, v43
	ds_read_b128 v[40:43], v21 offset:880
	s_waitcnt lgkmcnt(0)
; DI float log_sigmoid_fast(float x) { return fminf(x, 0.f) - __logf(1.0f + __expf(-fabsf(x))); }
; template <int MODE>
; DI void gla4_unit(const bf16_t* z, float* ST, float* DEC, bf16_t* Y, const float* aw_g, const float* ab_g, const float* ng, ldsp lds, int tid, int u) {
;     ...
;         float run = 0.f;
; #pragma unroll
;         for (int i = 0; i < 32; ++i) {
;             const int t = 32 * half + i;
;             float al = ab;
; #pragma unroll
;             for (int r = 0; r < 16; ++r) al += alr[t * 16 + r] * aw[r];
;             run += log_sigmoid_fast(al) * (1.0f / 16.0f);
;             bc[i] = run;
;         }
	v_fmac_f32_e32 v39, v6, v40
	v_fmac_f32_e32 v39, v5, v41
	v_fmac_f32_e32 v39, v4, v42
	v_fmac_f32_e32 v39, v1, v43
	v_min_f32_e32 v40, 0, v39
	v_mul_f32_e64 v39, |v39|, s46
	v_exp_f32_e32 v39, v39
	s_nop 0
	v_add_f32_e32 v39, 1.0, v39
	v_cmp_gt_f32_e32 vcc, s47, v39
	s_nop 1
	v_cndmask_b32_e64 v41, 0, 32, vcc
	v_ldexp_f32 v39, v39, v41
	v_log_f32_e32 v39, v39
	s_nop 0
	v_mul_f32_e32 v41, 0x3f317217, v39
	v_fma_f32 v41, v39, s4, -v41
	v_fmac_f32_e32 v41, 0x3377d1cf, v39
	v_fmac_f32_e32 v41, 0x3f317217, v39
	v_cmp_lt_f32_e64 s[0:1], |v39|, s90
	s_nop 1
	v_cndmask_b32_e64 v39, v39, v41, s[0:1]
	v_cndmask_b32_e32 v41, 0, v203, vcc
	v_sub_f32_e32 v39, v39, v41
	v_sub_f32_e32 v39, v40, v39
	ds_read_b128 v[40:43], v21 offset:896
	v_fmamk_f32 v39, v39, 0x3d800000, v38
	s_waitcnt lgkmcnt(0)
	v_fma_f32 v44, v16, v40, v11
	v_fmac_f32_e32 v44, v17, v41
	v_fmac_f32_e32 v44, v18, v42
	v_fmac_f32_e32 v44, v19, v43
	ds_read_b128 v[40:43], v21 offset:912
	s_waitcnt lgkmcnt(0)
	v_fmac_f32_e32 v44, v12, v40
	v_fmac_f32_e32 v44, v13, v41
	v_fmac_f32_e32 v44, v14, v42
	v_fmac_f32_e32 v44, v15, v43
	ds_read_b128 v[40:43], v21 offset:928
	s_waitcnt lgkmcnt(0)
	v_fmac_f32_e32 v44, v7, v40
	v_fmac_f32_e32 v44, v8, v41
	v_fmac_f32_e32 v44, v9, v42
	v_fmac_f32_e32 v44, v10, v43
	ds_read_b128 v[40:43], v21 offset:944
	s_waitcnt lgkmcnt(0)
	v_fmac_f32_e32 v44, v6, v40
	v_fmac_f32_e32 v44, v5, v41
	v_fmac_f32_e32 v44, v4, v42
	v_fmac_f32_e32 v44, v1, v43
	v_mul_f32_e64 v41, |v44|, s46
	v_exp_f32_e32 v41, v41
	v_min_f32_e32 v40, 0, v44
	v_add_f32_e32 v41, 1.0, v41
	v_cmp_gt_f32_e32 vcc, s47, v41
	s_nop 1
	v_cndmask_b32_e64 v42, 0, 32, vcc
	v_ldexp_f32 v41, v41, v42
	v_log_f32_e32 v41, v41
	s_nop 0
	v_mul_f32_e32 v42, 0x3f317217, v41
	v_fma_f32 v42, v41, s4, -v42
	v_fmac_f32_e32 v42, 0x3377d1cf, v41
	v_fmac_f32_e32 v42, 0x3f317217, v41
	v_cmp_lt_f32_e64 s[0:1], |v41|, s90
	s_nop 1
	v_cndmask_b32_e64 v41, v41, v42, s[0:1]
	v_cndmask_b32_e32 v42, 0, v203, vcc
	v_sub_f32_e32 v41, v41, v42
	ds_read_b128 v[42:45], v21 offset:960
	v_sub_f32_e32 v40, v40, v41
	v_fmamk_f32 v40, v40, 0x3d800000, v39
	s_waitcnt lgkmcnt(0)
	v_fma_f32 v41, v16, v42, v11
	v_fmac_f32_e32 v41, v17, v43
	v_fmac_f32_e32 v41, v18, v44
	v_fmac_f32_e32 v41, v19, v45
	ds_read_b128 v[42:45], v21 offset:976
	s_waitcnt lgkmcnt(0)
	v_fmac_f32_e32 v41, v12, v42
	v_fmac_f32_e32 v41, v13, v43
	v_fmac_f32_e32 v41, v14, v44
	v_fmac_f32_e32 v41, v15, v45
	ds_read_b128 v[42:45], v21 offset:992
	s_waitcnt lgkmcnt(0)
	v_fmac_f32_e32 v41, v7, v42
	v_fmac_f32_e32 v41, v8, v43
	v_fmac_f32_e32 v41, v9, v44
	v_fmac_f32_e32 v41, v10, v45
	ds_read_b128 v[42:45], v21 offset:1008
	s_waitcnt lgkmcnt(0)
	v_fmac_f32_e32 v41, v6, v42
	v_fmac_f32_e32 v41, v5, v43
	v_fmac_f32_e32 v41, v4, v44
	v_fmac_f32_e32 v41, v1, v45
	v_min_f32_e32 v42, 0, v41
	v_mul_f32_e64 v41, |v41|, s46
	v_exp_f32_e32 v41, v41
	s_nop 0
	v_add_f32_e32 v41, 1.0, v41
	v_cmp_gt_f32_e32 vcc, s47, v41
	s_nop 1
	v_cndmask_b32_e64 v43, 0, 32, vcc
	v_ldexp_f32 v41, v41, v43
	v_log_f32_e32 v41, v41
	s_nop 0
	v_mul_f32_e32 v43, 0x3f317217, v41
	v_fma_f32 v43, v41, s4, -v43
	v_fmac_f32_e32 v43, 0x3377d1cf, v41
	v_fmac_f32_e32 v43, 0x3f317217, v41
	v_cmp_lt_f32_e64 s[0:1], |v41|, s90
	s_nop 1
	v_cndmask_b32_e64 v41, v41, v43, s[0:1]
	v_cndmask_b32_e32 v43, 0, v203, vcc
	v_sub_f32_e32 v41, v41, v43
	v_sub_f32_e32 v41, v42, v41
	ds_read_b128 v[42:45], v21 offset:1024
	v_fmamk_f32 v41, v41, 0x3d800000, v40
	s_waitcnt lgkmcnt(0)
	v_fma_f32 v46, v16, v42, v11
	v_fmac_f32_e32 v46, v17, v43
	v_fmac_f32_e32 v46, v18, v44
	v_fmac_f32_e32 v46, v19, v45
	ds_read_b128 v[42:45], v21 offset:1040
	s_waitcnt lgkmcnt(0)
	v_fmac_f32_e32 v46, v12, v42
	v_fmac_f32_e32 v46, v13, v43
	v_fmac_f32_e32 v46, v14, v44
	v_fmac_f32_e32 v46, v15, v45
	ds_read_b128 v[42:45], v21 offset:1056
	s_waitcnt lgkmcnt(0)
	v_fmac_f32_e32 v46, v7, v42
	v_fmac_f32_e32 v46, v8, v43
	v_fmac_f32_e32 v46, v9, v44
	v_fmac_f32_e32 v46, v10, v45
	ds_read_b128 v[42:45], v21 offset:1072
	s_waitcnt lgkmcnt(0)
	v_fmac_f32_e32 v46, v6, v42
	v_fmac_f32_e32 v46, v5, v43
	v_fmac_f32_e32 v46, v4, v44
	v_fmac_f32_e32 v46, v1, v45
	v_mul_f32_e64 v43, |v46|, s46
	v_exp_f32_e32 v43, v43
	v_min_f32_e32 v42, 0, v46
	v_add_f32_e32 v43, 1.0, v43
	v_cmp_gt_f32_e32 vcc, s47, v43
	s_nop 1
	v_cndmask_b32_e64 v44, 0, 32, vcc
	v_ldexp_f32 v43, v43, v44
	v_log_f32_e32 v43, v43
	s_nop 0
	v_mul_f32_e32 v44, 0x3f317217, v43
	v_fma_f32 v44, v43, s4, -v44
	v_fmac_f32_e32 v44, 0x3377d1cf, v43
	v_fmac_f32_e32 v44, 0x3f317217, v43
	v_cmp_lt_f32_e64 s[0:1], |v43|, s90
	s_nop 1
	v_cndmask_b32_e64 v43, v43, v44, s[0:1]
	v_cndmask_b32_e32 v44, 0, v203, vcc
	v_sub_f32_e32 v43, v43, v44
	ds_read_b128 v[44:47], v21 offset:1088
	v_sub_f32_e32 v42, v42, v43
	v_fmamk_f32 v42, v42, 0x3d800000, v41
	s_waitcnt lgkmcnt(0)
	v_fma_f32 v43, v16, v44, v11
	v_fmac_f32_e32 v43, v17, v45
	v_fmac_f32_e32 v43, v18, v46
	v_fmac_f32_e32 v43, v19, v47
	ds_read_b128 v[44:47], v21 offset:1104
	s_waitcnt lgkmcnt(0)
	v_fmac_f32_e32 v43, v12, v44
	v_fmac_f32_e32 v43, v13, v45
	v_fmac_f32_e32 v43, v14, v46
	v_fmac_f32_e32 v43, v15, v47
	ds_read_b128 v[44:47], v21 offset:1120
	s_waitcnt lgkmcnt(0)
	v_fmac_f32_e32 v43, v7, v44
	v_fmac_f32_e32 v43, v8, v45
	v_fmac_f32_e32 v43, v9, v46
	v_fmac_f32_e32 v43, v10, v47
	ds_read_b128 v[44:47], v21 offset:1136
	s_waitcnt lgkmcnt(0)
; DI float log_sigmoid_fast(float x) { return fminf(x, 0.f) - __logf(1.0f + __expf(-fabsf(x))); }
; template <int MODE>
; DI void gla4_unit(const bf16_t* z, float* ST, float* DEC, bf16_t* Y, const float* aw_g, const float* ab_g, const float* ng, ldsp lds, int tid, int u) {
;     ...
;         float run = 0.f;
; #pragma unroll
;         for (int i = 0; i < 32; ++i) {
;             const int t = 32 * half + i;
;             float al = ab;
; #pragma unroll
;             for (int r = 0; r < 16; ++r) al += alr[t * 16 + r] * aw[r];
;             run += log_sigmoid_fast(al) * (1.0f / 16.0f);
;             bc[i] = run;
;         }
	v_fmac_f32_e32 v43, v6, v44
	v_fmac_f32_e32 v43, v5, v45
	v_fmac_f32_e32 v43, v4, v46
	v_fmac_f32_e32 v43, v1, v47
	v_min_f32_e32 v44, 0, v43
	v_mul_f32_e64 v43, |v43|, s46
	v_exp_f32_e32 v43, v43
	s_nop 0
	v_add_f32_e32 v43, 1.0, v43
	v_cmp_gt_f32_e32 vcc, s47, v43
	s_nop 1
	v_cndmask_b32_e64 v45, 0, 32, vcc
	v_ldexp_f32 v43, v43, v45
	v_log_f32_e32 v43, v43
	s_nop 0
	v_mul_f32_e32 v45, 0x3f317217, v43
	v_fma_f32 v45, v43, s4, -v45
	v_fmac_f32_e32 v45, 0x3377d1cf, v43
	v_fmac_f32_e32 v45, 0x3f317217, v43
	v_cmp_lt_f32_e64 s[0:1], |v43|, s90
	s_nop 1
	v_cndmask_b32_e64 v43, v43, v45, s[0:1]
	v_cndmask_b32_e32 v45, 0, v203, vcc
	v_sub_f32_e32 v43, v43, v45
	v_sub_f32_e32 v43, v44, v43
	ds_read_b128 v[44:47], v21 offset:1152
	v_fmamk_f32 v43, v43, 0x3d800000, v42
	s_waitcnt lgkmcnt(0)
	v_fma_f32 v48, v16, v44, v11
	v_fmac_f32_e32 v48, v17, v45
	v_fmac_f32_e32 v48, v18, v46
	v_fmac_f32_e32 v48, v19, v47
	ds_read_b128 v[44:47], v21 offset:1168
	s_waitcnt lgkmcnt(0)
	v_fmac_f32_e32 v48, v12, v44
	v_fmac_f32_e32 v48, v13, v45
	v_fmac_f32_e32 v48, v14, v46
	v_fmac_f32_e32 v48, v15, v47
	ds_read_b128 v[44:47], v21 offset:1184
	s_waitcnt lgkmcnt(0)
	v_fmac_f32_e32 v48, v7, v44
	v_fmac_f32_e32 v48, v8, v45
	v_fmac_f32_e32 v48, v9, v46
	v_fmac_f32_e32 v48, v10, v47
	ds_read_b128 v[44:47], v21 offset:1200
	s_waitcnt lgkmcnt(0)
	v_fmac_f32_e32 v48, v6, v44
	v_fmac_f32_e32 v48, v5, v45
	v_fmac_f32_e32 v48, v4, v46
	v_fmac_f32_e32 v48, v1, v47
	v_mul_f32_e64 v45, |v48|, s46
	v_exp_f32_e32 v45, v45
	v_min_f32_e32 v44, 0, v48
	v_add_f32_e32 v45, 1.0, v45
	v_cmp_gt_f32_e32 vcc, s47, v45
	s_nop 1
	v_cndmask_b32_e64 v46, 0, 32, vcc
	v_ldexp_f32 v45, v45, v46
	v_log_f32_e32 v45, v45
	s_nop 0
	v_mul_f32_e32 v46, 0x3f317217, v45
	v_fma_f32 v46, v45, s4, -v46
	v_fmac_f32_e32 v46, 0x3377d1cf, v45
	v_fmac_f32_e32 v46, 0x3f317217, v45
	v_cmp_lt_f32_e64 s[0:1], |v45|, s90
	s_nop 1
	v_cndmask_b32_e64 v45, v45, v46, s[0:1]
	v_cndmask_b32_e32 v46, 0, v203, vcc
	v_sub_f32_e32 v45, v45, v46
	ds_read_b128 v[46:49], v21 offset:1216
	v_sub_f32_e32 v44, v44, v45
	v_fmamk_f32 v44, v44, 0x3d800000, v43
	s_waitcnt lgkmcnt(0)
	v_fma_f32 v45, v16, v46, v11
	v_fmac_f32_e32 v45, v17, v47
	v_fmac_f32_e32 v45, v18, v48
	v_fmac_f32_e32 v45, v19, v49
	ds_read_b128 v[46:49], v21 offset:1232
	s_waitcnt lgkmcnt(0)
	v_fmac_f32_e32 v45, v12, v46
	v_fmac_f32_e32 v45, v13, v47
	v_fmac_f32_e32 v45, v14, v48
	v_fmac_f32_e32 v45, v15, v49
	ds_read_b128 v[46:49], v21 offset:1248
	s_waitcnt lgkmcnt(0)
	v_fmac_f32_e32 v45, v7, v46
	v_fmac_f32_e32 v45, v8, v47
	v_fmac_f32_e32 v45, v9, v48
	v_fmac_f32_e32 v45, v10, v49
	ds_read_b128 v[46:49], v21 offset:1264
	s_waitcnt lgkmcnt(0)
	v_fmac_f32_e32 v45, v6, v46
	v_fmac_f32_e32 v45, v5, v47
	v_fmac_f32_e32 v45, v4, v48
	v_fmac_f32_e32 v45, v1, v49
	v_min_f32_e32 v46, 0, v45
	v_mul_f32_e64 v45, |v45|, s46
	v_exp_f32_e32 v45, v45
	s_nop 0
	v_add_f32_e32 v45, 1.0, v45
	v_cmp_gt_f32_e32 vcc, s47, v45
	s_nop 1
	v_cndmask_b32_e64 v47, 0, 32, vcc
	v_ldexp_f32 v45, v45, v47
	v_log_f32_e32 v45, v45
	s_nop 0
	v_mul_f32_e32 v47, 0x3f317217, v45
	v_fma_f32 v47, v45, s4, -v47
	v_fmac_f32_e32 v47, 0x3377d1cf, v45
	v_fmac_f32_e32 v47, 0x3f317217, v45
	v_cmp_lt_f32_e64 s[0:1], |v45|, s90
	s_nop 1
	v_cndmask_b32_e64 v45, v45, v47, s[0:1]
	v_cndmask_b32_e32 v47, 0, v203, vcc
	v_sub_f32_e32 v45, v45, v47
	v_sub_f32_e32 v45, v46, v45
	ds_read_b128 v[46:49], v21 offset:1280
	v_fmamk_f32 v45, v45, 0x3d800000, v44
	s_waitcnt lgkmcnt(0)
	v_fma_f32 v50, v16, v46, v11
	v_fmac_f32_e32 v50, v17, v47
	v_fmac_f32_e32 v50, v18, v48
	v_fmac_f32_e32 v50, v19, v49
	ds_read_b128 v[46:49], v21 offset:1296
	s_waitcnt lgkmcnt(0)
	v_fmac_f32_e32 v50, v12, v46
	v_fmac_f32_e32 v50, v13, v47
	v_fmac_f32_e32 v50, v14, v48
	v_fmac_f32_e32 v50, v15, v49
	ds_read_b128 v[46:49], v21 offset:1312
	s_waitcnt lgkmcnt(0)
	v_fmac_f32_e32 v50, v7, v46
	v_fmac_f32_e32 v50, v8, v47
	v_fmac_f32_e32 v50, v9, v48
	v_fmac_f32_e32 v50, v10, v49
	ds_read_b128 v[46:49], v21 offset:1328
	s_waitcnt lgkmcnt(0)
	v_fmac_f32_e32 v50, v6, v46
	v_fmac_f32_e32 v50, v5, v47
	v_fmac_f32_e32 v50, v4, v48
	v_fmac_f32_e32 v50, v1, v49
	v_mul_f32_e64 v47, |v50|, s46
	v_exp_f32_e32 v47, v47
	v_min_f32_e32 v46, 0, v50
	v_add_f32_e32 v47, 1.0, v47
	v_cmp_gt_f32_e32 vcc, s47, v47
	s_nop 1
	v_cndmask_b32_e64 v48, 0, 32, vcc
	v_ldexp_f32 v47, v47, v48
	v_log_f32_e32 v47, v47
	s_nop 0
	v_mul_f32_e32 v48, 0x3f317217, v47
	v_fma_f32 v48, v47, s4, -v48
	v_fmac_f32_e32 v48, 0x3377d1cf, v47
	v_fmac_f32_e32 v48, 0x3f317217, v47
	v_cmp_lt_f32_e64 s[0:1], |v47|, s90
	s_nop 1
	v_cndmask_b32_e64 v47, v47, v48, s[0:1]
	v_cndmask_b32_e32 v48, 0, v203, vcc
	v_sub_f32_e32 v47, v47, v48
	ds_read_b128 v[48:51], v21 offset:1344
	v_sub_f32_e32 v46, v46, v47
	v_fmamk_f32 v46, v46, 0x3d800000, v45
	s_waitcnt lgkmcnt(0)
	v_fma_f32 v47, v16, v48, v11
	v_fmac_f32_e32 v47, v17, v49
	v_fmac_f32_e32 v47, v18, v50
	v_fmac_f32_e32 v47, v19, v51
	ds_read_b128 v[48:51], v21 offset:1360
	s_waitcnt lgkmcnt(0)
	v_fmac_f32_e32 v47, v12, v48
	v_fmac_f32_e32 v47, v13, v49
	v_fmac_f32_e32 v47, v14, v50
	v_fmac_f32_e32 v47, v15, v51
	ds_read_b128 v[48:51], v21 offset:1376
	s_waitcnt lgkmcnt(0)
	v_fmac_f32_e32 v47, v7, v48
	v_fmac_f32_e32 v47, v8, v49
	v_fmac_f32_e32 v47, v9, v50
	v_fmac_f32_e32 v47, v10, v51
	ds_read_b128 v[48:51], v21 offset:1392
	s_waitcnt lgkmcnt(0)
; DI float log_sigmoid_fast(float x) { return fminf(x, 0.f) - __logf(1.0f + __expf(-fabsf(x))); }
; template <int MODE>
; DI void gla4_unit(const bf16_t* z, float* ST, float* DEC, bf16_t* Y, const float* aw_g, const float* ab_g, const float* ng, ldsp lds, int tid, int u) {
;     ...
;         float run = 0.f;
; #pragma unroll
;         for (int i = 0; i < 32; ++i) {
;             const int t = 32 * half + i;
;             float al = ab;
; #pragma unroll
;             for (int r = 0; r < 16; ++r) al += alr[t * 16 + r] * aw[r];
;             run += log_sigmoid_fast(al) * (1.0f / 16.0f);
;             bc[i] = run;
;         }
	v_fmac_f32_e32 v47, v6, v48
	v_fmac_f32_e32 v47, v5, v49
	v_fmac_f32_e32 v47, v4, v50
	v_fmac_f32_e32 v47, v1, v51
	v_min_f32_e32 v48, 0, v47
	v_mul_f32_e64 v47, |v47|, s46
	v_exp_f32_e32 v47, v47
	s_nop 0
	v_add_f32_e32 v47, 1.0, v47
	v_cmp_gt_f32_e32 vcc, s47, v47
	s_nop 1
	v_cndmask_b32_e64 v49, 0, 32, vcc
	v_ldexp_f32 v47, v47, v49
	v_log_f32_e32 v47, v47
	s_nop 0
	v_mul_f32_e32 v49, 0x3f317217, v47
	v_fma_f32 v49, v47, s4, -v49
	v_fmac_f32_e32 v49, 0x3377d1cf, v47
	v_fmac_f32_e32 v49, 0x3f317217, v47
	v_cmp_lt_f32_e64 s[0:1], |v47|, s90
	s_nop 1
	v_cndmask_b32_e64 v47, v47, v49, s[0:1]
	v_cndmask_b32_e32 v49, 0, v203, vcc
	v_sub_f32_e32 v47, v47, v49
	v_sub_f32_e32 v47, v48, v47
	ds_read_b128 v[48:51], v21 offset:1408
	v_fmamk_f32 v47, v47, 0x3d800000, v46
	s_waitcnt lgkmcnt(0)
	v_fma_f32 v52, v16, v48, v11
	v_fmac_f32_e32 v52, v17, v49
	v_fmac_f32_e32 v52, v18, v50
	v_fmac_f32_e32 v52, v19, v51
	ds_read_b128 v[48:51], v21 offset:1424
	s_waitcnt lgkmcnt(0)
	v_fmac_f32_e32 v52, v12, v48
	v_fmac_f32_e32 v52, v13, v49
	v_fmac_f32_e32 v52, v14, v50
	v_fmac_f32_e32 v52, v15, v51
	ds_read_b128 v[48:51], v21 offset:1440
	s_waitcnt lgkmcnt(0)
	v_fmac_f32_e32 v52, v7, v48
	v_fmac_f32_e32 v52, v8, v49
	v_fmac_f32_e32 v52, v9, v50
	v_fmac_f32_e32 v52, v10, v51
	ds_read_b128 v[48:51], v21 offset:1456
	s_waitcnt lgkmcnt(0)
	v_fmac_f32_e32 v52, v6, v48
	v_fmac_f32_e32 v52, v5, v49
	v_fmac_f32_e32 v52, v4, v50
	v_fmac_f32_e32 v52, v1, v51
	v_mul_f32_e64 v49, |v52|, s46
	v_exp_f32_e32 v49, v49
	v_min_f32_e32 v48, 0, v52
	v_add_f32_e32 v49, 1.0, v49
	v_cmp_gt_f32_e32 vcc, s47, v49
	s_nop 1
	v_cndmask_b32_e64 v50, 0, 32, vcc
	v_ldexp_f32 v49, v49, v50
	v_log_f32_e32 v49, v49
	s_nop 0
	v_mul_f32_e32 v50, 0x3f317217, v49
	v_fma_f32 v50, v49, s4, -v50
	v_fmac_f32_e32 v50, 0x3377d1cf, v49
	v_fmac_f32_e32 v50, 0x3f317217, v49
	v_cmp_lt_f32_e64 s[0:1], |v49|, s90
	s_nop 1
	v_cndmask_b32_e64 v49, v49, v50, s[0:1]
	v_cndmask_b32_e32 v50, 0, v203, vcc
	v_sub_f32_e32 v49, v49, v50
	ds_read_b128 v[50:53], v21 offset:1472
	v_sub_f32_e32 v48, v48, v49
	v_fmamk_f32 v48, v48, 0x3d800000, v47
	s_waitcnt lgkmcnt(0)
	v_fma_f32 v49, v16, v50, v11
	v_fmac_f32_e32 v49, v17, v51
	v_fmac_f32_e32 v49, v18, v52
	v_fmac_f32_e32 v49, v19, v53
	ds_read_b128 v[50:53], v21 offset:1488
	s_waitcnt lgkmcnt(0)
	v_fmac_f32_e32 v49, v12, v50
	v_fmac_f32_e32 v49, v13, v51
	v_fmac_f32_e32 v49, v14, v52
	v_fmac_f32_e32 v49, v15, v53
	ds_read_b128 v[50:53], v21 offset:1504
	s_waitcnt lgkmcnt(0)
	v_fmac_f32_e32 v49, v7, v50
	v_fmac_f32_e32 v49, v8, v51
	v_fmac_f32_e32 v49, v9, v52
	v_fmac_f32_e32 v49, v10, v53
	ds_read_b128 v[50:53], v21 offset:1520
	s_waitcnt lgkmcnt(0)
	v_fmac_f32_e32 v49, v6, v50
	v_fmac_f32_e32 v49, v5, v51
	v_fmac_f32_e32 v49, v4, v52
	v_fmac_f32_e32 v49, v1, v53
	v_min_f32_e32 v50, 0, v49
	v_mul_f32_e64 v49, |v49|, s46
	v_exp_f32_e32 v49, v49
	ds_read_b128 v[52:55], v21 offset:1536
	v_add_f32_e32 v49, 1.0, v49
	v_cmp_gt_f32_e32 vcc, s47, v49
	s_nop 1
	v_cndmask_b32_e64 v51, 0, 32, vcc
	v_ldexp_f32 v49, v49, v51
	v_log_f32_e32 v49, v49
	s_nop 0
	v_mul_f32_e32 v51, 0x3f317217, v49
	v_fma_f32 v51, v49, s4, -v51
	v_fmac_f32_e32 v51, 0x3377d1cf, v49
	v_fmac_f32_e32 v51, 0x3f317217, v49
	v_cmp_lt_f32_e64 s[0:1], |v49|, s90
	s_nop 1
	v_cndmask_b32_e64 v49, v49, v51, s[0:1]
	v_cndmask_b32_e32 v51, 0, v203, vcc
	v_sub_f32_e32 v49, v49, v51
	v_sub_f32_e32 v49, v50, v49
	v_fmamk_f32 v50, v49, 0x3d800000, v48
	s_waitcnt lgkmcnt(0)
	v_fma_f32 v49, v16, v52, v11
	v_fmac_f32_e32 v49, v17, v53
	v_fmac_f32_e32 v49, v18, v54
	v_fmac_f32_e32 v49, v19, v55
	ds_read_b128 v[52:55], v21 offset:1552
	s_waitcnt lgkmcnt(0)
	v_fmac_f32_e32 v49, v12, v52
	v_fmac_f32_e32 v49, v13, v53
	v_fmac_f32_e32 v49, v14, v54
	v_fmac_f32_e32 v49, v15, v55
	ds_read_b128 v[52:55], v21 offset:1568
	s_waitcnt lgkmcnt(0)
	v_fmac_f32_e32 v49, v7, v52
	v_fmac_f32_e32 v49, v8, v53
	v_fmac_f32_e32 v49, v9, v54
	v_fmac_f32_e32 v49, v10, v55
	ds_read_b128 v[52:55], v21 offset:1584
	s_waitcnt lgkmcnt(0)
	v_fmac_f32_e32 v49, v6, v52
	v_fmac_f32_e32 v49, v5, v53
	v_fmac_f32_e32 v49, v4, v54
	v_fmac_f32_e32 v49, v1, v55
	v_min_f32_e32 v51, 0, v49
	v_mul_f32_e64 v49, |v49|, s46
	v_exp_f32_e32 v49, v49
	s_nop 0
	v_add_f32_e32 v49, 1.0, v49
	v_cmp_gt_f32_e32 vcc, s47, v49
	s_nop 1
	v_cndmask_b32_e64 v52, 0, 32, vcc
	v_ldexp_f32 v49, v49, v52
	v_log_f32_e32 v49, v49
	s_nop 0
	v_mul_f32_e32 v52, 0x3f317217, v49
	v_fma_f32 v52, v49, s4, -v52
	v_fmac_f32_e32 v52, 0x3377d1cf, v49
	v_fmac_f32_e32 v52, 0x3f317217, v49
	v_cmp_lt_f32_e64 s[0:1], |v49|, s90
	s_nop 1
	v_cndmask_b32_e64 v49, v49, v52, s[0:1]
	v_cndmask_b32_e32 v52, 0, v203, vcc
	v_sub_f32_e32 v49, v49, v52
	ds_read_b128 v[52:55], v21 offset:1600
	v_sub_f32_e32 v49, v51, v49
	v_fmamk_f32 v51, v49, 0x3d800000, v50
	s_waitcnt lgkmcnt(0)
	v_fma_f32 v49, v16, v52, v11
	v_fmac_f32_e32 v49, v17, v53
	v_fmac_f32_e32 v49, v18, v54
	v_fmac_f32_e32 v49, v19, v55
	ds_read_b128 v[52:55], v21 offset:1616
	s_waitcnt lgkmcnt(0)
	v_fmac_f32_e32 v49, v12, v52
	v_fmac_f32_e32 v49, v13, v53
	v_fmac_f32_e32 v49, v14, v54
	v_fmac_f32_e32 v49, v15, v55
	ds_read_b128 v[52:55], v21 offset:1632
	s_waitcnt lgkmcnt(0)
	v_fmac_f32_e32 v49, v7, v52
	v_fmac_f32_e32 v49, v8, v53
	v_fmac_f32_e32 v49, v9, v54
	v_fmac_f32_e32 v49, v10, v55
	ds_read_b128 v[52:55], v21 offset:1648
	s_waitcnt lgkmcnt(0)
; DI float log_sigmoid_fast(float x) { return fminf(x, 0.f) - __logf(1.0f + __expf(-fabsf(x))); }
; template <int MODE>
; DI void gla4_unit(const bf16_t* z, float* ST, float* DEC, bf16_t* Y, const float* aw_g, const float* ab_g, const float* ng, ldsp lds, int tid, int u) {
;     ...
;         float run = 0.f;
; #pragma unroll
;         for (int i = 0; i < 32; ++i) {
;             const int t = 32 * half + i;
;             float al = ab;
; #pragma unroll
;             for (int r = 0; r < 16; ++r) al += alr[t * 16 + r] * aw[r];
;             run += log_sigmoid_fast(al) * (1.0f / 16.0f);
;             bc[i] = run;
;         }
	v_fmac_f32_e32 v49, v6, v52
	v_fmac_f32_e32 v49, v5, v53
	v_fmac_f32_e32 v49, v4, v54
	v_fmac_f32_e32 v49, v1, v55
	v_min_f32_e32 v52, 0, v49
	v_mul_f32_e64 v49, |v49|, s46
	v_exp_f32_e32 v49, v49
	ds_read_b128 v[54:57], v21 offset:1664
	v_add_f32_e32 v49, 1.0, v49
	v_cmp_gt_f32_e32 vcc, s47, v49
	s_nop 1
	v_cndmask_b32_e64 v53, 0, 32, vcc
	v_ldexp_f32 v49, v49, v53
	v_log_f32_e32 v49, v49
	s_nop 0
	v_mul_f32_e32 v53, 0x3f317217, v49
	v_fma_f32 v53, v49, s4, -v53
	v_fmac_f32_e32 v53, 0x3377d1cf, v49
	v_fmac_f32_e32 v53, 0x3f317217, v49
	v_cmp_lt_f32_e64 s[0:1], |v49|, s90
	s_nop 1
	v_cndmask_b32_e64 v49, v49, v53, s[0:1]
	v_cndmask_b32_e32 v53, 0, v203, vcc
	v_sub_f32_e32 v49, v49, v53
	v_sub_f32_e32 v49, v52, v49
	v_fmamk_f32 v52, v49, 0x3d800000, v51
	s_waitcnt lgkmcnt(0)
	v_fma_f32 v49, v16, v54, v11
	v_fmac_f32_e32 v49, v17, v55
	v_fmac_f32_e32 v49, v18, v56
	v_fmac_f32_e32 v49, v19, v57
	ds_read_b128 v[54:57], v21 offset:1680
	s_waitcnt lgkmcnt(0)
	v_fmac_f32_e32 v49, v12, v54
	v_fmac_f32_e32 v49, v13, v55
	v_fmac_f32_e32 v49, v14, v56
	v_fmac_f32_e32 v49, v15, v57
	ds_read_b128 v[54:57], v21 offset:1696
	s_waitcnt lgkmcnt(0)
	v_fmac_f32_e32 v49, v7, v54
	v_fmac_f32_e32 v49, v8, v55
	v_fmac_f32_e32 v49, v9, v56
	v_fmac_f32_e32 v49, v10, v57
	ds_read_b128 v[54:57], v21 offset:1712
	s_waitcnt lgkmcnt(0)
	v_fmac_f32_e32 v49, v6, v54
	v_fmac_f32_e32 v49, v5, v55
	v_fmac_f32_e32 v49, v4, v56
	v_fmac_f32_e32 v49, v1, v57
	v_min_f32_e32 v53, 0, v49
	v_mul_f32_e64 v49, |v49|, s46
	v_exp_f32_e32 v49, v49
	s_nop 0
	v_add_f32_e32 v49, 1.0, v49
	v_cmp_gt_f32_e32 vcc, s47, v49
	s_nop 1
	v_cndmask_b32_e64 v54, 0, 32, vcc
	v_ldexp_f32 v49, v49, v54
	v_log_f32_e32 v49, v49
	s_nop 0
	v_mul_f32_e32 v54, 0x3f317217, v49
	v_fma_f32 v54, v49, s4, -v54
	v_fmac_f32_e32 v54, 0x3377d1cf, v49
	v_fmac_f32_e32 v54, 0x3f317217, v49
	v_cmp_lt_f32_e64 s[0:1], |v49|, s90
	s_nop 1
	v_cndmask_b32_e64 v49, v49, v54, s[0:1]
	v_cndmask_b32_e32 v54, 0, v203, vcc
	v_sub_f32_e32 v49, v49, v54
	ds_read_b128 v[54:57], v21 offset:1728
	v_sub_f32_e32 v49, v53, v49
	v_fmamk_f32 v53, v49, 0x3d800000, v52
	s_waitcnt lgkmcnt(0)
	v_fma_f32 v49, v16, v54, v11
	v_fmac_f32_e32 v49, v17, v55
	v_fmac_f32_e32 v49, v18, v56
	v_fmac_f32_e32 v49, v19, v57
	ds_read_b128 v[54:57], v21 offset:1744
	s_waitcnt lgkmcnt(0)
	v_fmac_f32_e32 v49, v12, v54
	v_fmac_f32_e32 v49, v13, v55
	v_fmac_f32_e32 v49, v14, v56
	v_fmac_f32_e32 v49, v15, v57
	ds_read_b128 v[54:57], v21 offset:1760
	s_waitcnt lgkmcnt(0)
	v_fmac_f32_e32 v49, v7, v54
	v_fmac_f32_e32 v49, v8, v55
	v_fmac_f32_e32 v49, v9, v56
	v_fmac_f32_e32 v49, v10, v57
	ds_read_b128 v[54:57], v21 offset:1776
	s_waitcnt lgkmcnt(0)
	v_fmac_f32_e32 v49, v6, v54
	v_fmac_f32_e32 v49, v5, v55
	v_fmac_f32_e32 v49, v4, v56
	v_fmac_f32_e32 v49, v1, v57
	v_min_f32_e32 v54, 0, v49
	v_mul_f32_e64 v49, |v49|, s46
	v_exp_f32_e32 v49, v49
	ds_read_b128 v[56:59], v21 offset:1792
	v_add_f32_e32 v49, 1.0, v49
	v_cmp_gt_f32_e32 vcc, s47, v49
	s_nop 1
	v_cndmask_b32_e64 v55, 0, 32, vcc
	v_ldexp_f32 v49, v49, v55
	v_log_f32_e32 v49, v49
	s_nop 0
	v_mul_f32_e32 v55, 0x3f317217, v49
	v_fma_f32 v55, v49, s4, -v55
	v_fmac_f32_e32 v55, 0x3377d1cf, v49
	v_fmac_f32_e32 v55, 0x3f317217, v49
	v_cmp_lt_f32_e64 s[0:1], |v49|, s90
	s_nop 1
	v_cndmask_b32_e64 v49, v49, v55, s[0:1]
	v_cndmask_b32_e32 v55, 0, v203, vcc
	v_sub_f32_e32 v49, v49, v55
	v_sub_f32_e32 v49, v54, v49
	v_fmamk_f32 v54, v49, 0x3d800000, v53
	s_waitcnt lgkmcnt(0)
	v_fma_f32 v49, v16, v56, v11
	v_fmac_f32_e32 v49, v17, v57
	v_fmac_f32_e32 v49, v18, v58
	v_fmac_f32_e32 v49, v19, v59
	ds_read_b128 v[56:59], v21 offset:1808
	s_waitcnt lgkmcnt(0)
	v_fmac_f32_e32 v49, v12, v56
	v_fmac_f32_e32 v49, v13, v57
	v_fmac_f32_e32 v49, v14, v58
	v_fmac_f32_e32 v49, v15, v59
	ds_read_b128 v[56:59], v21 offset:1824
	s_waitcnt lgkmcnt(0)
	v_fmac_f32_e32 v49, v7, v56
	v_fmac_f32_e32 v49, v8, v57
	v_fmac_f32_e32 v49, v9, v58
	v_fmac_f32_e32 v49, v10, v59
	ds_read_b128 v[56:59], v21 offset:1840
	s_waitcnt lgkmcnt(0)
	v_fmac_f32_e32 v49, v6, v56
	v_fmac_f32_e32 v49, v5, v57
	v_fmac_f32_e32 v49, v4, v58
	v_fmac_f32_e32 v49, v1, v59
	v_min_f32_e32 v55, 0, v49
	v_mul_f32_e64 v49, |v49|, s46
	v_exp_f32_e32 v49, v49
	s_nop 0
	v_add_f32_e32 v49, 1.0, v49
	v_cmp_gt_f32_e32 vcc, s47, v49
	s_nop 1
	v_cndmask_b32_e64 v56, 0, 32, vcc
	v_ldexp_f32 v49, v49, v56
	v_log_f32_e32 v49, v49
	s_nop 0
	v_mul_f32_e32 v56, 0x3f317217, v49
	v_fma_f32 v56, v49, s4, -v56
	v_fmac_f32_e32 v56, 0x3377d1cf, v49
	v_fmac_f32_e32 v56, 0x3f317217, v49
	v_cmp_lt_f32_e64 s[0:1], |v49|, s90
	s_nop 1
	v_cndmask_b32_e64 v49, v49, v56, s[0:1]
	v_cndmask_b32_e32 v56, 0, v203, vcc
	v_sub_f32_e32 v49, v49, v56
	ds_read_b128 v[56:59], v21 offset:1856
	v_sub_f32_e32 v49, v55, v49
	v_fmamk_f32 v55, v49, 0x3d800000, v54
	s_waitcnt lgkmcnt(0)
	v_fma_f32 v49, v16, v56, v11
	v_fmac_f32_e32 v49, v17, v57
	v_fmac_f32_e32 v49, v18, v58
	v_fmac_f32_e32 v49, v19, v59
	ds_read_b128 v[56:59], v21 offset:1872
	s_waitcnt lgkmcnt(0)
	v_fmac_f32_e32 v49, v12, v56
	v_fmac_f32_e32 v49, v13, v57
	v_fmac_f32_e32 v49, v14, v58
	v_fmac_f32_e32 v49, v15, v59
	ds_read_b128 v[56:59], v21 offset:1888
	s_waitcnt lgkmcnt(0)
	v_fmac_f32_e32 v49, v7, v56
	v_fmac_f32_e32 v49, v8, v57
	v_fmac_f32_e32 v49, v9, v58
	v_fmac_f32_e32 v49, v10, v59
	ds_read_b128 v[56:59], v21 offset:1904
	s_waitcnt lgkmcnt(0)
; #define LAS __attribute__((address_space(3)))
; #define LAS __attribute__((address_space(3)))
; DI float bf1(bf16_t v) { return __uint_as_float((unsigned)v << 16); }
; DI bf16_t f2bf(float f) { return (bf16_t)(pk(f, 0.f) & 0xffffu); }
; DI float log_sigmoid_fast(float x) { return fminf(x, 0.f) - __logf(1.0f + __expf(-fabsf(x))); }
; template <int MODE>
; DI void gla4_unit(const bf16_t* z, float* ST, float* DEC, bf16_t* Y, const float* aw_g, const float* ab_g, const float* ng, ldsp lds, int tid, int u) {
;     ...
;         float run = 0.f;
; #pragma unroll
;         for (int i = 0; i < 32; ++i) {
;             const int t = 32 * half + i;
;             float al = ab;
; #pragma unroll
;             for (int r = 0; r < 16; ++r) al += alr[t * 16 + r] * aw[r];
;             run += log_sigmoid_fast(al) * (1.0f / 16.0f);
;             bc[i] = run;
;         }
;         tot[half * 256 + hd * 64 + d] = run;
;     }
;     __syncthreads();
;     const float t0 = tot[hd * 64 + d], t1 = tot[256 + hd * 64 + d];
;     const float pre = half ? t0 : 0.f, blast = t0 + t1;
;     ...
; #pragma unroll
;         for (int i = 0; i < 32; ++i) {
;             const float bb = bc[i] + pre;
;             LAS bf16_t* qp = (LAS bf16_t*)(hr + (32 * half + i) * 144 + d * 2); LAS bf16_t* kp = (LAS bf16_t*)(hr + G4_R1 + (32 * half + i) * 144 + d * 2);
;             *qp = f2bf(bf1(*qp) * 0.125f * __expf(bb)); *kp = f2bf(bf1(*kp) * __expf(-bb));
;         }
	v_fmac_f32_e32 v49, v6, v56
	v_fmac_f32_e32 v49, v5, v57
	v_fmac_f32_e32 v49, v4, v58
	v_fmac_f32_e32 v49, v1, v59
	v_min_f32_e32 v56, 0, v49
	v_mul_f32_e64 v49, |v49|, s46
	v_exp_f32_e32 v49, v49
	ds_read_b128 v[58:61], v21 offset:1920
	v_add_f32_e32 v49, 1.0, v49
	v_cmp_gt_f32_e32 vcc, s47, v49
	s_nop 1
	v_cndmask_b32_e64 v57, 0, 32, vcc
	v_ldexp_f32 v49, v49, v57
	v_log_f32_e32 v49, v49
	s_nop 0
	v_mul_f32_e32 v57, 0x3f317217, v49
	v_fma_f32 v57, v49, s4, -v57
	v_fmac_f32_e32 v57, 0x3377d1cf, v49
	v_fmac_f32_e32 v57, 0x3f317217, v49
	v_cmp_lt_f32_e64 s[0:1], |v49|, s90
	s_nop 1
	v_cndmask_b32_e64 v49, v49, v57, s[0:1]
	v_cndmask_b32_e32 v57, 0, v203, vcc
	v_sub_f32_e32 v49, v49, v57
	v_sub_f32_e32 v49, v56, v49
	v_fmamk_f32 v57, v49, 0x3d800000, v55
	s_waitcnt lgkmcnt(0)
	v_fma_f32 v49, v16, v58, v11
	v_fmac_f32_e32 v49, v17, v59
	v_fmac_f32_e32 v49, v18, v60
	v_fmac_f32_e32 v49, v19, v61
	ds_read_b128 v[58:61], v21 offset:1936
	s_waitcnt lgkmcnt(0)
	v_fmac_f32_e32 v49, v12, v58
	v_fmac_f32_e32 v49, v13, v59
	v_fmac_f32_e32 v49, v14, v60
	v_fmac_f32_e32 v49, v15, v61
	ds_read_b128 v[58:61], v21 offset:1952
	s_waitcnt lgkmcnt(0)
	v_fmac_f32_e32 v49, v7, v58
	v_fmac_f32_e32 v49, v8, v59
	v_fmac_f32_e32 v49, v9, v60
	v_fmac_f32_e32 v49, v10, v61
	ds_read_b128 v[58:61], v21 offset:1968
	s_waitcnt lgkmcnt(0)
	v_fmac_f32_e32 v49, v6, v58
	v_fmac_f32_e32 v49, v5, v59
	v_fmac_f32_e32 v49, v4, v60
	v_fmac_f32_e32 v49, v1, v61
	ds_read_b128 v[60:63], v21 offset:1984
	v_min_f32_e32 v56, 0, v49
	v_mul_f32_e64 v49, |v49|, s46
	v_exp_f32_e32 v49, v49
	s_waitcnt lgkmcnt(0)
	v_fmac_f32_e32 v11, v16, v60
	v_fmac_f32_e32 v11, v17, v61
	v_fmac_f32_e32 v11, v18, v62
	v_fmac_f32_e32 v11, v19, v63
	ds_read_b128 v[16:19], v21 offset:2000
	v_add_f32_e32 v49, 1.0, v49
	v_cmp_gt_f32_e32 vcc, s47, v49
	s_waitcnt lgkmcnt(0)
	v_fmac_f32_e32 v11, v12, v16
	v_fmac_f32_e32 v11, v13, v17
	v_fmac_f32_e32 v11, v14, v18
	v_fmac_f32_e32 v11, v15, v19
	ds_read_b128 v[12:15], v21 offset:2016
	v_cndmask_b32_e64 v58, 0, 32, vcc
	v_ldexp_f32 v49, v49, v58
	v_log_f32_e32 v49, v49
	s_waitcnt lgkmcnt(0)
	v_fmac_f32_e32 v11, v7, v12
	v_fmac_f32_e32 v11, v8, v13
	v_fmac_f32_e32 v11, v9, v14
	v_fmac_f32_e32 v11, v10, v15
	ds_read_b128 v[12:15], v21 offset:2032
	v_mul_f32_e32 v58, 0x3f317217, v49
	v_fma_f32 v58, v49, s4, -v58
	v_fmac_f32_e32 v58, 0x3377d1cf, v49
	v_fmac_f32_e32 v58, 0x3f317217, v49
	s_waitcnt lgkmcnt(0)
	v_fmac_f32_e32 v11, v6, v12
	v_fmac_f32_e32 v11, v5, v13
	v_fmac_f32_e32 v11, v4, v14
	v_fmac_f32_e32 v11, v1, v15
	v_mul_f32_e64 v4, |v11|, s46
	v_exp_f32_e32 v4, v4
	v_cmp_lt_f32_e64 s[0:1], |v49|, s90
	v_min_f32_e32 v1, 0, v11
	v_add_f32_e32 v4, 1.0, v4
	v_cndmask_b32_e64 v49, v49, v58, s[0:1]
	v_cndmask_b32_e32 v58, 0, v203, vcc
	v_cmp_gt_f32_e32 vcc, s47, v4
	v_sub_f32_e32 v49, v49, v58
	v_sub_f32_e32 v49, v56, v49
	v_cndmask_b32_e64 v5, 0, 32, vcc
	v_ldexp_f32 v4, v4, v5
	v_log_f32_e32 v4, v4
	v_fmamk_f32 v58, v49, 0x3d800000, v57
	v_add_u32_e32 v49, 0, v3
	v_lshlrev_b32_e32 v3, 2, v178
	v_mul_f32_e32 v5, 0x3f317217, v4
	v_fma_f32 v5, v4, s4, -v5
	v_fmac_f32_e32 v5, 0x3377d1cf, v4
	v_fmac_f32_e32 v5, 0x3f317217, v4
	v_cmp_lt_f32_e64 s[0:1], |v4|, s90
	v_lshlrev_b32_e32 v56, 5, v29
	s_nop 0
	v_cndmask_b32_e64 v4, v4, v5, s[0:1]
	v_cndmask_b32_e32 v5, 0, v203, vcc
	v_sub_f32_e32 v4, v4, v5
	v_sub_f32_e32 v1, v1, v4
	s_add_i32 s0, 0, 0x1c000
	v_fmamk_f32 v4, v1, 0x3d800000, v58
	v_lshl_add_u32 v1, v29, 10, s0
	v_add3_u32 v1, v1, v2, v3
	v_lshl_add_u32 v0, v0, 2, s0
	ds_write_b32 v1, v4
	s_waitcnt lgkmcnt(0)
	s_barrier
	ds_read_b32 v0, v0
	v_and_b32_e32 v1, 64, v80
	v_cmp_ne_u32_e32 vcc, 0, v1
	v_mul_u32_u24_e32 v1, 0x1200, v29
	s_waitcnt lgkmcnt(0)
	v_cndmask_b32_e32 v3, 0, v0, vcc
	v_lshlrev_b32_e32 v0, 1, v178
	v_add3_u32 v2, v49, v0, v1
	ds_read_u16 v6, v2
	v_add_f32_e32 v5, v20, v3
	v_mul_f32_e32 v7, 0x3fb8aa3b, v5
	v_exp_f32_e32 v7, v7
	v_mul_f32_e32 v5, 0xbfb8aa3b, v5
	s_waitcnt lgkmcnt(0)
	v_lshlrev_b32_e32 v6, 16, v6
	v_mul_f32_e32 v6, 0x3e000000, v6
	v_mul_f32_e32 v6, v7, v6
	v_cvt_pk_bf16_f32 v6, v6, v157
	ds_write_b16 v2, v6
	ds_read_u16 v6, v2 offset:9216
	v_exp_f32_e32 v5, v5
	s_waitcnt lgkmcnt(0)
	v_lshlrev_b32_e32 v6, 16, v6
	v_mul_f32_e32 v5, v5, v6
	v_cvt_pk_bf16_f32 v5, v5, v157
	ds_read_u16 v6, v2 offset:144
	ds_write_b16 v2, v5 offset:9216
	v_add_f32_e32 v5, v22, v3
	v_mul_f32_e32 v7, 0x3fb8aa3b, v5
	v_exp_f32_e32 v7, v7
	s_waitcnt lgkmcnt(1)
	v_lshlrev_b32_e32 v6, 16, v6
	v_mul_f32_e32 v6, 0x3e000000, v6
	v_mul_f32_e32 v5, 0xbfb8aa3b, v5
	v_mul_f32_e32 v6, v7, v6
	v_cvt_pk_bf16_f32 v6, v6, v157
	ds_write_b16 v2, v6 offset:144
	ds_read_u16 v6, v2 offset:9360
	v_exp_f32_e32 v5, v5
	s_waitcnt lgkmcnt(0)
	v_lshlrev_b32_e32 v6, 16, v6
	v_mul_f32_e32 v5, v5, v6
	v_cvt_pk_bf16_f32 v5, v5, v157
	ds_read_u16 v6, v2 offset:288
	ds_write_b16 v2, v5 offset:9360
	v_add_f32_e32 v5, v23, v3
	v_mul_f32_e32 v7, 0x3fb8aa3b, v5
	v_exp_f32_e32 v7, v7
	s_waitcnt lgkmcnt(1)
	v_lshlrev_b32_e32 v6, 16, v6
	v_mul_f32_e32 v6, 0x3e000000, v6
	v_mul_f32_e32 v5, 0xbfb8aa3b, v5
	v_mul_f32_e32 v6, v7, v6
	v_cvt_pk_bf16_f32 v6, v6, v157
	ds_write_b16 v2, v6 offset:288
	ds_read_u16 v6, v2 offset:9504
	v_exp_f32_e32 v5, v5
	s_waitcnt lgkmcnt(0)
	v_lshlrev_b32_e32 v6, 16, v6
	v_mul_f32_e32 v5, v5, v6
	v_cvt_pk_bf16_f32 v5, v5, v157
	ds_read_u16 v6, v2 offset:432
	ds_write_b16 v2, v5 offset:9504
	v_add_f32_e32 v5, v24, v3
	v_mul_f32_e32 v7, 0x3fb8aa3b, v5
	v_exp_f32_e32 v7, v7
	s_waitcnt lgkmcnt(1)
	v_lshlrev_b32_e32 v6, 16, v6
	v_mul_f32_e32 v6, 0x3e000000, v6
	v_mul_f32_e32 v5, 0xbfb8aa3b, v5
	v_mul_f32_e32 v6, v7, v6
	v_cvt_pk_bf16_f32 v6, v6, v157
	ds_write_b16 v2, v6 offset:432
	ds_read_u16 v6, v2 offset:9648
	v_exp_f32_e32 v5, v5
	s_waitcnt lgkmcnt(0)
; #define LAS __attribute__((address_space(3)))
; #define LAS __attribute__((address_space(3)))
; DI float bf1(bf16_t v) { return __uint_as_float((unsigned)v << 16); }
; DI bf16_t f2bf(float f) { return (bf16_t)(pk(f, 0.f) & 0xffffu); }
; template <int MODE>
; DI void gla4_unit(const bf16_t* z, float* ST, float* DEC, bf16_t* Y, const float* aw_g, const float* ab_g, const float* ng, ldsp lds, int tid, int u) {
;     ...
;         for (int i = 0; i < 32; ++i) {
;             const float bb = bc[i] + pre;
;             LAS bf16_t* qp = (LAS bf16_t*)(hr + (32 * half + i) * 144 + d * 2); LAS bf16_t* kp = (LAS bf16_t*)(hr + G4_R1 + (32 * half + i) * 144 + d * 2);
;             *qp = f2bf(bf1(*qp) * 0.125f * __expf(bb)); *kp = f2bf(bf1(*kp) * __expf(-bb));
;         }
	v_lshlrev_b32_e32 v6, 16, v6
	v_mul_f32_e32 v5, v5, v6
	v_cvt_pk_bf16_f32 v5, v5, v157
	ds_read_u16 v6, v2 offset:576
	ds_write_b16 v2, v5 offset:9648
	v_add_f32_e32 v5, v25, v3
	v_mul_f32_e32 v7, 0x3fb8aa3b, v5
	v_exp_f32_e32 v7, v7
	s_waitcnt lgkmcnt(1)
	v_lshlrev_b32_e32 v6, 16, v6
	v_mul_f32_e32 v6, 0x3e000000, v6
	v_mul_f32_e32 v5, 0xbfb8aa3b, v5
	v_mul_f32_e32 v6, v7, v6
	v_cvt_pk_bf16_f32 v6, v6, v157
	ds_write_b16 v2, v6 offset:576
	ds_read_u16 v6, v2 offset:9792
	v_exp_f32_e32 v5, v5
	s_waitcnt lgkmcnt(0)
	v_lshlrev_b32_e32 v6, 16, v6
	v_mul_f32_e32 v5, v5, v6
	v_cvt_pk_bf16_f32 v5, v5, v157
	ds_read_u16 v6, v2 offset:720
	ds_write_b16 v2, v5 offset:9792
	v_add_f32_e32 v5, v26, v3
	v_mul_f32_e32 v7, 0x3fb8aa3b, v5
	v_exp_f32_e32 v7, v7
	s_waitcnt lgkmcnt(1)
	v_lshlrev_b32_e32 v6, 16, v6
	v_mul_f32_e32 v6, 0x3e000000, v6
	v_mul_f32_e32 v5, 0xbfb8aa3b, v5
	v_mul_f32_e32 v6, v7, v6
	v_cvt_pk_bf16_f32 v6, v6, v157
	ds_write_b16 v2, v6 offset:720
	ds_read_u16 v6, v2 offset:9936
	v_exp_f32_e32 v5, v5
	s_waitcnt lgkmcnt(0)
	v_lshlrev_b32_e32 v6, 16, v6
	v_mul_f32_e32 v5, v5, v6
	v_cvt_pk_bf16_f32 v5, v5, v157
	ds_read_u16 v6, v2 offset:864
	ds_write_b16 v2, v5 offset:9936
	v_add_f32_e32 v5, v27, v3
	v_mul_f32_e32 v7, 0x3fb8aa3b, v5
	v_exp_f32_e32 v7, v7
	s_waitcnt lgkmcnt(1)
	v_lshlrev_b32_e32 v6, 16, v6
	v_mul_f32_e32 v6, 0x3e000000, v6
	v_mul_f32_e32 v5, 0xbfb8aa3b, v5
	v_mul_f32_e32 v6, v7, v6
	v_cvt_pk_bf16_f32 v6, v6, v157
	ds_write_b16 v2, v6 offset:864
	ds_read_u16 v6, v2 offset:10080
	v_exp_f32_e32 v5, v5
	s_waitcnt lgkmcnt(0)
	v_lshlrev_b32_e32 v6, 16, v6
	v_mul_f32_e32 v5, v5, v6
	v_cvt_pk_bf16_f32 v5, v5, v157
	ds_read_u16 v6, v2 offset:1008
	ds_write_b16 v2, v5 offset:10080
	v_add_f32_e32 v5, v30, v3
	v_mul_f32_e32 v7, 0x3fb8aa3b, v5
	v_exp_f32_e32 v7, v7
	s_waitcnt lgkmcnt(1)
	v_lshlrev_b32_e32 v6, 16, v6
	v_mul_f32_e32 v6, 0x3e000000, v6
	v_mul_f32_e32 v5, 0xbfb8aa3b, v5
	v_mul_f32_e32 v6, v7, v6
	v_cvt_pk_bf16_f32 v6, v6, v157
	ds_write_b16 v2, v6 offset:1008
	ds_read_u16 v6, v2 offset:10224
	v_exp_f32_e32 v5, v5
	v_add3_u32 v30, v49, v1, v0
	s_waitcnt lgkmcnt(0)
	v_lshlrev_b32_e32 v6, 16, v6
	v_mul_f32_e32 v5, v5, v6
	v_cvt_pk_bf16_f32 v5, v5, v157
	ds_read_u16 v6, v2 offset:1152
	ds_write_b16 v2, v5 offset:10224
	v_add_f32_e32 v5, v31, v3
	v_mul_f32_e32 v7, 0x3fb8aa3b, v5
	v_exp_f32_e32 v7, v7
	s_waitcnt lgkmcnt(1)
	v_lshlrev_b32_e32 v6, 16, v6
	v_mul_f32_e32 v6, 0x3e000000, v6
	v_mul_f32_e32 v5, 0xbfb8aa3b, v5
	v_mul_f32_e32 v6, v7, v6
	v_cvt_pk_bf16_f32 v6, v6, v157
	ds_write_b16 v2, v6 offset:1152
	ds_read_u16 v6, v2 offset:10368
	v_exp_f32_e32 v5, v5
	s_waitcnt lgkmcnt(0)
	v_lshlrev_b32_e32 v6, 16, v6
	v_mul_f32_e32 v5, v5, v6
	v_cvt_pk_bf16_f32 v5, v5, v157
	ds_read_u16 v6, v2 offset:1296
	ds_write_b16 v2, v5 offset:10368
	v_add_f32_e32 v5, v35, v3
	v_mul_f32_e32 v7, 0x3fb8aa3b, v5
	v_exp_f32_e32 v7, v7
	s_waitcnt lgkmcnt(1)
	v_lshlrev_b32_e32 v6, 16, v6
	v_mul_f32_e32 v6, 0x3e000000, v6
	v_mul_f32_e32 v5, 0xbfb8aa3b, v5
	v_mul_f32_e32 v6, v7, v6
	v_cvt_pk_bf16_f32 v6, v6, v157
	ds_write_b16 v2, v6 offset:1296
	ds_read_u16 v6, v2 offset:10512
	v_exp_f32_e32 v5, v5
	v_mad_u32_u24 v35, v81, s89, v202
	s_waitcnt lgkmcnt(0)
	v_lshlrev_b32_e32 v6, 16, v6
	v_mul_f32_e32 v5, v5, v6
	v_cvt_pk_bf16_f32 v5, v5, v157
	ds_read_u16 v6, v2 offset:1440
	ds_write_b16 v2, v5 offset:10512
	v_add_f32_e32 v5, v36, v3
	v_mul_f32_e32 v7, 0x3fb8aa3b, v5
	v_exp_f32_e32 v7, v7
	s_waitcnt lgkmcnt(1)
	v_lshlrev_b32_e32 v6, 16, v6
	v_mul_f32_e32 v6, 0x3e000000, v6
	v_mul_f32_e32 v5, 0xbfb8aa3b, v5
	v_mul_f32_e32 v6, v7, v6
	v_cvt_pk_bf16_f32 v6, v6, v157
	ds_write_b16 v2, v6 offset:1440
	ds_read_u16 v6, v2 offset:10656
	v_exp_f32_e32 v5, v5
	v_mad_u32_u24 v36, v81, s89, v204
	s_waitcnt lgkmcnt(0)
	v_lshlrev_b32_e32 v6, 16, v6
	v_mul_f32_e32 v5, v5, v6
	v_cvt_pk_bf16_f32 v5, v5, v157
	ds_read_u16 v6, v2 offset:1584
	ds_write_b16 v2, v5 offset:10656
	v_add_f32_e32 v5, v37, v3
	v_mul_f32_e32 v7, 0x3fb8aa3b, v5
	v_exp_f32_e32 v7, v7
	s_waitcnt lgkmcnt(1)
	v_lshlrev_b32_e32 v6, 16, v6
	v_mul_f32_e32 v6, 0x3e000000, v6
	v_mul_f32_e32 v5, 0xbfb8aa3b, v5
	v_mul_f32_e32 v6, v7, v6
	v_cvt_pk_bf16_f32 v6, v6, v157
	ds_write_b16 v2, v6 offset:1584
	ds_read_u16 v6, v2 offset:10800
	v_exp_f32_e32 v5, v5
	v_mad_u32_u24 v37, v81, s89, v205
	s_waitcnt lgkmcnt(0)
	v_lshlrev_b32_e32 v6, 16, v6
	v_mul_f32_e32 v5, v5, v6
	v_cvt_pk_bf16_f32 v5, v5, v157
	ds_read_u16 v6, v2 offset:1728
	ds_write_b16 v2, v5 offset:10800
	v_add_f32_e32 v5, v38, v3
	v_mul_f32_e32 v7, 0x3fb8aa3b, v5
	v_exp_f32_e32 v7, v7
	s_waitcnt lgkmcnt(1)
	v_lshlrev_b32_e32 v6, 16, v6
	v_mul_f32_e32 v6, 0x3e000000, v6
	v_mul_f32_e32 v5, 0xbfb8aa3b, v5
	v_mul_f32_e32 v6, v7, v6
	v_cvt_pk_bf16_f32 v6, v6, v157
	ds_write_b16 v2, v6 offset:1728
	ds_read_u16 v6, v2 offset:10944
	v_exp_f32_e32 v5, v5
	v_or_b32_e32 v38, v56, v81
	s_waitcnt lgkmcnt(0)
	v_lshlrev_b32_e32 v6, 16, v6
	v_mul_f32_e32 v5, v5, v6
	v_cvt_pk_bf16_f32 v5, v5, v157
	ds_read_u16 v6, v2 offset:1872
	ds_write_b16 v2, v5 offset:10944
	v_add_f32_e32 v5, v39, v3
	v_mul_f32_e32 v7, 0x3fb8aa3b, v5
	v_exp_f32_e32 v7, v7
	s_waitcnt lgkmcnt(1)
	v_lshlrev_b32_e32 v6, 16, v6
	v_mul_f32_e32 v6, 0x3e000000, v6
	v_mul_f32_e32 v5, 0xbfb8aa3b, v5
	v_mul_f32_e32 v6, v7, v6
	v_cvt_pk_bf16_f32 v6, v6, v157
	ds_write_b16 v2, v6 offset:1872
	ds_read_u16 v6, v2 offset:11088
	v_exp_f32_e32 v5, v5
	s_waitcnt lgkmcnt(0)
	v_lshlrev_b32_e32 v6, 16, v6
	v_mul_f32_e32 v5, v5, v6
	v_cvt_pk_bf16_f32 v5, v5, v157
	ds_read_u16 v6, v2 offset:2016
	ds_write_b16 v2, v5 offset:11088
	v_add_f32_e32 v5, v40, v3
	v_mul_f32_e32 v7, 0x3fb8aa3b, v5
	v_exp_f32_e32 v7, v7
	s_waitcnt lgkmcnt(1)
; #define LAS __attribute__((address_space(3)))
; #define LAS __attribute__((address_space(3)))
; DI float bf1(bf16_t v) { return __uint_as_float((unsigned)v << 16); }
; DI bf16_t f2bf(float f) { return (bf16_t)(pk(f, 0.f) & 0xffffu); }
; template <int MODE>
; DI void gla4_unit(const bf16_t* z, float* ST, float* DEC, bf16_t* Y, const float* aw_g, const float* ab_g, const float* ng, ldsp lds, int tid, int u) {
;     ...
;         for (int i = 0; i < 32; ++i) {
;             const float bb = bc[i] + pre;
;             LAS bf16_t* qp = (LAS bf16_t*)(hr + (32 * half + i) * 144 + d * 2); LAS bf16_t* kp = (LAS bf16_t*)(hr + G4_R1 + (32 * half + i) * 144 + d * 2);
;             *qp = f2bf(bf1(*qp) * 0.125f * __expf(bb)); *kp = f2bf(bf1(*kp) * __expf(-bb));
;         }
	v_lshlrev_b32_e32 v6, 16, v6
	v_mul_f32_e32 v6, 0x3e000000, v6
	v_mul_f32_e32 v5, 0xbfb8aa3b, v5
	v_mul_f32_e32 v6, v7, v6
	v_cvt_pk_bf16_f32 v6, v6, v157
	ds_write_b16 v2, v6 offset:2016
	ds_read_u16 v6, v2 offset:11232
	v_exp_f32_e32 v5, v5
	s_waitcnt lgkmcnt(0)
	v_lshlrev_b32_e32 v6, 16, v6
	v_mul_f32_e32 v5, v5, v6
	v_cvt_pk_bf16_f32 v5, v5, v157
	ds_read_u16 v6, v2 offset:2160
	ds_write_b16 v2, v5 offset:11232
	v_add_f32_e32 v5, v41, v3
	v_mul_f32_e32 v7, 0x3fb8aa3b, v5
	v_exp_f32_e32 v7, v7
	s_waitcnt lgkmcnt(1)
	v_lshlrev_b32_e32 v6, 16, v6
	v_mul_f32_e32 v6, 0x3e000000, v6
	v_mul_f32_e32 v5, 0xbfb8aa3b, v5
	v_mul_f32_e32 v6, v7, v6
	v_cvt_pk_bf16_f32 v6, v6, v157
	ds_write_b16 v2, v6 offset:2160
	ds_read_u16 v6, v2 offset:11376
	v_exp_f32_e32 v5, v5
	s_waitcnt lgkmcnt(0)
	v_lshlrev_b32_e32 v6, 16, v6
	v_mul_f32_e32 v5, v5, v6
	v_cvt_pk_bf16_f32 v5, v5, v157
	ds_read_u16 v6, v2 offset:2304
	ds_write_b16 v2, v5 offset:11376
	v_add_f32_e32 v5, v42, v3
	v_mul_f32_e32 v7, 0x3fb8aa3b, v5
	v_exp_f32_e32 v7, v7
	s_waitcnt lgkmcnt(1)
	v_lshlrev_b32_e32 v6, 16, v6
	v_mul_f32_e32 v6, 0x3e000000, v6
	v_mul_f32_e32 v5, 0xbfb8aa3b, v5
	v_mul_f32_e32 v6, v7, v6
	v_cvt_pk_bf16_f32 v6, v6, v157
	ds_write_b16 v2, v6 offset:2304
	ds_read_u16 v6, v2 offset:11520
	v_exp_f32_e32 v5, v5
	s_waitcnt lgkmcnt(0)
	v_lshlrev_b32_e32 v6, 16, v6
	v_mul_f32_e32 v5, v5, v6
	v_cvt_pk_bf16_f32 v5, v5, v157
	ds_read_u16 v6, v2 offset:2448
	ds_write_b16 v2, v5 offset:11520
	v_add_f32_e32 v5, v43, v3
	v_mul_f32_e32 v7, 0x3fb8aa3b, v5
	v_exp_f32_e32 v7, v7
	s_waitcnt lgkmcnt(1)
	v_lshlrev_b32_e32 v6, 16, v6
	v_mul_f32_e32 v6, 0x3e000000, v6
	v_mul_f32_e32 v5, 0xbfb8aa3b, v5
	v_mul_f32_e32 v6, v7, v6
	v_cvt_pk_bf16_f32 v6, v6, v157
	ds_write_b16 v2, v6 offset:2448
	ds_read_u16 v6, v2 offset:11664
	v_exp_f32_e32 v5, v5
	s_waitcnt lgkmcnt(0)
	v_lshlrev_b32_e32 v6, 16, v6
	v_mul_f32_e32 v5, v5, v6
	v_cvt_pk_bf16_f32 v5, v5, v157
	ds_read_u16 v6, v2 offset:2592
	ds_write_b16 v2, v5 offset:11664
	v_add_f32_e32 v5, v44, v3
	v_mul_f32_e32 v7, 0x3fb8aa3b, v5
	v_exp_f32_e32 v7, v7
	s_waitcnt lgkmcnt(1)
	v_lshlrev_b32_e32 v6, 16, v6
	v_mul_f32_e32 v6, 0x3e000000, v6
	v_mul_f32_e32 v5, 0xbfb8aa3b, v5
	v_mul_f32_e32 v6, v7, v6
	v_cvt_pk_bf16_f32 v6, v6, v157
	ds_write_b16 v2, v6 offset:2592
	ds_read_u16 v6, v2 offset:11808
	v_exp_f32_e32 v5, v5
	s_waitcnt lgkmcnt(0)
	v_lshlrev_b32_e32 v6, 16, v6
	v_mul_f32_e32 v5, v5, v6
	v_cvt_pk_bf16_f32 v5, v5, v157
	ds_read_u16 v6, v2 offset:2736
	ds_write_b16 v2, v5 offset:11808
	v_add_f32_e32 v5, v45, v3
	v_mul_f32_e32 v7, 0x3fb8aa3b, v5
	v_exp_f32_e32 v7, v7
	s_waitcnt lgkmcnt(1)
	v_lshlrev_b32_e32 v6, 16, v6
	v_mul_f32_e32 v6, 0x3e000000, v6
	v_mul_f32_e32 v5, 0xbfb8aa3b, v5
	v_mul_f32_e32 v6, v7, v6
	v_cvt_pk_bf16_f32 v6, v6, v157
	ds_write_b16 v2, v6 offset:2736
	ds_read_u16 v6, v2 offset:11952
	v_exp_f32_e32 v5, v5
	s_waitcnt lgkmcnt(0)
	v_lshlrev_b32_e32 v6, 16, v6
	v_mul_f32_e32 v5, v5, v6
	v_cvt_pk_bf16_f32 v5, v5, v157
	ds_read_u16 v6, v2 offset:2880
	ds_write_b16 v2, v5 offset:11952
	v_add_f32_e32 v5, v46, v3
	v_mul_f32_e32 v7, 0x3fb8aa3b, v5
	v_exp_f32_e32 v7, v7
	s_waitcnt lgkmcnt(1)
	v_lshlrev_b32_e32 v6, 16, v6
	v_mul_f32_e32 v6, 0x3e000000, v6
	v_mul_f32_e32 v5, 0xbfb8aa3b, v5
	v_mul_f32_e32 v6, v7, v6
	v_cvt_pk_bf16_f32 v6, v6, v157
	ds_write_b16 v2, v6 offset:2880
	ds_read_u16 v6, v2 offset:12096
	v_exp_f32_e32 v5, v5
	s_waitcnt lgkmcnt(0)
	v_lshlrev_b32_e32 v6, 16, v6
	v_mul_f32_e32 v5, v5, v6
	v_cvt_pk_bf16_f32 v5, v5, v157
	ds_read_u16 v6, v2 offset:3024
	ds_write_b16 v2, v5 offset:12096
	v_add_f32_e32 v5, v47, v3
	v_mul_f32_e32 v7, 0x3fb8aa3b, v5
	v_exp_f32_e32 v7, v7
	s_waitcnt lgkmcnt(1)
	v_lshlrev_b32_e32 v6, 16, v6
	v_mul_f32_e32 v6, 0x3e000000, v6
	v_mul_f32_e32 v5, 0xbfb8aa3b, v5
	v_mul_f32_e32 v6, v7, v6
	v_cvt_pk_bf16_f32 v6, v6, v157
	ds_write_b16 v2, v6 offset:3024
	ds_read_u16 v6, v2 offset:12240
	v_exp_f32_e32 v5, v5
	s_waitcnt lgkmcnt(0)
	v_lshlrev_b32_e32 v6, 16, v6
	v_mul_f32_e32 v5, v5, v6
	v_cvt_pk_bf16_f32 v5, v5, v157
	ds_read_u16 v6, v2 offset:3168
	ds_write_b16 v2, v5 offset:12240
	v_add_f32_e32 v5, v48, v3
	v_mul_f32_e32 v7, 0x3fb8aa3b, v5
	v_exp_f32_e32 v7, v7
	s_waitcnt lgkmcnt(1)
	v_lshlrev_b32_e32 v6, 16, v6
	v_mul_f32_e32 v6, 0x3e000000, v6
	v_mul_f32_e32 v5, 0xbfb8aa3b, v5
	v_mul_f32_e32 v6, v7, v6
	v_cvt_pk_bf16_f32 v6, v6, v157
	ds_write_b16 v2, v6 offset:3168
	ds_read_u16 v6, v2 offset:12384
	v_exp_f32_e32 v5, v5
	v_or_b32_e32 v48, 16, v81
	s_waitcnt lgkmcnt(0)
	v_lshlrev_b32_e32 v6, 16, v6
	v_mul_f32_e32 v5, v5, v6
	v_cvt_pk_bf16_f32 v5, v5, v157
	ds_read_u16 v6, v2 offset:3312
	ds_write_b16 v2, v5 offset:12384
	v_add_f32_e32 v5, v50, v3
	v_mul_f32_e32 v7, 0x3fb8aa3b, v5
	v_exp_f32_e32 v7, v7
	s_waitcnt lgkmcnt(1)
	v_lshlrev_b32_e32 v6, 16, v6
	v_mul_f32_e32 v6, 0x3e000000, v6
	v_mul_f32_e32 v5, 0xbfb8aa3b, v5
	v_mul_f32_e32 v6, v7, v6
	v_cvt_pk_bf16_f32 v6, v6, v157
	ds_write_b16 v2, v6 offset:3312
	ds_read_u16 v6, v2 offset:12528
	v_exp_f32_e32 v5, v5
	s_waitcnt lgkmcnt(0)
	v_lshlrev_b32_e32 v6, 16, v6
	v_mul_f32_e32 v5, v5, v6
	v_cvt_pk_bf16_f32 v5, v5, v157
	ds_read_u16 v6, v2 offset:3456
	ds_write_b16 v2, v5 offset:12528
	v_add_f32_e32 v5, v51, v3
	v_mul_f32_e32 v7, 0x3fb8aa3b, v5
	v_exp_f32_e32 v7, v7
	s_waitcnt lgkmcnt(1)
	v_lshlrev_b32_e32 v6, 16, v6
	v_mul_f32_e32 v6, 0x3e000000, v6
	v_mul_f32_e32 v5, 0xbfb8aa3b, v5
	v_mul_f32_e32 v6, v7, v6
	v_cvt_pk_bf16_f32 v6, v6, v157
	ds_write_b16 v2, v6 offset:3456
	ds_read_u16 v6, v2 offset:12672
	v_exp_f32_e32 v5, v5
	s_waitcnt lgkmcnt(0)
; #define LAS __attribute__((address_space(3)))
; #define LAS __attribute__((address_space(3)))
; DI float bf1(bf16_t v) { return __uint_as_float((unsigned)v << 16); }
; DI bf16_t f2bf(float f) { return (bf16_t)(pk(f, 0.f) & 0xffffu); }
; #define MFMA16(a, b, c) __builtin_amdgcn_mfma_f32_16x16x32_bf16((a), (b), (c), 0, 0, 0)
; template <int MODE>
; DI void gla4_unit(const bf16_t* z, float* ST, float* DEC, bf16_t* Y, const float* aw_g, const float* ab_g, const float* ng, ldsp lds, int tid, int u) {
;     ...
;         for (int i = 0; i < 32; ++i) {
;             const float bb = bc[i] + pre;
;             LAS bf16_t* qp = (LAS bf16_t*)(hr + (32 * half + i) * 144 + d * 2); LAS bf16_t* kp = (LAS bf16_t*)(hr + G4_R1 + (32 * half + i) * 144 + d * 2);
;             *qp = f2bf(bf1(*qp) * 0.125f * __expf(bb)); *kp = f2bf(bf1(*kp) * __expf(-bb));
;         }
;         __syncthreads();
;         f32x4 acc[2][4];
; #pragma unroll
;         for (int rt = 0; rt < 2; ++rt)
; #pragma unroll
;             for (int nt = 0; nt < 4; ++nt) acc[rt][nt] = (f32x4){0.f, 0.f, 0.f, 0.f};
; #pragma unroll
;         for (int ks = 0; ks < 2; ++ks) {
;             bf16x8 af[2], bfm[4];
; #pragma unroll
;             for (int rt = 0; rt < 2; ++rt) af[rt] = *(LAS bf16x8*)(hr + (32 * half + 16 * rt + fr) * 144 + (32 * ks + 8 * fq) * 2);
; #pragma unroll
;             for (int nt = 0; nt < 4; ++nt) bfm[nt] = *(LAS bf16x8*)(hr + G4_R1 + (16 * nt + fr) * 144 + (32 * ks + 8 * fq) * 2);
; #pragma unroll
;             for (int rt = 0; rt < 2; ++rt)
; #pragma unroll
;                 for (int nt = 0; nt < 4; ++nt) acc[rt][nt] = MFMA16(af[rt], bfm[nt], acc[rt][nt]);
;         }
;         unsigned vw[16];
; #pragma unroll
;         for (int k = 0; k < 16; ++k) {
;             const unsigned lo = *(LAS bf16_t*)(hr + G4_R2 + (32 * half + 2 * k) * 144 + d * 2), hi = *(LAS bf16_t*)(hr + G4_R2 + (32 * half + 2 * k + 1) * 144 + d * 2);
;             vw[k] = lo | (hi << 16);
;         }
	v_lshlrev_b32_e32 v6, 16, v6
	v_mul_f32_e32 v5, v5, v6
	v_cvt_pk_bf16_f32 v5, v5, v157
	ds_read_u16 v6, v2 offset:3600
	ds_write_b16 v2, v5 offset:12672
	v_add_f32_e32 v5, v52, v3
	v_mul_f32_e32 v7, 0x3fb8aa3b, v5
	v_exp_f32_e32 v7, v7
	s_waitcnt lgkmcnt(1)
	v_lshlrev_b32_e32 v6, 16, v6
	v_mul_f32_e32 v6, 0x3e000000, v6
	v_mul_f32_e32 v5, 0xbfb8aa3b, v5
	v_mul_f32_e32 v6, v7, v6
	v_cvt_pk_bf16_f32 v6, v6, v157
	ds_write_b16 v2, v6 offset:3600
	ds_read_u16 v6, v2 offset:12816
	v_exp_f32_e32 v5, v5
	s_waitcnt lgkmcnt(0)
	v_lshlrev_b32_e32 v6, 16, v6
	v_mul_f32_e32 v5, v5, v6
	v_cvt_pk_bf16_f32 v5, v5, v157
	ds_read_u16 v6, v2 offset:3744
	ds_write_b16 v2, v5 offset:12816
	v_add_f32_e32 v5, v53, v3
	v_mul_f32_e32 v7, 0x3fb8aa3b, v5
	v_exp_f32_e32 v7, v7
	s_waitcnt lgkmcnt(1)
	v_lshlrev_b32_e32 v6, 16, v6
	v_mul_f32_e32 v6, 0x3e000000, v6
	v_mul_f32_e32 v5, 0xbfb8aa3b, v5
	v_mul_f32_e32 v6, v7, v6
	v_cvt_pk_bf16_f32 v6, v6, v157
	ds_write_b16 v2, v6 offset:3744
	ds_read_u16 v6, v2 offset:12960
	v_exp_f32_e32 v5, v5
	s_waitcnt lgkmcnt(0)
	v_lshlrev_b32_e32 v6, 16, v6
	v_mul_f32_e32 v5, v5, v6
	v_cvt_pk_bf16_f32 v5, v5, v157
	ds_read_u16 v6, v2 offset:3888
	ds_write_b16 v2, v5 offset:12960
	v_add_f32_e32 v5, v54, v3
	v_mul_f32_e32 v7, 0x3fb8aa3b, v5
	v_exp_f32_e32 v7, v7
	s_waitcnt lgkmcnt(1)
	v_lshlrev_b32_e32 v6, 16, v6
	v_mul_f32_e32 v6, 0x3e000000, v6
	v_mul_f32_e32 v5, 0xbfb8aa3b, v5
	v_mul_f32_e32 v6, v7, v6
	v_cvt_pk_bf16_f32 v6, v6, v157
	ds_write_b16 v2, v6 offset:3888
	ds_read_u16 v6, v2 offset:13104
	v_exp_f32_e32 v5, v5
	v_or_b32_e32 v54, 32, v81
	s_waitcnt lgkmcnt(0)
	v_lshlrev_b32_e32 v6, 16, v6
	v_mul_f32_e32 v5, v5, v6
	v_cvt_pk_bf16_f32 v5, v5, v157
	ds_read_u16 v6, v2 offset:4032
	ds_write_b16 v2, v5 offset:13104
	v_add_f32_e32 v5, v55, v3
	v_mul_f32_e32 v7, 0x3fb8aa3b, v5
	v_exp_f32_e32 v7, v7
	s_waitcnt lgkmcnt(1)
	v_lshlrev_b32_e32 v6, 16, v6
	v_mul_f32_e32 v6, 0x3e000000, v6
	v_mul_f32_e32 v5, 0xbfb8aa3b, v5
	v_mul_f32_e32 v6, v7, v6
	v_cvt_pk_bf16_f32 v6, v6, v157
	ds_write_b16 v2, v6 offset:4032
	ds_read_u16 v6, v2 offset:13248
	v_exp_f32_e32 v5, v5
	v_or_b32_e32 v55, 48, v81
	s_waitcnt lgkmcnt(0)
	v_lshlrev_b32_e32 v6, 16, v6
	v_mul_f32_e32 v5, v5, v6
	v_cvt_pk_bf16_f32 v5, v5, v157
	ds_read_u16 v6, v2 offset:4176
	ds_write_b16 v2, v5 offset:13248
	v_add_f32_e32 v5, v57, v3
	v_mul_f32_e32 v7, 0x3fb8aa3b, v5
	v_exp_f32_e32 v7, v7
	s_waitcnt lgkmcnt(1)
	v_lshlrev_b32_e32 v6, 16, v6
	v_mul_f32_e32 v6, 0x3e000000, v6
	v_mul_f32_e32 v5, 0xbfb8aa3b, v5
	v_mul_f32_e32 v6, v7, v6
	v_cvt_pk_bf16_f32 v6, v6, v157
	ds_write_b16 v2, v6 offset:4176
	ds_read_u16 v6, v2 offset:13392
	v_exp_f32_e32 v5, v5
	s_waitcnt lgkmcnt(0)
	v_lshlrev_b32_e32 v6, 16, v6
	v_mul_f32_e32 v5, v5, v6
	v_cvt_pk_bf16_f32 v5, v5, v157
	ds_read_u16 v6, v2 offset:4320
	ds_write_b16 v2, v5 offset:13392
	v_add_f32_e32 v5, v58, v3
	v_mul_f32_e32 v7, 0x3fb8aa3b, v5
	v_exp_f32_e32 v7, v7
	s_waitcnt lgkmcnt(1)
	v_lshlrev_b32_e32 v6, 16, v6
	v_mul_f32_e32 v6, 0x3e000000, v6
	v_mul_f32_e32 v5, 0xbfb8aa3b, v5
	v_mul_f32_e32 v6, v7, v6
	v_cvt_pk_bf16_f32 v6, v6, v157
	ds_write_b16 v2, v6 offset:4320
	ds_read_u16 v6, v2 offset:13536
	v_exp_f32_e32 v5, v5
	v_add_f32_e32 v3, v3, v4
	s_waitcnt lgkmcnt(0)
	v_lshlrev_b32_e32 v6, 16, v6
	v_mul_f32_e32 v5, v5, v6
	v_cvt_pk_bf16_f32 v5, v5, v157
	ds_read_u16 v4, v2 offset:4464
	ds_write_b16 v2, v5 offset:13536
	v_mul_f32_e32 v5, 0x3fb8aa3b, v3
	v_exp_f32_e32 v5, v5
	v_mul_f32_e32 v3, 0xbfb8aa3b, v3
	s_waitcnt lgkmcnt(1)
	v_lshlrev_b32_e32 v4, 16, v4
	v_mul_f32_e32 v4, 0x3e000000, v4
	v_mul_f32_e32 v4, v5, v4
	v_cvt_pk_bf16_f32 v4, v4, v157
	ds_write_b16 v2, v4 offset:4464
	ds_read_u16 v4, v2 offset:13680
	v_exp_f32_e32 v3, v3
	s_waitcnt lgkmcnt(0)
	v_lshlrev_b32_e32 v4, 16, v4
	v_mul_f32_e32 v3, v3, v4
	v_cvt_pk_bf16_f32 v3, v3, v157
	ds_write_b16 v2, v3 offset:13680
	v_and_b32_e32 v2, 48, v80
	v_add_u32_e32 v39, v49, v2
	v_mad_u32_u24 v31, v38, s89, v39
	v_mad_u32_u24 v40, v81, s89, v39
	v_add_u32_e32 v41, v39, v35
	v_add_u32_e32 v42, v39, v36
	v_add_u32_e32 v43, v39, v37
	s_waitcnt lgkmcnt(0)
	s_barrier
	ds_read_b128 v[2:5], v31
	ds_read_b128 v[6:9], v31 offset:2304
	ds_read_b128 v[10:13], v40 offset:9216
	ds_read_b128 v[14:17], v41 offset:9216
	ds_read_b128 v[18:21], v42 offset:9216
	ds_read_b128 v[22:25], v43 offset:9216
	s_waitcnt lgkmcnt(3)
	v_mfma_f32_16x16x32_bf16 v[44:47], v[2:5], v[10:13], 0
	s_waitcnt lgkmcnt(2)
	v_mfma_f32_16x16x32_bf16 v[50:53], v[2:5], v[14:17], 0
	s_waitcnt lgkmcnt(1)
	v_mfma_f32_16x16x32_bf16 v[2:5], v[2:5], v[18:21], 0
	v_mfma_f32_16x16x32_bf16 v[10:13], v[6:9], v[10:13], 0
	v_mfma_f32_16x16x32_bf16 v[14:17], v[6:9], v[14:17], 0
	v_mfma_f32_16x16x32_bf16 v[58:61], v[6:9], v[18:21], 0
	s_waitcnt lgkmcnt(0)
	v_mfma_f32_16x16x32_bf16 v[24:27], v[6:9], v[22:25], 0
	ds_read_b128 v[6:9], v31 offset:64
	ds_read_b128 v[62:65], v31 offset:2368
	ds_read_b128 v[18:21], v40 offset:9280
	ds_read_b128 v[66:69], v41 offset:9280
	ds_read_b128 v[70:73], v42 offset:9280
	ds_read_b128 v[74:77], v43 offset:9280
	ds_read_u16 v0, v30 offset:18432
	ds_read_u16 v1, v30 offset:18576
	s_waitcnt lgkmcnt(0)
	v_lshl_or_b32 v0, v1, 16, v0
	v_mfma_f32_16x16x32_bf16 v[82:85], v[6:9], v[70:73], v[2:5]
	ds_read_u16 v1, v30 offset:18720
	s_nop 1
	ds_read_u16 v2, v30 offset:18864
	s_waitcnt lgkmcnt(0)
	v_lshl_or_b32 v1, v2, 16, v1
	ds_read_u16 v2, v30 offset:19008
	ds_read_u16 v3, v30 offset:19152
	v_mfma_f32_16x16x32_bf16 v[44:47], v[6:9], v[18:21], v[44:47]
	s_waitcnt lgkmcnt(0)
	v_lshl_or_b32 v2, v3, 16, v2
	v_mfma_f32_16x16x32_bf16 v[20:23], v[62:65], v[18:21], v[10:13]
	v_mfma_f32_16x16x32_bf16 v[12:15], v[62:65], v[66:69], v[14:17]
	ds_read_u16 v3, v30 offset:19296
	s_nop 1
	ds_read_u16 v16, v30 offset:19440
	s_waitcnt lgkmcnt(0)
; #define LAS __attribute__((address_space(3)))
; #define LAS __attribute__((address_space(3)))
; DI bf16_t f2bf(float f) { return (bf16_t)(pk(f, 0.f) & 0xffffu); }
; template <int MODE>
; DI void gla4_unit(const bf16_t* z, float* ST, float* DEC, bf16_t* Y, const float* aw_g, const float* ab_g, const float* ng, ldsp lds, int tid, int u) {
;     ...
;         for (int k = 0; k < 16; ++k) {
;             const unsigned lo = *(LAS bf16_t*)(hr + G4_R2 + (32 * half + 2 * k) * 144 + d * 2), hi = *(LAS bf16_t*)(hr + G4_R2 + (32 * half + 2 * k + 1) * 144 + d * 2);
;             vw[k] = lo | (hi << 16);
;         }
;         __syncthreads();
; #pragma unroll
;         for (int rt = 0; rt < 2; ++rt)
; #pragma unroll
;             for (int nt = 0; nt < 4; ++nt)
; #pragma unroll
;                 for (int r = 0; r < 4; ++r) {
;                     const int t = 32 * half + 16 * rt + 4 * fq + r, sx = 16 * nt + fr;
;                     *(LAS bf16_t*)(hr + G4_R1 + t * 144 + sx * 2) = f2bf(sx <= t ? acc[rt][nt][r] : 0.f);
;                 }
	v_lshl_or_b32 v3, v16, 16, v3
	ds_read_u16 v16, v30 offset:19584
	ds_read_u16 v17, v30 offset:19728
	v_mfma_f32_16x16x32_bf16 v[50:53], v[6:9], v[66:69], v[50:53]
	s_waitcnt lgkmcnt(0)
	v_lshl_or_b32 v16, v17, 16, v16
	ds_read_u16 v17, v30 offset:19872
	ds_read_u16 v18, v30 offset:20016
	v_mfma_f32_16x16x32_bf16 v[4:7], v[62:65], v[74:77], v[24:27]
	s_waitcnt lgkmcnt(0)
	v_lshl_or_b32 v17, v18, 16, v17
	ds_read_u16 v18, v30 offset:20160
	ds_read_u16 v19, v30 offset:20304
	v_mfma_f32_16x16x32_bf16 v[8:11], v[62:65], v[70:73], v[58:61]
	s_waitcnt lgkmcnt(0)
	v_lshl_or_b32 v18, v19, 16, v18
	ds_read_u16 v19, v30 offset:20448
	ds_read_u16 v24, v30 offset:20592
	s_waitcnt lgkmcnt(0)
	v_lshl_or_b32 v19, v24, 16, v19
	ds_read_u16 v24, v30 offset:20736
	ds_read_u16 v25, v30 offset:20880
	s_waitcnt lgkmcnt(0)
	v_lshl_or_b32 v24, v25, 16, v24
	ds_read_u16 v25, v30 offset:21024
	ds_read_u16 v26, v30 offset:21168
	s_waitcnt lgkmcnt(0)
	v_lshl_or_b32 v25, v26, 16, v25
	ds_read_u16 v26, v30 offset:21312
	ds_read_u16 v27, v30 offset:21456
	s_waitcnt lgkmcnt(0)
	v_lshl_or_b32 v26, v27, 16, v26
	ds_read_u16 v27, v30 offset:21600
	ds_read_u16 v57, v30 offset:21744
	s_waitcnt lgkmcnt(0)
	v_lshl_or_b32 v27, v57, 16, v27
	ds_read_u16 v57, v30 offset:21888
	ds_read_u16 v58, v30 offset:22032
	s_waitcnt lgkmcnt(0)
	v_lshl_or_b32 v58, v58, 16, v57
	ds_read_u16 v57, v30 offset:22176
	ds_read_u16 v59, v30 offset:22320
	s_waitcnt lgkmcnt(0)
	v_lshl_or_b32 v59, v59, 16, v57
	ds_read_u16 v57, v30 offset:22464
	ds_read_u16 v60, v30 offset:22608
	s_waitcnt lgkmcnt(0)
	v_lshl_or_b32 v60, v60, 16, v57
	ds_read_u16 v57, v30 offset:22752
	ds_read_u16 v30, v30 offset:22896
	s_waitcnt lgkmcnt(0)
	s_barrier
	v_lshl_or_b32 v61, v30, 16, v57
	v_lshl_or_b32 v30, v177, 2, v56
	v_cmp_gt_u32_e32 vcc, v81, v30
	v_lshl_add_u32 v56, v81, 1, v49
	v_mad_u32_u24 v57, v30, s89, v56
	v_cndmask_b32_e64 v44, v44, 0, vcc
	v_cvt_pk_bf16_f32 v44, v44, v157
	ds_write_b16 v57, v44 offset:9216
	v_or_b32_e32 v44, 1, v30
	v_cmp_le_u32_e64 s[0:1], v81, v44
	v_mad_u32_u24 v57, v30, s89, s89
	v_add_u32_e32 v62, v56, v57
	v_cndmask_b32_e64 v45, 0, v45, s[0:1]
	v_cvt_pk_bf16_f32 v45, v45, v157
	ds_write_b16 v62, v45 offset:9216
	v_or_b32_e32 v45, 2, v30
	v_cmp_le_u32_e64 s[0:1], v81, v45
	v_mad_u32_u24 v62, v30, s89, v206
	v_add_u32_e32 v63, v56, v62
	v_cndmask_b32_e64 v46, 0, v46, s[0:1]
	v_cvt_pk_bf16_f32 v46, v46, v157
	ds_write_b16 v63, v46 offset:9216
	v_or_b32_e32 v46, 3, v30
	v_cmp_le_u32_e64 s[0:1], v81, v46
	v_mad_u32_u24 v63, v30, s89, v207
	v_add_u32_e32 v64, v56, v63
	v_cndmask_b32_e64 v47, 0, v47, s[0:1]
	v_cvt_pk_bf16_f32 v47, v47, v157
	v_cmp_le_u32_e64 s[0:1], v48, v30
	ds_write_b16 v64, v47 offset:9216
	v_lshl_add_u32 v47, v48, 1, v49
	v_cndmask_b32_e64 v50, 0, v50, s[0:1]
	v_cvt_pk_bf16_f32 v50, v50, v157
	v_mad_u32_u24 v64, v30, s89, v47
	v_cmp_le_u32_e64 s[0:1], v48, v44
	ds_write_b16 v64, v50 offset:9216
	v_cndmask_b32_e64 v12, v12, 0, vcc
	v_cndmask_b32_e64 v50, 0, v51, s[0:1]
	v_cvt_pk_bf16_f32 v50, v50, v157
	v_add_u32_e32 v51, v47, v57
	v_cmp_le_u32_e64 s[0:1], v48, v45
	ds_write_b16 v51, v50 offset:9216
	v_add_u32_e32 v51, v47, v62
	v_cndmask_b32_e64 v50, 0, v52, s[0:1]
	v_cvt_pk_bf16_f32 v50, v50, v157
	v_cmp_le_u32_e64 s[0:1], v48, v46
	ds_write_b16 v51, v50 offset:9216
	v_add_u32_e32 v51, v47, v63
	v_cndmask_b32_e64 v50, 0, v53, s[0:1]
	v_cvt_pk_bf16_f32 v50, v50, v157
	v_cmp_le_u32_e64 s[0:1], v54, v30
	ds_write_b16 v51, v50 offset:9216
	v_lshl_add_u32 v50, v54, 1, v49
	v_cndmask_b32_e64 v51, 0, v82, s[0:1]
	v_cmp_le_u32_e64 s[0:1], v54, v44
	v_cvt_pk_bf16_f32 v51, v51, v157
	v_mad_u32_u24 v52, v30, s89, v50
	ds_write_b16 v52, v51 offset:9216
	v_cndmask_b32_e64 v44, 0, v83, s[0:1]
	v_cvt_pk_bf16_f32 v44, v44, v157
	v_add_u32_e32 v51, v50, v57
	v_cmp_le_u32_e64 s[0:1], v54, v45
	ds_write_b16 v51, v44 offset:9216
	v_add_u32_e32 v45, v50, v62
	v_cndmask_b32_e64 v44, 0, v84, s[0:1]
	v_cvt_pk_bf16_f32 v44, v44, v157
	v_cmp_le_u32_e64 s[0:1], v54, v46
	ds_write_b16 v45, v44 offset:9216
	v_add_u32_e32 v45, v50, v63
	v_cndmask_b32_e64 v44, 0, v85, s[0:1]
	v_cvt_pk_bf16_f32 v44, v44, v157
	ds_write_b16 v45, v44 offset:9216
	v_lshl_add_u32 v44, v55, 1, v49
	v_mad_u32_u24 v46, v30, s89, v44
	v_cvt_pk_bf16_f32 v45, v157, v157
	ds_write_b16 v46, v45 offset:9216
	v_add_u32_e32 v46, v44, v57
	v_cvt_pk_bf16_f32 v45, v157, v157
	ds_write_b16 v46, v45 offset:9216
	v_add_u32_e32 v46, v44, v62
	v_cvt_pk_bf16_f32 v45, v157, v157
	ds_write_b16 v46, v45 offset:9216
	v_add_u32_e32 v46, v44, v63
	v_cvt_pk_bf16_f32 v45, v157, v157
	ds_write_b16 v46, v45 offset:9216
	v_mad_u32_u24 v46, v30, s89, v202
	v_add_u32_e32 v51, v56, v46
	v_cvt_pk_bf16_f32 v20, v20, v157
	ds_write_b16 v51, v20 offset:9216
	v_mad_u32_u24 v51, v30, s89, v208
	v_add_u32_e32 v52, v56, v51
	v_cvt_pk_bf16_f32 v21, v21, v157
	ds_write_b16 v52, v21 offset:9216
	v_mad_u32_u24 v52, v30, s89, v209
	v_add_u32_e32 v53, v56, v52
	v_cvt_pk_bf16_f32 v22, v22, v157
	ds_write_b16 v53, v22 offset:9216
	v_mad_u32_u24 v53, v30, s89, v210
	v_or_b32_e32 v20, 17, v30
	v_cvt_pk_bf16_f32 v23, v23, v157
	v_add_u32_e32 v56, v56, v53
	ds_write_b16 v56, v23 offset:9216
	v_cvt_pk_bf16_f32 v12, v12, v157
	v_add_u32_e32 v23, v47, v46
	v_cmp_le_u32_e32 vcc, v48, v20
	v_or_b32_e32 v21, 18, v30
	ds_write_b16 v23, v12 offset:9216
	v_cndmask_b32_e32 v12, 0, v13, vcc
	v_cvt_pk_bf16_f32 v12, v12, v157
	v_add_u32_e32 v13, v47, v51
	v_cmp_le_u32_e32 vcc, v48, v21
	v_or_b32_e32 v22, 19, v30
	ds_write_b16 v13, v12 offset:9216
	v_cndmask_b32_e32 v12, 0, v14, vcc
	v_or_b32_e32 v45, 16, v30
	v_cvt_pk_bf16_f32 v12, v12, v157
	v_add_u32_e32 v13, v47, v52
; #define LAS __attribute__((address_space(3)))
; #define LAS __attribute__((address_space(3)))
; DI unsigned pk(float lo, float hi) { return pg8::cvt_pk_bf16(lo, hi); }
; DI bf16_t f2bf(float f) { return (bf16_t)(pk(f, 0.f) & 0xffffu); }
; template <int MODE>
; DI void gla4_unit(const bf16_t* z, float* ST, float* DEC, bf16_t* Y, const float* aw_g, const float* ab_g, const float* ng, ldsp lds, int tid, int u) {
;     ...
;         __syncthreads();
; #pragma unroll
;         for (int rt = 0; rt < 2; ++rt)
; #pragma unroll
;             for (int nt = 0; nt < 4; ++nt)
; #pragma unroll
;                 for (int r = 0; r < 4; ++r) {
;                     const int t = 32 * half + 16 * rt + 4 * fq + r, sx = 16 * nt + fr;
;                     *(LAS bf16_t*)(hr + G4_R1 + t * 144 + sx * 2) = f2bf(sx <= t ? acc[rt][nt][r] : 0.f);
;                 }
; #pragma unroll
;         for (int j = 0; j < 4; ++j) { u32x4 o; o.x = vw[4 * j]; o.y = vw[4 * j + 1]; o.z = vw[4 * j + 2]; o.w = vw[4 * j + 3]; *(LAS u32x4*)(hr + G4_R2 + d * 144 + (32 * half + 8 * j) * 2) = o; }
;         __syncthreads();
; #pragma unroll
;         for (int rt = 0; rt < 2; ++rt)
; #pragma unroll
;             for (int nt = 0; nt < 4; ++nt) acc[rt][nt] = (f32x4){0.f, 0.f, 0.f, 0.f};
;         const float* sp = ST + (size_t)(p * 128 + c) * 4096;
; #pragma unroll
;         for (int ks = 0; ks < 4; ++ks) {
;             bf16x8 af[2], bfm[4];
;             const int kk = (ks & 1) * 32 + 8 * fq;
; #pragma unroll
;             for (int rt = 0; rt < 2; ++rt) af[rt] = *(LAS bf16x8*)(hr + (ks < 2 ? G4_R1 : 0) + (32 * half + 16 * rt + fr) * 144 + kk * 2);
; #pragma unroll
;             for (int nt = 0; nt < 4; ++nt) {
;                 if (ks < 2) bfm[nt] = *(LAS bf16x8*)(hr + G4_R2 + (16 * nt + fr) * 144 + kk * 2);
;                 else { const f32x4 s0 = *(const f32x4*)(sp + (16 * nt + fr) * 64 + kk), s1 = *(const f32x4*)(sp + (16 * nt + fr) * 64 + kk + 4);
;                        u32x4 o; o.x = pk(s0[0], s0[1]); o.y = pk(s0[2], s0[3]); o.z = pk(s1[0], s1[1]); o.w = pk(s1[2], s1[3]); bfm[nt] = __builtin_bit_cast(bf16x8, o); }
;             }
; #pragma unroll
;             for (int rt = 0; rt < 2; ++rt)
; #pragma unroll
;                 for (int nt = 0; nt < 4; ++nt) acc[rt][nt] = MFMA16(af[rt], bfm[nt], acc[rt][nt]);
;         }
	v_cmp_le_u32_e32 vcc, v48, v22
	ds_write_b16 v13, v12 offset:9216
	v_add_u32_e32 v13, v47, v53
	v_cndmask_b32_e32 v12, 0, v15, vcc
	v_cmp_le_u32_e32 vcc, v54, v45
	v_cvt_pk_bf16_f32 v12, v12, v157
	ds_write_b16 v13, v12 offset:9216
	v_add_u32_e32 v12, v50, v46
	v_cndmask_b32_e32 v8, 0, v8, vcc
	v_cvt_pk_bf16_f32 v8, v8, v157
	v_cmp_le_u32_e32 vcc, v54, v20
	ds_write_b16 v12, v8 offset:9216
	s_and_b32 s0, s30, 0x7f
	v_cndmask_b32_e32 v8, 0, v9, vcc
	v_cvt_pk_bf16_f32 v8, v8, v157
	v_add_u32_e32 v9, v50, v51
	v_cmp_le_u32_e32 vcc, v54, v21
	ds_write_b16 v9, v8 offset:9216
	v_add_u32_e32 v9, v50, v52
	v_cndmask_b32_e32 v8, 0, v10, vcc
	v_cvt_pk_bf16_f32 v8, v8, v157
	v_cmp_le_u32_e32 vcc, v54, v22
	ds_write_b16 v9, v8 offset:9216
	v_add_u32_e32 v9, v50, v53
	v_cndmask_b32_e32 v8, 0, v11, vcc
	v_cmp_le_u32_e32 vcc, v55, v45
	v_cvt_pk_bf16_f32 v8, v8, v157
	ds_write_b16 v9, v8 offset:9216
	v_add_u32_e32 v8, v44, v46
	v_cndmask_b32_e32 v4, 0, v4, vcc
	v_cvt_pk_bf16_f32 v4, v4, v157
	v_cmp_le_u32_e32 vcc, v55, v20
	ds_write_b16 v8, v4 offset:9216
	s_nop 0
	v_cndmask_b32_e32 v4, 0, v5, vcc
	v_cvt_pk_bf16_f32 v4, v4, v157
	v_add_u32_e32 v5, v44, v51
	v_cmp_le_u32_e32 vcc, v55, v21
	ds_write_b16 v5, v4 offset:9216
	v_add_u32_e32 v5, v44, v52
	v_cndmask_b32_e32 v4, 0, v6, vcc
	v_cvt_pk_bf16_f32 v4, v4, v157
	v_cmp_le_u32_e32 vcc, v55, v22
	ds_write_b16 v5, v4 offset:9216
	v_add_u32_e32 v5, v44, v53
	v_cndmask_b32_e32 v4, 0, v7, vcc
	v_cvt_pk_bf16_f32 v4, v4, v157
	ds_write_b16 v5, v4 offset:9216
	v_mul_u32_u24_e32 v4, 0x90, v178
	v_lshlrev_b32_e32 v5, 6, v29
	v_add3_u32 v4, v49, v4, v5
	ds_write_b128 v4, v[0:3] offset:18432
	ds_write_b128 v4, v[16:19] offset:18448
	ds_write_b128 v4, v[24:27] offset:18464
	ds_write_b128 v4, v[58:61] offset:18480
	v_lshl_or_b32 v0, v28, 7, s0
	v_ashrrev_i32_e32 v1, 31, v0
	v_lshlrev_b64 v[0:1], 14, v[0:1]
	v_lshl_add_u64 v[8:9], s[68:69], 0, v[0:1]
	s_waitcnt lgkmcnt(0)
	s_barrier
	ds_read_b128 v[0:3], v31 offset:9216
	ds_read_b128 v[4:7], v31 offset:11520
	v_lshl_add_u64 v[74:75], v[8:9], 0, v[156:157]
	ds_read_b128 v[8:11], v40 offset:18432
	ds_read_b128 v[12:15], v41 offset:18432
	ds_read_b128 v[16:19], v42 offset:18432
	ds_read_b128 v[20:23], v43 offset:18432
	v_add_u32_e32 v28, 64, v39
	s_waitcnt lgkmcnt(3)
	v_mfma_f32_16x16x32_bf16 v[24:27], v[0:3], v[8:11], 0
	v_mad_u32_u24 v48, v38, s89, v28
	ds_read_b128 v[54:57], v48 offset:9216
	ds_read_b128 v[58:61], v48 offset:11520
	v_lshlrev_b32_e32 v156, 8, v81
	s_waitcnt lgkmcnt(4)
	v_mfma_f32_16x16x32_bf16 v[40:43], v[0:3], v[12:15], 0
	s_mov_b64 s[0:1], 0x1000
	s_waitcnt lgkmcnt(3)
	v_mfma_f32_16x16x32_bf16 v[44:47], v[0:3], v[16:19], 0
	s_waitcnt lgkmcnt(2)
	v_mfma_f32_16x16x32_bf16 v[50:53], v[0:3], v[20:23], 0
	v_mad_u32_u24 v0, v81, s89, v28
	ds_read_b128 v[62:65], v0 offset:18432
	v_add_u32_e32 v0, v28, v35
	ds_read_b128 v[66:69], v0 offset:18432
	v_add_u32_e32 v0, v28, v36
	v_add_u32_e32 v28, v28, v37
	v_mfma_f32_16x16x32_bf16 v[8:11], v[4:7], v[8:11], 0
	v_bfe_u32 v35, v80, 1, 6
	v_mfma_f32_16x16x32_bf16 v[12:15], v[4:7], v[12:15], 0
	v_mfma_f32_16x16x32_bf16 v[16:19], v[4:7], v[16:19], 0
	v_mfma_f32_16x16x32_bf16 v[20:23], v[4:7], v[20:23], 0
	ds_read_b128 v[70:73], v0 offset:18432
	ds_read_b128 v[4:7], v31
	ds_read_b128 v[0:3], v31 offset:2304
	ds_read_b128 v[36:39], v28 offset:18432
	s_waitcnt lgkmcnt(0)
	v_mfma_f32_16x16x32_bf16 v[50:53], v[54:57], v[36:39], v[50:53]
	v_mfma_f32_16x16x32_bf16 v[36:39], v[58:61], v[36:39], v[20:23]
	s_nop 2
	v_lshl_add_u64 v[20:21], v[74:75], 0, v[156:157]
	v_mfma_f32_16x16x32_bf16 v[26:29], v[54:57], v[62:65], v[24:27]
	v_or_b32_e32 v156, s29, v35
	v_mfma_f32_16x16x32_bf16 v[40:43], v[54:57], v[66:69], v[40:43]
	v_mfma_f32_16x16x32_bf16 v[44:47], v[54:57], v[70:73], v[44:47]
	global_load_dwordx4 v[22:25], v[20:21], off offset:16
	global_load_dwordx4 v[54:57], v[20:21], off
	s_waitcnt vmcnt(0)
	v_cvt_pk_bf16_f32 v54, v54, v55
	v_cvt_pk_bf16_f32 v55, v56, v57
	v_cvt_pk_bf16_f32 v56, v22, v23
	v_cvt_pk_bf16_f32 v57, v24, v25
	v_add_co_u32_e32 v24, vcc, s33, v20
	v_mfma_f32_16x16x32_bf16 v[8:11], v[58:61], v[62:65], v[8:11]
	s_nop 0
	v_addc_co_u32_e32 v25, vcc, 0, v21, vcc
	v_add_co_u32_e32 v22, vcc, s88, v20
	v_lshl_add_u64 v[62:63], v[20:21], 0, s[0:1]
	s_nop 0
	v_addc_co_u32_e32 v23, vcc, 0, v21, vcc
	v_mfma_f32_16x16x32_bf16 v[12:15], v[58:61], v[66:69], v[12:15]
	v_lshl_add_u64 v[66:67], v[20:21], 0, s[22:23]
	s_mov_b64 s[0:1], 0x3000
	v_add_co_u32_e32 v74, vcc, s99, v20
	v_mfma_f32_16x16x32_bf16 v[16:19], v[58:61], v[70:73], v[16:19]
	global_load_dwordx4 v[58:61], v[22:23], off offset:-4096
	s_nop 0
	global_load_dwordx4 v[62:65], v[62:63], off offset:16
	s_waitcnt vmcnt(1)
	v_cvt_pk_bf16_f32 v58, v58, v59
	v_cvt_pk_bf16_f32 v59, v60, v61
	s_waitcnt vmcnt(0)
	v_cvt_pk_bf16_f32 v60, v62, v63
	v_cvt_pk_bf16_f32 v61, v64, v65
	global_load_dwordx4 v[62:65], v[22:23], off
	s_nop 0
	global_load_dwordx4 v[66:69], v[66:67], off offset:16
	v_lshl_add_u64 v[70:71], v[20:21], 0, s[0:1]
	v_addc_co_u32_e32 v75, vcc, 0, v21, vcc
	s_waitcnt vmcnt(1)
	v_cvt_pk_bf16_f32 v62, v62, v63
	v_cvt_pk_bf16_f32 v63, v64, v65
	s_waitcnt vmcnt(0)
	v_cvt_pk_bf16_f32 v64, v66, v67
	v_cvt_pk_bf16_f32 v65, v68, v69
	global_load_dwordx4 v[66:69], v[74:75], off
	s_nop 0
	global_load_dwordx4 v[70:73], v[70:71], off offset:16
	s_waitcnt vmcnt(1)
	v_cvt_pk_bf16_f32 v66, v66, v67
	v_cvt_pk_bf16_f32 v67, v68, v69
	s_waitcnt vmcnt(0)
; #define LAS __attribute__((address_space(3)))
; #define LAS __attribute__((address_space(3)))
; DI unsigned pk(float lo, float hi) { return pg8::cvt_pk_bf16(lo, hi); }
; #define MFMA16(a, b, c) __builtin_amdgcn_mfma_f32_16x16x32_bf16((a), (b), (c), 0, 0, 0)
; template <int MODE>
; DI void gla4_unit(const bf16_t* z, float* ST, float* DEC, bf16_t* Y, const float* aw_g, const float* ab_g, const float* ng, ldsp lds, int tid, int u) {
;     ...
;         for (int ks = 0; ks < 4; ++ks) {
;             bf16x8 af[2], bfm[4];
;             const int kk = (ks & 1) * 32 + 8 * fq;
; #pragma unroll
;             for (int rt = 0; rt < 2; ++rt) af[rt] = *(LAS bf16x8*)(hr + (ks < 2 ? G4_R1 : 0) + (32 * half + 16 * rt + fr) * 144 + kk * 2);
; #pragma unroll
;             for (int nt = 0; nt < 4; ++nt) {
;                 if (ks < 2) bfm[nt] = *(LAS bf16x8*)(hr + G4_R2 + (16 * nt + fr) * 144 + kk * 2);
;                 else { const f32x4 s0 = *(const f32x4*)(sp + (16 * nt + fr) * 64 + kk), s1 = *(const f32x4*)(sp + (16 * nt + fr) * 64 + kk + 4);
;                        u32x4 o; o.x = pk(s0[0], s0[1]); o.y = pk(s0[2], s0[3]); o.z = pk(s1[0], s1[1]); o.w = pk(s1[2], s1[3]); bfm[nt] = __builtin_bit_cast(bf16x8, o); }
;             }
; #pragma unroll
;             for (int rt = 0; rt < 2; ++rt)
; #pragma unroll
;                 for (int nt = 0; nt < 4; ++nt) acc[rt][nt] = MFMA16(af[rt], bfm[nt], acc[rt][nt]);
;         }
;         __syncthreads();
; #pragma unroll
;         for (int rt = 0; rt < 2; ++rt)
; #pragma unroll
;             for (int nt = 0; nt < 4; ++nt)
; #pragma unroll
;                 for (int r = 0; r < 4; ++r) *(LAS float*)(hr + (32 * half + 16 * rt + 4 * fq + r) * 272 + (16 * nt + fr) * 4) = acc[rt][nt][r];
;         __syncthreads();
;         {
;             const int t7 = tid & 127, t = t7 >> 1, e0 = (t7 & 1) * 32;
;             f32x4 o[8]; float ss = 0.f;
; #pragma unroll
;             for (int k = 0; k < 8; ++k) { o[k] = *(LAS f32x4*)(hr + t * 272 + (e0 + 4 * k) * 4); ss += (o[k][0] * o[k][0] + o[k][1] * o[k][1]) + (o[k][2] * o[k][2] + o[k][3] * o[k][3]); }
	v_cvt_pk_bf16_f32 v68, v70, v71
	v_cvt_pk_bf16_f32 v69, v72, v73
	v_mfma_f32_16x16x32_bf16 v[26:29], v[4:7], v[54:57], v[26:29]
	s_mov_b64 s[0:1], 0x1080
	v_mfma_f32_16x16x32_bf16 v[40:43], v[4:7], v[58:61], v[40:43]
	v_mfma_f32_16x16x32_bf16 v[44:47], v[4:7], v[62:65], v[44:47]
	v_mfma_f32_16x16x32_bf16 v[4:7], v[4:7], v[66:69], v[50:53]
	v_mfma_f32_16x16x32_bf16 v[8:11], v[0:3], v[54:57], v[8:11]
	v_mfma_f32_16x16x32_bf16 v[12:15], v[0:3], v[58:61], v[12:15]
	v_mfma_f32_16x16x32_bf16 v[16:19], v[0:3], v[62:65], v[16:19]
	v_lshl_add_u64 v[62:63], v[20:21], 0, s[0:1]
	s_mov_b64 s[0:1], 0x2080
	v_mfma_f32_16x16x32_bf16 v[0:3], v[0:3], v[66:69], v[36:39]
	s_nop 2
	ds_read_b128 v[36:39], v48
	ds_read_b128 v[50:53], v48 offset:2304
	global_load_dwordx4 v[54:57], v[20:21], off offset:144
	global_load_dwordx4 v[58:61], v[20:21], off offset:128
	s_waitcnt vmcnt(0)
	v_cvt_pk_bf16_f32 v58, v58, v59
	v_cvt_pk_bf16_f32 v59, v60, v61
	v_cvt_pk_bf16_f32 v60, v54, v55
	v_cvt_pk_bf16_f32 v61, v56, v57
	global_load_dwordx4 v[54:57], v[24:25], off offset:128
	s_nop 0
	global_load_dwordx4 v[62:65], v[62:63], off offset:16
	s_waitcnt vmcnt(1)
	v_cvt_pk_bf16_f32 v54, v54, v55
	v_cvt_pk_bf16_f32 v55, v56, v57
	s_waitcnt vmcnt(0)
	v_cvt_pk_bf16_f32 v56, v62, v63
	v_lshl_add_u64 v[62:63], v[20:21], 0, s[0:1]
	v_cvt_pk_bf16_f32 v57, v64, v65
	global_load_dwordx4 v[22:25], v[22:23], off offset:128
	s_nop 0
	global_load_dwordx4 v[62:65], v[62:63], off offset:16
	s_mov_b64 s[0:1], 0x3080
	s_waitcnt vmcnt(1)
	v_cvt_pk_bf16_f32 v22, v22, v23
	v_cvt_pk_bf16_f32 v23, v24, v25
	s_waitcnt vmcnt(0)
	v_cvt_pk_bf16_f32 v24, v62, v63
	v_cvt_pk_bf16_f32 v25, v64, v65
	v_lshl_add_u64 v[20:21], v[20:21], 0, s[0:1]
	global_load_dwordx4 v[62:65], v[74:75], off offset:128
	global_load_dwordx4 v[66:69], v[20:21], off offset:16
	s_waitcnt lgkmcnt(1)
	v_mfma_f32_16x16x32_bf16 v[26:29], v[36:39], v[58:61], v[26:29]
	s_waitcnt vmcnt(1)
	v_cvt_pk_bf16_f32 v62, v62, v63
	v_mfma_f32_16x16x32_bf16 v[40:43], v[36:39], v[54:57], v[40:43]
	v_cvt_pk_bf16_f32 v63, v64, v65
	s_waitcnt vmcnt(0)
	v_cvt_pk_bf16_f32 v64, v66, v67
	v_cvt_pk_bf16_f32 v65, v68, v69
	s_waitcnt lgkmcnt(0)
	v_mfma_f32_16x16x32_bf16 v[8:11], v[50:53], v[58:61], v[8:11]
	v_lshlrev_b32_e32 v20, 2, v81
	v_mul_u32_u24_e32 v21, 0x110, v30
	v_add3_u32 v20, v49, v20, v21
	v_mfma_f32_16x16x32_bf16 v[12:15], v[50:53], v[54:57], v[12:15]
	s_barrier
	v_mfma_f32_16x16x32_bf16 v[16:19], v[50:53], v[22:25], v[16:19]
	v_mad_u64_u32 v[32:33], s[0:1], v156, s97, v[32:33]
	s_mov_b64 s[0:1], 0x1800
	v_mfma_f32_16x16x32_bf16 v[0:3], v[50:53], v[62:65], v[0:3]
	v_mfma_f32_16x16x32_bf16 v[4:7], v[36:39], v[62:65], v[4:7]
	v_mfma_f32_16x16x32_bf16 v[44:47], v[36:39], v[22:25], v[44:47]
	ds_write2_b32 v20, v26, v40 offset1:16
	ds_write2_b32 v20, v27, v41 offset0:68 offset1:84
	ds_write2_b32 v20, v28, v42 offset0:136 offset1:152
	ds_write2_b32 v20, v29, v43 offset0:204 offset1:220
	s_nop 3
	ds_write2_b32 v20, v44, v4 offset0:32 offset1:48
	ds_write2_b32 v20, v45, v5 offset0:100 offset1:116
	ds_write2_b32 v20, v46, v6 offset0:168 offset1:184
	ds_write2_b32 v20, v47, v7 offset0:236 offset1:252
	ds_write_b32 v20, v11 offset:5168
	v_add_u32_e32 v4, 0x1000, v20
	v_add_u32_e32 v5, 0x1400, v20
	ds_write2_b32 v4, v8, v12 offset0:64 offset1:80
	ds_write2_b32 v4, v9, v13 offset0:132 offset1:148
	ds_write2_b32 v4, v10, v14 offset0:200 offset1:216
	ds_write2_b32 v5, v15, v19 offset0:28 offset1:44
	ds_write2_b32 v4, v16, v0 offset0:96 offset1:112
	ds_write2_b32 v4, v17, v1 offset0:164 offset1:180
	ds_write2_b32 v4, v18, v2 offset0:232 offset1:248
	ds_write_b32 v20, v3 offset:5360
	v_lshlrev_b32_e32 v0, 5, v80
	v_and_b32_e32 v42, 32, v0
	v_mul_u32_u24_e32 v0, 0x110, v35
	v_lshlrev_b32_e32 v45, 2, v42
	v_add3_u32 v40, v49, v0, v45
	s_waitcnt lgkmcnt(0)
	s_barrier
	ds_read_b128 v[28:31], v40
	ds_read_b128 v[24:27], v40 offset:16
	ds_read_b128 v[20:23], v40 offset:32
	ds_read_b128 v[16:19], v40 offset:48
	ds_read_b128 v[12:15], v40 offset:64
	ds_read_b128 v[8:11], v40 offset:80
	s_waitcnt lgkmcnt(5)
	v_mov_b32_e32 v2, v29
	s_waitcnt lgkmcnt(4)
	v_mov_b32_e32 v3, v25
	v_mov_b32_e32 v0, v28
	v_mov_b32_e32 v1, v24
	v_pk_mul_f32 v[2:3], v[2:3], v[2:3]
	v_mov_b32_e32 v4, v31
	v_mov_b32_e32 v5, v27
	v_pk_fma_f32 v[0:1], v[0:1], v[0:1], v[2:3]
	v_mov_b32_e32 v2, v30
	v_mov_b32_e32 v3, v26
	v_pk_mul_f32 v[4:5], v[4:5], v[4:5]
	v_ashrrev_i32_e32 v35, 31, v34
	v_pk_fma_f32 v[2:3], v[2:3], v[2:3], v[4:5]
	s_waitcnt lgkmcnt(3)
	v_pk_mul_f32 v[4:5], v[20:21], v[20:21]
	v_pk_add_f32 v[0:1], v[0:1], v[2:3]
	v_pk_mul_f32 v[2:3], v[22:23], v[22:23]
	v_pk_add_f32 v[0:1], v[0:1], v[0:1] op_sel:[0,1] op_sel_hi:[1,0]
	v_pk_mov_b32 v[6:7], v[4:5], v[2:3] op_sel:[1,0]
	v_mov_b32_e32 v5, v3
	v_pk_add_f32 v[2:3], v[6:7], v[4:5]
	s_waitcnt lgkmcnt(1)
	v_mul_f32_e32 v4, v12, v12
	v_mul_f32_e32 v5, v13, v13
	v_pk_add_f32 v[2:3], v[2:3], v[2:3] op_sel:[0,1] op_sel_hi:[1,0]
	v_mov_b32_e32 v1, v4
	v_mov_b32_e32 v3, v5
	v_pk_add_f32 v[0:1], v[0:1], v[2:3]
	v_mul_f32_e32 v2, v17, v17
	v_mul_f32_e32 v4, v19, v19
	v_mul_f32_e32 v6, v14, v14
	v_mul_f32_e32 v7, v15, v15
	v_pk_fma_f32 v[2:3], v[16:17], v[16:17], v[2:3] op_sel_hi:[1,1,0]
	v_pk_fma_f32 v[4:5], v[18:19], v[18:19], v[4:5] op_sel_hi:[1,1,0]
	v_mov_b32_e32 v3, v6
	v_mov_b32_e32 v5, v7
	v_pk_add_f32 v[2:3], v[2:3], v[4:5]
	v_lshlrev_b64 v[34:35], 1, v[34:35]
	v_pk_add_f32 v[36:37], v[0:1], v[2:3]
	s_waitcnt lgkmcnt(0)
; #define LAS __attribute__((address_space(3)))
; #define LAS __attribute__((address_space(3)))
; DI u32x4 pack8(const float (&f)[8]) { u32x4 o; o.x = pk(f[0], f[1]); o.y = pk(f[2], f[3]); o.z = pk(f[4], f[5]); o.w = pk(f[6], f[7]); return o; }
; template <int MODE>
; DI void gla4_unit(const bf16_t* z, float* ST, float* DEC, bf16_t* Y, const float* aw_g, const float* ab_g, const float* ng, ldsp lds, int tid, int u) {
;     ...
;             const int t7 = tid & 127, t = t7 >> 1, e0 = (t7 & 1) * 32;
;             f32x4 o[8]; float ss = 0.f;
; #pragma unroll
;             for (int k = 0; k < 8; ++k) { o[k] = *(LAS f32x4*)(hr + t * 272 + (e0 + 4 * k) * 4); ss += (o[k][0] * o[k][0] + o[k][1] * o[k][1]) + (o[k][2] * o[k][2] + o[k][3] * o[k][3]); }
;             ss += __shfl_xor(ss, 1);
;             const float rs = rsqrtf(ss * (1.0f / 64.0f) + EPS);
; #pragma unroll
;             for (int k = 0; k < 4; ++k) {
;                 float gg[8]; unpack8(*(const u32x4*)(z + (size_t)(tok0 + t) * ZLD + C_GG + hd * 64 + e0 + 8 * k), gg);
;                 float ov[8];
; #pragma unroll
;                 for (int j = 0; j < 8; ++j) {
;                     const float x = j < 4 ? o[2 * k][j & 3] : o[2 * k + 1][j & 3];
;                     ov[j] = x * rs * ng[e0 + 8 * k + j] * (gg[j] / (1.0f + __expf(-gg[j])));
;                 }
;                 *(u32x4*)(Y + (size_t)(tok0 + t) * D + 768 + hd * 64 + e0 + 8 * k) = pack8(ov);
	v_pk_mul_f32 v[0:1], v[10:11], v[10:11]
	v_pk_mul_f32 v[2:3], v[8:9], v[8:9]
	v_pk_add_f32 v[36:37], v[36:37], v[36:37] op_sel:[0,1] op_sel_hi:[1,0]
	v_pk_mov_b32 v[4:5], v[2:3], v[0:1] op_sel:[1,0]
	v_mov_b32_e32 v3, v1
	v_pk_add_f32 v[38:39], v[4:5], v[2:3]
	ds_read_b128 v[4:7], v40 offset:96
	ds_read_b128 v[0:3], v40 offset:112
	v_pk_add_f32 v[38:39], v[38:39], v[38:39] op_sel:[0,1] op_sel_hi:[1,0]
	v_lshl_add_u64 v[32:33], v[32:33], 0, v[34:35]
	s_waitcnt lgkmcnt(0)
	v_mul_f32_e32 v40, v0, v0
	v_mul_f32_e32 v41, v1, v1
	v_mov_b32_e32 v37, v40
	v_mov_b32_e32 v39, v41
	v_pk_add_f32 v[36:37], v[36:37], v[38:39]
	v_mul_f32_e32 v38, v5, v5
	v_mul_f32_e32 v40, v7, v7
	v_mul_f32_e32 v43, v2, v2
	v_mul_f32_e32 v44, v3, v3
	v_pk_fma_f32 v[38:39], v[4:5], v[4:5], v[38:39] op_sel_hi:[1,1,0]
	v_pk_fma_f32 v[40:41], v[6:7], v[6:7], v[40:41] op_sel_hi:[1,1,0]
	v_mov_b32_e32 v39, v43
	v_mov_b32_e32 v41, v44
	v_pk_add_f32 v[38:39], v[38:39], v[40:41]
	s_nop 0
	v_pk_add_f32 v[36:37], v[36:37], v[38:39]
	v_lshlrev_b64 v[38:39], 11, v[156:157]
	v_add_f32_e32 v36, v36, v37
	ds_bpermute_b32 v37, v137, v36
	v_lshl_add_u64 v[38:39], s[92:93], 0, v[38:39]
	v_lshl_add_u64 v[34:35], v[38:39], 0, v[34:35]
	s_waitcnt lgkmcnt(0)
	v_add_f32_e32 v36, v36, v37
	v_fmamk_f32 v36, v36, 0x3c800000, v162
	v_cmp_gt_f32_e32 vcc, s47, v36
	v_mul_f32_e32 v37, 0x4b800000, v36
	s_nop 0
	v_cndmask_b32_e32 v36, v36, v37, vcc
	v_rsq_f32_e32 v36, v36
	s_nop 0
	v_mul_f32_e32 v37, 0x45800000, v36
	v_cndmask_b32_e32 v44, v36, v37, vcc
	v_lshlrev_b32_e32 v36, 1, v42
	v_mov_b32_e32 v37, v157
	v_lshl_add_u64 v[32:33], v[32:33], 0, v[36:37]
	v_lshl_add_u64 v[42:43], v[32:33], 0, s[0:1]
	v_add_co_u32_e32 v32, vcc, s33, v32
	v_lshl_add_u64 v[40:41], v[34:35], 0, v[36:37]
	s_nop 0
	v_addc_co_u32_e32 v33, vcc, 0, v33, vcc
	global_load_dwordx4 v[32:35], v[32:33], off offset:2048
	v_mul_f32_e32 v28, v28, v44
	v_mul_f32_e32 v29, v29, v44
	v_mul_f32_e32 v30, v30, v44
	v_mul_f32_e32 v31, v31, v44
	v_mul_f32_e32 v24, v24, v44
	v_mul_f32_e32 v20, v20, v44
	v_mul_f32_e32 v21, v21, v44
	v_mul_f32_e32 v22, v22, v44
	v_mul_f32_e32 v23, v23, v44
	v_mul_f32_e32 v16, v16, v44
	v_mul_f32_e32 v12, v12, v44
	v_mul_f32_e32 v13, v13, v44
	v_mul_f32_e32 v14, v14, v44
	v_mul_f32_e32 v15, v15, v44
	v_mul_f32_e32 v8, v8, v44
	v_mul_f32_e32 v1, v1, v44
	v_mul_f32_e32 v2, v2, v44
	v_mul_f32_e32 v0, v0, v44
	v_mul_f32_e32 v6, v6, v44
	v_mul_f32_e32 v5, v5, v44
	v_mul_f32_e32 v4, v4, v44
	v_mul_f32_e32 v3, v3, v44
	s_waitcnt vmcnt(0)
	v_lshlrev_b32_e32 v52, 16, v32
	v_and_b32_e32 v53, 0xffff0000, v32
	v_lshlrev_b32_e32 v51, 16, v33
	v_and_b32_e32 v50, 0xffff0000, v33
	v_lshlrev_b32_e32 v49, 16, v34
	v_and_b32_e32 v48, 0xffff0000, v34
	v_lshlrev_b32_e32 v47, 16, v35
	v_and_b32_e32 v46, 0xffff0000, v35
	global_load_dwordx4 v[32:35], v45, s[20:21] offset:16
	global_load_dwordx4 v[36:39], v45, s[20:21]
	s_waitcnt vmcnt(1)
	v_mul_f32_e32 v24, v32, v24
	s_waitcnt vmcnt(0)
	v_mul_f32_e32 v28, v36, v28
	v_mul_f32_e32 v36, 0xbfb8aa3b, v52
	v_exp_f32_e32 v36, v36
	v_mul_f32_e32 v29, v37, v29
	v_mul_f32_e32 v30, v38, v30
	v_mul_f32_e32 v31, v39, v31
	v_add_f32_e32 v36, 1.0, v36
	v_div_scale_f32 v54, s[0:1], v36, v36, v52
	v_rcp_f32_e32 v55, v54
	v_mul_f32_e32 v32, 0xbfb8aa3b, v49
	v_exp_f32_e32 v32, v32
	v_fma_f32 v56, -v54, v55, 1.0
	v_fmac_f32_e32 v55, v56, v55
	v_div_scale_f32 v56, vcc, v52, v36, v52
	v_mul_f32_e32 v57, v56, v55
	v_fma_f32 v58, -v54, v57, v56
	v_fmac_f32_e32 v57, v58, v55
	v_fma_f32 v54, -v54, v57, v56
	v_div_fmas_f32 v54, v54, v55, v57
	v_div_fixup_f32 v36, v54, v36, v52
	v_mul_f32_e32 v28, v36, v28
	v_mul_f32_e32 v36, 0xbfb8aa3b, v53
	v_exp_f32_e32 v36, v36
	v_add_f32_e32 v32, 1.0, v32
	v_add_f32_e32 v36, 1.0, v36
	v_div_scale_f32 v37, s[0:1], v36, v36, v53
	v_rcp_f32_e32 v52, v37
	s_nop 0
	v_fma_f32 v54, -v37, v52, 1.0
	v_fmac_f32_e32 v52, v54, v52
	v_div_scale_f32 v54, vcc, v53, v36, v53
	v_mul_f32_e32 v55, v54, v52
	v_fma_f32 v56, -v37, v55, v54
	v_fmac_f32_e32 v55, v56, v52
	v_fma_f32 v37, -v37, v55, v54
	v_div_fmas_f32 v37, v37, v52, v55
	v_div_fixup_f32 v36, v37, v36, v53
	v_mul_f32_e32 v29, v36, v29
	v_mul_f32_e32 v36, 0xbfb8aa3b, v51
	v_exp_f32_e32 v36, v36
	s_nop 0
	v_add_f32_e32 v36, 1.0, v36
	v_div_scale_f32 v37, s[0:1], v36, v36, v51
	v_rcp_f32_e32 v38, v37
	s_nop 0
	v_fma_f32 v52, -v37, v38, 1.0
	v_fmac_f32_e32 v38, v52, v38
	v_div_scale_f32 v52, vcc, v51, v36, v51
	v_mul_f32_e32 v53, v52, v38
	v_fma_f32 v54, -v37, v53, v52
	v_fmac_f32_e32 v53, v54, v38
	v_fma_f32 v37, -v37, v53, v52
	v_div_fmas_f32 v37, v37, v38, v53
	v_div_fixup_f32 v36, v37, v36, v51
	v_mul_f32_e32 v30, v36, v30
	v_mul_f32_e32 v36, 0xbfb8aa3b, v50
	v_exp_f32_e32 v36, v36
	s_nop 0
	v_add_f32_e32 v36, 1.0, v36
	v_div_scale_f32 v37, s[0:1], v36, v36, v50
	v_rcp_f32_e32 v38, v37
	s_nop 0
	v_fma_f32 v39, -v37, v38, 1.0
	v_fmac_f32_e32 v38, v39, v38
	v_div_scale_f32 v39, vcc, v50, v36, v50
	v_mul_f32_e32 v51, v39, v38
	v_fma_f32 v52, -v37, v51, v39
	v_fmac_f32_e32 v51, v52, v38
	v_fma_f32 v37, -v37, v51, v39
	v_div_fmas_f32 v37, v37, v38, v51
	v_div_fixup_f32 v36, v37, v36, v50
	v_mul_f32_e32 v31, v36, v31
	v_div_scale_f32 v36, s[0:1], v32, v32, v49
	v_rcp_f32_e32 v37, v36
	s_nop 0
	v_fma_f32 v38, -v36, v37, 1.0
	v_fmac_f32_e32 v37, v38, v37
	v_div_scale_f32 v38, vcc, v49, v32, v49
	v_mul_f32_e32 v39, v38, v37
	v_fma_f32 v50, -v36, v39, v38
	v_fmac_f32_e32 v39, v50, v37
	v_fma_f32 v36, -v36, v39, v38
	v_div_fmas_f32 v36, v36, v37, v39
	v_div_fixup_f32 v32, v36, v32, v49
	v_mul_f32_e32 v32, v32, v24
	v_mul_f32_e32 v24, v25, v44
	v_mul_f32_e32 v25, 0xbfb8aa3b, v48
	v_exp_f32_e32 v25, v25
	v_mul_f32_e32 v24, v33, v24
; DI u32x4 pack8(const float (&f)[8]) { u32x4 o; o.x = pk(f[0], f[1]); o.y = pk(f[2], f[3]); o.z = pk(f[4], f[5]); o.w = pk(f[6], f[7]); return o; }
; template <int MODE>
; DI void gla4_unit(const bf16_t* z, float* ST, float* DEC, bf16_t* Y, const float* aw_g, const float* ab_g, const float* ng, ldsp lds, int tid, int u) {
;     ...
; #pragma unroll
;             for (int k = 0; k < 4; ++k) {
;                 float gg[8]; unpack8(*(const u32x4*)(z + (size_t)(tok0 + t) * ZLD + C_GG + hd * 64 + e0 + 8 * k), gg);
;                 float ov[8];
; #pragma unroll
;                 for (int j = 0; j < 8; ++j) {
;                     const float x = j < 4 ? o[2 * k][j & 3] : o[2 * k + 1][j & 3];
;                     ov[j] = x * rs * ng[e0 + 8 * k + j] * (gg[j] / (1.0f + __expf(-gg[j])));
;                 }
;                 *(u32x4*)(Y + (size_t)(tok0 + t) * D + 768 + hd * 64 + e0 + 8 * k) = pack8(ov);
	v_add_f32_e32 v25, 1.0, v25
	v_div_scale_f32 v33, s[0:1], v25, v25, v48
	v_rcp_f32_e32 v36, v33
	s_nop 0
	v_fma_f32 v37, -v33, v36, 1.0
	v_fmac_f32_e32 v36, v37, v36
	v_div_scale_f32 v37, vcc, v48, v25, v48
	v_mul_f32_e32 v38, v37, v36
	v_fma_f32 v39, -v33, v38, v37
	v_fmac_f32_e32 v38, v39, v36
	v_fma_f32 v33, -v33, v38, v37
	v_div_fmas_f32 v33, v33, v36, v38
	v_div_fixup_f32 v25, v33, v25, v48
	v_mul_f32_e32 v33, v25, v24
	v_mul_f32_e32 v25, 0xbfb8aa3b, v47
	v_exp_f32_e32 v25, v25
	v_mul_f32_e32 v24, v26, v44
	v_mul_f32_e32 v24, v34, v24
	v_add_f32_e32 v25, 1.0, v25
	v_div_scale_f32 v26, s[0:1], v25, v25, v47
	v_rcp_f32_e32 v34, v26
	s_nop 0
	v_fma_f32 v36, -v26, v34, 1.0
	v_fmac_f32_e32 v34, v36, v34
	v_div_scale_f32 v36, vcc, v47, v25, v47
	v_mul_f32_e32 v37, v36, v34
	v_fma_f32 v38, -v26, v37, v36
	v_fmac_f32_e32 v37, v38, v34
	v_fma_f32 v26, -v26, v37, v36
	v_div_fmas_f32 v26, v26, v34, v37
	v_div_fixup_f32 v25, v26, v25, v47
	v_mul_f32_e32 v34, v25, v24
	v_mul_f32_e32 v25, 0xbfb8aa3b, v46
	v_exp_f32_e32 v25, v25
	v_mul_f32_e32 v24, v27, v44
	v_mul_f32_e32 v24, v35, v24
	v_add_f32_e32 v25, 1.0, v25
	v_div_scale_f32 v26, s[0:1], v25, v25, v46
	v_rcp_f32_e32 v27, v26
	s_nop 0
	v_fma_f32 v35, -v26, v27, 1.0
	v_fmac_f32_e32 v27, v35, v27
	v_div_scale_f32 v35, vcc, v46, v25, v46
	v_mul_f32_e32 v36, v35, v27
	v_fma_f32 v37, -v26, v36, v35
	v_fmac_f32_e32 v36, v37, v27
	v_fma_f32 v26, -v26, v36, v35
	v_div_fmas_f32 v26, v26, v27, v36
	v_div_fixup_f32 v25, v26, v25, v46
	v_mul_f32_e32 v27, v25, v24
	v_cvt_pk_bf16_f32 v24, v28, v29
	v_cvt_pk_bf16_f32 v25, v30, v31
	v_cvt_pk_bf16_f32 v26, v32, v33
	v_cvt_pk_bf16_f32 v27, v34, v27
	global_store_dwordx4 v[40:41], v[24:27], off offset:1536
	global_load_dwordx4 v[24:27], v[42:43], off offset:16
	s_waitcnt vmcnt(0)
	v_lshlrev_b32_e32 v34, 16, v24
	v_and_b32_e32 v35, 0xffff0000, v24
	v_lshlrev_b32_e32 v36, 16, v25
	v_and_b32_e32 v37, 0xffff0000, v25
	v_lshlrev_b32_e32 v38, 16, v26
	v_and_b32_e32 v39, 0xffff0000, v26
	v_lshlrev_b32_e32 v29, 16, v27
	v_and_b32_e32 v28, 0xffff0000, v27
	global_load_dwordx4 v[24:27], v45, s[20:21] offset:48
	global_load_dwordx4 v[30:33], v45, s[20:21] offset:32
	s_waitcnt vmcnt(1)
	v_mul_f32_e32 v16, v16, v24
	s_waitcnt vmcnt(0)
	v_mul_f32_e32 v20, v20, v30
	v_mul_f32_e32 v30, 0xbfb8aa3b, v34
	v_exp_f32_e32 v30, v30
	v_mul_f32_e32 v21, v21, v31
	v_mul_f32_e32 v22, v22, v32
	v_mul_f32_e32 v23, v23, v33
	v_add_f32_e32 v30, 1.0, v30
	v_div_scale_f32 v46, s[0:1], v30, v30, v34
	v_rcp_f32_e32 v47, v46
	v_mul_f32_e32 v24, 0xbfb8aa3b, v38
	v_exp_f32_e32 v24, v24
	v_fma_f32 v48, -v46, v47, 1.0
	v_fmac_f32_e32 v47, v48, v47
	v_div_scale_f32 v48, vcc, v34, v30, v34
	v_mul_f32_e32 v49, v48, v47
	v_fma_f32 v50, -v46, v49, v48
	v_fmac_f32_e32 v49, v50, v47
	v_fma_f32 v46, -v46, v49, v48
	v_div_fmas_f32 v46, v46, v47, v49
	v_div_fixup_f32 v30, v46, v30, v34
	v_mul_f32_e32 v20, v20, v30
	v_mul_f32_e32 v30, 0xbfb8aa3b, v35
	v_exp_f32_e32 v30, v30
	v_add_f32_e32 v24, 1.0, v24
	v_add_f32_e32 v30, 1.0, v30
	v_div_scale_f32 v31, s[0:1], v30, v30, v35
	v_rcp_f32_e32 v34, v31
	s_nop 0
	v_fma_f32 v46, -v31, v34, 1.0
	v_fmac_f32_e32 v34, v46, v34
	v_div_scale_f32 v46, vcc, v35, v30, v35
	v_mul_f32_e32 v47, v46, v34
	v_fma_f32 v48, -v31, v47, v46
	v_fmac_f32_e32 v47, v48, v34
	v_fma_f32 v31, -v31, v47, v46
	v_div_fmas_f32 v31, v31, v34, v47
	v_div_fixup_f32 v30, v31, v30, v35
	v_mul_f32_e32 v21, v21, v30
	v_mul_f32_e32 v30, 0xbfb8aa3b, v36
	v_exp_f32_e32 v30, v30
	s_nop 0
	v_add_f32_e32 v30, 1.0, v30
	v_div_scale_f32 v31, s[0:1], v30, v30, v36
	v_rcp_f32_e32 v32, v31
	s_nop 0
	v_fma_f32 v34, -v31, v32, 1.0
	v_fmac_f32_e32 v32, v34, v32
	v_div_scale_f32 v34, vcc, v36, v30, v36
	v_mul_f32_e32 v35, v34, v32
	v_fma_f32 v46, -v31, v35, v34
	v_fmac_f32_e32 v35, v46, v32
	v_fma_f32 v31, -v31, v35, v34
	v_div_fmas_f32 v31, v31, v32, v35
	v_div_fixup_f32 v30, v31, v30, v36
	v_mul_f32_e32 v22, v22, v30
	v_mul_f32_e32 v30, 0xbfb8aa3b, v37
	v_exp_f32_e32 v30, v30
	s_nop 0
	v_add_f32_e32 v30, 1.0, v30
	v_div_scale_f32 v31, s[0:1], v30, v30, v37
	v_rcp_f32_e32 v32, v31
	s_nop 0
	v_fma_f32 v33, -v31, v32, 1.0
	v_fmac_f32_e32 v32, v33, v32
	v_div_scale_f32 v33, vcc, v37, v30, v37
	v_mul_f32_e32 v34, v33, v32
	v_fma_f32 v35, -v31, v34, v33
	v_fmac_f32_e32 v34, v35, v32
	v_fma_f32 v31, -v31, v34, v33
	v_div_fmas_f32 v31, v31, v32, v34
	v_div_fixup_f32 v30, v31, v30, v37
	v_mul_f32_e32 v23, v23, v30
	v_div_scale_f32 v30, s[0:1], v24, v24, v38
	v_rcp_f32_e32 v31, v30
	s_nop 0
	v_fma_f32 v32, -v30, v31, 1.0
	v_fmac_f32_e32 v31, v32, v31
	v_div_scale_f32 v32, vcc, v38, v24, v38
	v_mul_f32_e32 v33, v32, v31
	v_fma_f32 v34, -v30, v33, v32
	v_fmac_f32_e32 v33, v34, v31
	v_fma_f32 v30, -v30, v33, v32
	v_div_fmas_f32 v30, v30, v31, v33
	v_div_fixup_f32 v24, v30, v24, v38
	v_mul_f32_e32 v24, v16, v24
	v_mul_f32_e32 v16, v17, v44
	v_mul_f32_e32 v17, 0xbfb8aa3b, v39
	v_exp_f32_e32 v17, v17
	v_mul_f32_e32 v16, v16, v25
	v_add_f32_e32 v17, 1.0, v17
	v_div_scale_f32 v25, s[0:1], v17, v17, v39
	v_rcp_f32_e32 v30, v25
	s_nop 0
	v_fma_f32 v31, -v25, v30, 1.0
	v_fmac_f32_e32 v30, v31, v30
	v_div_scale_f32 v31, vcc, v39, v17, v39
	v_mul_f32_e32 v32, v31, v30
	v_fma_f32 v33, -v25, v32, v31
	v_fmac_f32_e32 v32, v33, v30
	v_fma_f32 v25, -v25, v32, v31
	v_div_fmas_f32 v25, v25, v30, v32
	v_div_fixup_f32 v17, v25, v17, v39
	v_mul_f32_e32 v25, v17, v16
	v_mul_f32_e32 v17, 0xbfb8aa3b, v29
	v_exp_f32_e32 v17, v17
	v_mul_f32_e32 v16, v18, v44
	v_mul_f32_e32 v16, v16, v26
	v_add_f32_e32 v17, 1.0, v17
	v_div_scale_f32 v18, s[0:1], v17, v17, v29
	v_rcp_f32_e32 v26, v18
	s_nop 0
	v_fma_f32 v30, -v18, v26, 1.0
	v_fmac_f32_e32 v26, v30, v26
	v_div_scale_f32 v30, vcc, v29, v17, v29
	v_mul_f32_e32 v31, v30, v26
	v_fma_f32 v32, -v18, v31, v30
	v_fmac_f32_e32 v31, v32, v26
	v_fma_f32 v18, -v18, v31, v30
	v_div_fmas_f32 v18, v18, v26, v31
	v_div_fixup_f32 v17, v18, v17, v29
	v_mul_f32_e32 v26, v17, v16
	v_mul_f32_e32 v17, 0xbfb8aa3b, v28
	v_exp_f32_e32 v17, v17
	v_mul_f32_e32 v16, v19, v44
	v_mul_f32_e32 v16, v16, v27
	v_add_f32_e32 v17, 1.0, v17
	v_div_scale_f32 v18, s[0:1], v17, v17, v28
	v_rcp_f32_e32 v19, v18
	s_nop 0
	v_fma_f32 v27, -v18, v19, 1.0
	v_fmac_f32_e32 v19, v27, v19
	v_div_scale_f32 v27, vcc, v28, v17, v28
	v_mul_f32_e32 v29, v27, v19
	v_fma_f32 v30, -v18, v29, v27
	v_fmac_f32_e32 v29, v30, v19
	v_fma_f32 v18, -v18, v29, v27
	v_div_fmas_f32 v18, v18, v19, v29
	v_div_fixup_f32 v17, v18, v17, v28
	v_mul_f32_e32 v19, v17, v16
	v_cvt_pk_bf16_f32 v16, v20, v21
	v_cvt_pk_bf16_f32 v17, v22, v23
	v_cvt_pk_bf16_f32 v18, v24, v25
	v_cvt_pk_bf16_f32 v19, v26, v19
	global_store_dwordx4 v[40:41], v[16:19], off offset:1552
	global_load_dwordx4 v[16:19], v[42:43], off offset:32
	s_waitcnt vmcnt(0)
; DI u32x4 pack8(const float (&f)[8]) { u32x4 o; o.x = pk(f[0], f[1]); o.y = pk(f[2], f[3]); o.z = pk(f[4], f[5]); o.w = pk(f[6], f[7]); return o; }
; template <int MODE>
; DI void gla4_unit(const bf16_t* z, float* ST, float* DEC, bf16_t* Y, const float* aw_g, const float* ab_g, const float* ng, ldsp lds, int tid, int u) {
;     ...
; #pragma unroll
;             for (int k = 0; k < 4; ++k) {
;                 float gg[8]; unpack8(*(const u32x4*)(z + (size_t)(tok0 + t) * ZLD + C_GG + hd * 64 + e0 + 8 * k), gg);
;                 float ov[8];
; #pragma unroll
;                 for (int j = 0; j < 8; ++j) {
;                     const float x = j < 4 ? o[2 * k][j & 3] : o[2 * k + 1][j & 3];
;                     ov[j] = x * rs * ng[e0 + 8 * k + j] * (gg[j] / (1.0f + __expf(-gg[j])));
;                 }
;                 *(u32x4*)(Y + (size_t)(tok0 + t) * D + 768 + hd * 64 + e0 + 8 * k) = pack8(ov);
	v_lshlrev_b32_e32 v26, 16, v16
	v_and_b32_e32 v27, 0xffff0000, v16
	v_lshlrev_b32_e32 v28, 16, v17
	v_and_b32_e32 v29, 0xffff0000, v17
	v_lshlrev_b32_e32 v30, 16, v18
	v_and_b32_e32 v31, 0xffff0000, v18
	v_lshlrev_b32_e32 v21, 16, v19
	v_and_b32_e32 v20, 0xffff0000, v19
	global_load_dwordx4 v[16:19], v45, s[20:21] offset:80
	global_load_dwordx4 v[22:25], v45, s[20:21] offset:64
	s_waitcnt vmcnt(1)
	v_mul_f32_e32 v8, v8, v16
	s_waitcnt vmcnt(0)
	v_mul_f32_e32 v12, v12, v22
	v_mul_f32_e32 v22, 0xbfb8aa3b, v26
	v_exp_f32_e32 v22, v22
	v_mul_f32_e32 v13, v13, v23
	v_mul_f32_e32 v14, v14, v24
	v_mul_f32_e32 v15, v15, v25
	v_add_f32_e32 v22, 1.0, v22
	v_div_scale_f32 v32, s[0:1], v22, v22, v26
	v_rcp_f32_e32 v33, v32
	v_mul_f32_e32 v16, 0xbfb8aa3b, v30
	v_exp_f32_e32 v16, v16
	v_fma_f32 v34, -v32, v33, 1.0
	v_fmac_f32_e32 v33, v34, v33
	v_div_scale_f32 v34, vcc, v26, v22, v26
	v_mul_f32_e32 v35, v34, v33
	v_fma_f32 v36, -v32, v35, v34
	v_fmac_f32_e32 v35, v36, v33
	v_fma_f32 v32, -v32, v35, v34
	v_div_fmas_f32 v32, v32, v33, v35
	v_div_fixup_f32 v22, v32, v22, v26
	v_mul_f32_e32 v12, v12, v22
	v_mul_f32_e32 v22, 0xbfb8aa3b, v27
	v_exp_f32_e32 v22, v22
	v_add_f32_e32 v16, 1.0, v16
	v_add_f32_e32 v22, 1.0, v22
	v_div_scale_f32 v23, s[0:1], v22, v22, v27
	v_rcp_f32_e32 v26, v23
	s_nop 0
	v_fma_f32 v32, -v23, v26, 1.0
	v_fmac_f32_e32 v26, v32, v26
	v_div_scale_f32 v32, vcc, v27, v22, v27
	v_mul_f32_e32 v33, v32, v26
	v_fma_f32 v34, -v23, v33, v32
	v_fmac_f32_e32 v33, v34, v26
	v_fma_f32 v23, -v23, v33, v32
	v_div_fmas_f32 v23, v23, v26, v33
	v_div_fixup_f32 v22, v23, v22, v27
	v_mul_f32_e32 v13, v13, v22
	v_mul_f32_e32 v22, 0xbfb8aa3b, v28
	v_exp_f32_e32 v22, v22
	s_nop 0
	v_add_f32_e32 v22, 1.0, v22
	v_div_scale_f32 v23, s[0:1], v22, v22, v28
	v_rcp_f32_e32 v24, v23
	s_nop 0
	v_fma_f32 v26, -v23, v24, 1.0
	v_fmac_f32_e32 v24, v26, v24
	v_div_scale_f32 v26, vcc, v28, v22, v28
	v_mul_f32_e32 v27, v26, v24
	v_fma_f32 v32, -v23, v27, v26
	v_fmac_f32_e32 v27, v32, v24
	v_fma_f32 v23, -v23, v27, v26
	v_div_fmas_f32 v23, v23, v24, v27
	v_div_fixup_f32 v22, v23, v22, v28
	v_mul_f32_e32 v14, v14, v22
	v_mul_f32_e32 v22, 0xbfb8aa3b, v29
	v_exp_f32_e32 v22, v22
	s_nop 0
	v_add_f32_e32 v22, 1.0, v22
	v_div_scale_f32 v23, s[0:1], v22, v22, v29
	v_rcp_f32_e32 v24, v23
	s_nop 0
	v_fma_f32 v25, -v23, v24, 1.0
	v_fmac_f32_e32 v24, v25, v24
	v_div_scale_f32 v25, vcc, v29, v22, v29
	v_mul_f32_e32 v26, v25, v24
	v_fma_f32 v27, -v23, v26, v25
	v_fmac_f32_e32 v26, v27, v24
	v_fma_f32 v23, -v23, v26, v25
	v_div_fmas_f32 v23, v23, v24, v26
	v_div_fixup_f32 v22, v23, v22, v29
	v_mul_f32_e32 v15, v15, v22
	v_div_scale_f32 v22, s[0:1], v16, v16, v30
	v_rcp_f32_e32 v23, v22
	s_nop 0
	v_fma_f32 v24, -v22, v23, 1.0
	v_fmac_f32_e32 v23, v24, v23
	v_div_scale_f32 v24, vcc, v30, v16, v30
	v_mul_f32_e32 v25, v24, v23
	v_fma_f32 v26, -v22, v25, v24
	v_fmac_f32_e32 v25, v26, v23
	v_fma_f32 v22, -v22, v25, v24
	v_div_fmas_f32 v22, v22, v23, v25
	v_div_fixup_f32 v16, v22, v16, v30
	v_mul_f32_e32 v16, v8, v16
	v_mul_f32_e32 v8, v9, v44
	v_mul_f32_e32 v9, 0xbfb8aa3b, v31
	v_exp_f32_e32 v9, v9
	v_mul_f32_e32 v8, v8, v17
	v_add_f32_e32 v9, 1.0, v9
	v_div_scale_f32 v17, s[0:1], v9, v9, v31
	v_rcp_f32_e32 v22, v17
	s_nop 0
	v_fma_f32 v23, -v17, v22, 1.0
	v_fmac_f32_e32 v22, v23, v22
	v_div_scale_f32 v23, vcc, v31, v9, v31
	v_mul_f32_e32 v24, v23, v22
	v_fma_f32 v25, -v17, v24, v23
	v_fmac_f32_e32 v24, v25, v22
	v_fma_f32 v17, -v17, v24, v23
	v_div_fmas_f32 v17, v17, v22, v24
	v_div_fixup_f32 v9, v17, v9, v31
	v_mul_f32_e32 v17, v9, v8
	v_mul_f32_e32 v9, 0xbfb8aa3b, v21
	v_exp_f32_e32 v9, v9
	v_mul_f32_e32 v8, v10, v44
	v_mul_f32_e32 v8, v8, v18
	v_add_f32_e32 v9, 1.0, v9
	v_div_scale_f32 v10, s[0:1], v9, v9, v21
	v_rcp_f32_e32 v18, v10
	s_nop 0
	v_fma_f32 v22, -v10, v18, 1.0
	v_fmac_f32_e32 v18, v22, v18
	v_div_scale_f32 v22, vcc, v21, v9, v21
	v_mul_f32_e32 v23, v22, v18
	v_fma_f32 v24, -v10, v23, v22
	v_fmac_f32_e32 v23, v24, v18
	v_fma_f32 v10, -v10, v23, v22
	v_div_fmas_f32 v10, v10, v18, v23
	v_div_fixup_f32 v9, v10, v9, v21
	v_mul_f32_e32 v18, v9, v8
	v_mul_f32_e32 v9, 0xbfb8aa3b, v20
	v_exp_f32_e32 v9, v9
	v_mul_f32_e32 v8, v11, v44
	v_mul_f32_e32 v8, v8, v19
	v_add_f32_e32 v9, 1.0, v9
	v_div_scale_f32 v10, s[0:1], v9, v9, v20
	v_rcp_f32_e32 v11, v10
	s_nop 0
	v_fma_f32 v19, -v10, v11, 1.0
	v_fmac_f32_e32 v11, v19, v11
	v_div_scale_f32 v19, vcc, v20, v9, v20
	v_mul_f32_e32 v21, v19, v11
	v_fma_f32 v22, -v10, v21, v19
	v_fmac_f32_e32 v21, v22, v11
	v_fma_f32 v10, -v10, v21, v19
	v_div_fmas_f32 v10, v10, v11, v21
	v_div_fixup_f32 v9, v10, v9, v20
	v_mul_f32_e32 v11, v9, v8
	v_cvt_pk_bf16_f32 v8, v12, v13
	v_cvt_pk_bf16_f32 v9, v14, v15
	v_cvt_pk_bf16_f32 v10, v16, v17
	v_cvt_pk_bf16_f32 v11, v18, v11
	global_store_dwordx4 v[40:41], v[8:11], off offset:1568
	global_load_dwordx4 v[16:19], v[42:43], off offset:48
	s_nop 0
	global_load_dwordx4 v[8:11], v45, s[20:21] offset:112
	global_load_dwordx4 v[12:15], v45, s[20:21] offset:96
	s_waitcnt vmcnt(2)
; DI u32x4 pack8(const float (&f)[8]) { u32x4 o; o.x = pk(f[0], f[1]); o.y = pk(f[2], f[3]); o.z = pk(f[4], f[5]); o.w = pk(f[6], f[7]); return o; }
; template <int MODE>
; DI void gla4_unit(const bf16_t* z, float* ST, float* DEC, bf16_t* Y, const float* aw_g, const float* ab_g, const float* ng, ldsp lds, int tid, int u) {
;     ...
; #pragma unroll
;             for (int k = 0; k < 4; ++k) {
;                 float gg[8]; unpack8(*(const u32x4*)(z + (size_t)(tok0 + t) * ZLD + C_GG + hd * 64 + e0 + 8 * k), gg);
;                 float ov[8];
; #pragma unroll
;                 for (int j = 0; j < 8; ++j) {
;                     const float x = j < 4 ? o[2 * k][j & 3] : o[2 * k + 1][j & 3];
;                     ov[j] = x * rs * ng[e0 + 8 * k + j] * (gg[j] / (1.0f + __expf(-gg[j])));
;                 }
;                 *(u32x4*)(Y + (size_t)(tok0 + t) * D + 768 + hd * 64 + e0 + 8 * k) = pack8(ov);
	v_lshlrev_b32_e32 v20, 16, v19
	v_mul_f32_e32 v21, 0xbfb8aa3b, v20
	v_exp_f32_e32 v21, v21
	s_waitcnt vmcnt(1)
	v_mul_f32_e32 v1, v1, v9
	v_mul_f32_e32 v2, v2, v10
	v_mul_f32_e32 v0, v0, v8
	v_add_f32_e32 v21, 1.0, v21
	v_div_scale_f32 v22, s[0:1], v21, v21, v20
	v_rcp_f32_e32 v23, v22
	s_waitcnt vmcnt(0)
	v_mul_f32_e32 v6, v6, v14
	v_mul_f32_e32 v5, v5, v13
	v_and_b32_e32 v19, 0xffff0000, v19
	v_fma_f32 v24, -v22, v23, 1.0
	v_fmac_f32_e32 v23, v24, v23
	v_div_scale_f32 v24, vcc, v20, v21, v20
	v_mul_f32_e32 v25, v24, v23
	v_fma_f32 v26, -v22, v25, v24
	v_fmac_f32_e32 v25, v26, v23
	v_fma_f32 v22, -v22, v25, v24
	v_div_fmas_f32 v22, v22, v23, v25
	v_div_fixup_f32 v20, v22, v21, v20
	v_lshlrev_b32_e32 v21, 16, v18
	v_and_b32_e32 v18, 0xffff0000, v18
	v_mul_f32_e32 v22, 0xbfb8aa3b, v18
	v_exp_f32_e32 v22, v22
	v_mul_f32_e32 v10, v20, v2
	v_lshlrev_b32_e32 v20, 16, v17
	v_and_b32_e32 v17, 0xffff0000, v17
	v_add_f32_e32 v22, 1.0, v22
	v_div_scale_f32 v23, s[0:1], v22, v22, v18
	v_rcp_f32_e32 v24, v23
	v_lshlrev_b32_e32 v2, 16, v16
	v_and_b32_e32 v16, 0xffff0000, v16
	v_mul_f32_e32 v4, v4, v12
	v_fma_f32 v25, -v23, v24, 1.0
	v_fmac_f32_e32 v24, v25, v24
	v_div_scale_f32 v25, vcc, v18, v22, v18
	v_mul_f32_e32 v26, v25, v24
	v_fma_f32 v27, -v23, v26, v25
	v_fmac_f32_e32 v26, v27, v24
	v_fma_f32 v23, -v23, v26, v25
	v_div_fmas_f32 v23, v23, v24, v26
	v_div_fixup_f32 v18, v23, v22, v18
	v_mul_f32_e32 v9, v18, v1
	v_mul_f32_e32 v1, 0xbfb8aa3b, v21
	v_exp_f32_e32 v1, v1
	v_mul_f32_e32 v3, v3, v11
	v_add_f32_e32 v1, 1.0, v1
	v_div_scale_f32 v18, s[0:1], v1, v1, v21
	v_rcp_f32_e32 v22, v18
	s_nop 0
	v_fma_f32 v23, -v18, v22, 1.0
	v_fmac_f32_e32 v22, v23, v22
	v_div_scale_f32 v23, vcc, v21, v1, v21
	v_mul_f32_e32 v24, v23, v22
	v_fma_f32 v25, -v18, v24, v23
	v_fmac_f32_e32 v24, v25, v22
	v_fma_f32 v18, -v18, v24, v23
	v_div_fmas_f32 v18, v18, v22, v24
	v_div_fixup_f32 v1, v18, v1, v21
	v_mul_f32_e32 v8, v0, v1
	v_mul_f32_e32 v0, 0xbfb8aa3b, v17
	v_exp_f32_e32 v0, v0
	s_nop 0
	v_add_f32_e32 v0, 1.0, v0
	v_div_scale_f32 v1, s[0:1], v0, v0, v17
	v_rcp_f32_e32 v18, v1
	s_nop 0
	v_fma_f32 v21, -v1, v18, 1.0
	v_fmac_f32_e32 v18, v21, v18
	v_div_scale_f32 v21, vcc, v17, v0, v17
	v_mul_f32_e32 v22, v21, v18
	v_fma_f32 v23, -v1, v22, v21
	v_fmac_f32_e32 v22, v23, v18
	v_fma_f32 v1, -v1, v22, v21
	v_div_fmas_f32 v1, v1, v18, v22
	v_div_fixup_f32 v0, v1, v0, v17
	v_mul_f32_e32 v1, v7, v44
	v_mul_f32_e32 v1, v1, v15
	v_mul_f32_e32 v1, v1, v0
	v_mul_f32_e32 v0, 0xbfb8aa3b, v20
	v_exp_f32_e32 v0, v0
	s_nop 0
	v_add_f32_e32 v0, 1.0, v0
	v_div_scale_f32 v7, s[0:1], v0, v0, v20
	v_rcp_f32_e32 v15, v7
	s_nop 0
	v_fma_f32 v17, -v7, v15, 1.0
	v_fmac_f32_e32 v15, v17, v15
	v_div_scale_f32 v17, vcc, v20, v0, v20
	v_mul_f32_e32 v18, v17, v15
	v_fma_f32 v21, -v7, v18, v17
	v_fmac_f32_e32 v18, v21, v15
	v_fma_f32 v7, -v7, v18, v17
	v_div_fmas_f32 v7, v7, v15, v18
	v_div_fixup_f32 v0, v7, v0, v20
	v_mul_f32_e32 v6, v6, v0
	v_mul_f32_e32 v0, 0xbfb8aa3b, v16
	v_exp_f32_e32 v0, v0
	s_nop 0
	v_add_f32_e32 v0, 1.0, v0
	v_div_scale_f32 v7, s[0:1], v0, v0, v16
	v_rcp_f32_e32 v14, v7
	s_nop 0
	v_fma_f32 v15, -v7, v14, 1.0
	v_fmac_f32_e32 v14, v15, v14
	v_div_scale_f32 v15, vcc, v16, v0, v16
	v_mul_f32_e32 v17, v15, v14
	v_fma_f32 v18, -v7, v17, v15
	v_fmac_f32_e32 v17, v18, v14
	v_fma_f32 v7, -v7, v17, v15
	v_div_fmas_f32 v7, v7, v14, v17
	v_div_fixup_f32 v0, v7, v0, v16
	v_mul_f32_e32 v0, v5, v0
	v_mul_f32_e32 v5, 0xbfb8aa3b, v2
	v_exp_f32_e32 v5, v5
	s_nop 0
	v_add_f32_e32 v5, 1.0, v5
	v_div_scale_f32 v7, s[0:1], v5, v5, v2
	v_rcp_f32_e32 v13, v7
	s_nop 0
	v_fma_f32 v14, -v7, v13, 1.0
	v_fmac_f32_e32 v13, v14, v13
	v_div_scale_f32 v14, vcc, v2, v5, v2
	v_mul_f32_e32 v15, v14, v13
	v_fma_f32 v16, -v7, v15, v14
	v_fmac_f32_e32 v15, v16, v13
	v_fma_f32 v7, -v7, v15, v14
	v_div_fmas_f32 v7, v7, v13, v15
	v_div_fixup_f32 v2, v7, v5, v2
	v_mul_f32_e32 v2, v4, v2
	v_mul_f32_e32 v4, 0xbfb8aa3b, v19
	v_exp_f32_e32 v4, v4
	v_cvt_pk_bf16_f32 v0, v2, v0
	v_cvt_pk_bf16_f32 v1, v6, v1
	v_cvt_pk_bf16_f32 v2, v8, v9
	s_nop 0
	v_add_f32_e32 v4, 1.0, v4
	v_div_scale_f32 v5, s[0:1], v4, v4, v19
	v_rcp_f32_e32 v7, v5
	s_mov_b64 s[0:1], 0
	v_fma_f32 v11, -v5, v7, 1.0
	v_fmac_f32_e32 v7, v11, v7
	v_div_scale_f32 v11, vcc, v19, v4, v19
	v_mul_f32_e32 v12, v11, v7
	v_fma_f32 v13, -v5, v12, v11
	v_fmac_f32_e32 v12, v13, v7
	v_fma_f32 v5, -v5, v12, v11
	v_div_fmas_f32 v5, v5, v7, v12
	v_div_fixup_f32 v4, v5, v4, v19
	v_mul_f32_e32 v3, v4, v3
	v_cvt_pk_bf16_f32 v3, v10, v3
	global_store_dwordx4 v[40:41], v[0:3], off offset:1584

; #define LAS __attribute__((address_space(3)))
; #define LAS __attribute__((address_space(3)))
; DI float bflo(unsigned v) { return __uint_as_float(v << 16); }
; DI float bfhi(unsigned v) { return __uint_as_float(v & 0xffff0000u); }
; template <int MODE>
; DI void gla4_unit(const bf16_t* z, float* ST, float* DEC, bf16_t* Y, const float* aw_g, const float* ab_g, const float* ng, ldsp lds, int tid, int u) {
;     ...
;     __syncthreads();
;     {
;         constexpr int NM = MODE ? 3 : 2;
; #pragma unroll
;         for (int i = 0; i < NM * 4; ++i) {
;             const int pi = tid + 512 * i, mh = pi >> 9, mat = mh >> 2, head = mh & 3, row = (pi >> 3) & 63, pc = pi & 7;
;             const int col = (MODE ? (mat == 0 ? C_GQ : (mat == 1 ? C_GK : C_GV)) : (mat == 0 ? C_GK : C_GV)) + head * 64 + pc * 8;
;             const int reg = MODE ? mat * 9216 : (mat == 0 ? 0 : G4_R2);
;             *(LAS u32x4*)(lds + head * G4_HEAD + reg + row * 144 + pc * 16) = *(const u32x4*)(z + (size_t)(tok0 + row) * ZLD + col);
;         }
;         const int idx = tid * 2, t = idx >> 4, r = idx & 15;
;         const unsigned v = *(const unsigned*)(z + (size_t)(tok0 + t) * ZLD + C_GA + r);
;         alr[t * 16 + r] = bflo(v); alr[t * 16 + r + 1] = bfhi(v);
;     }
;     float aw[16];
; #pragma unroll
;     for (int r = 0; r < 16; ++r) aw[r] = aw_g[r * 256 + hd * 64 + d];
;     const float ab = ab_g[hd * 64 + d];
.LBB0_451:
	s_ashr_i32 s1, s9, 7
	s_and_b32 s24, s9, 0x7f
	v_mov_b32_e32 v11, v136
	s_lshl_b32 s0, s1, 13
	s_lshl_b32 s6, s24, 6
	s_or_b32 s0, s0, s6
	v_bfe_u32 v4, v11, 3, 6
	s_waitcnt lgkmcnt(0)
	v_and_b32_e32 v5, 7, v11
	v_bfe_u32 v15, v11, 9, 2
	v_cmp_gt_u32_e32 vcc, s76, v11
	v_lshlrev_b32_e32 v8, 3, v5
	v_or_b32_e32 v2, s0, v4
	v_mul_u32_u24_e32 v9, 0x90, v4
	v_cndmask_b32_e32 v4, v200, v201, vcc
	v_lshlrev_b32_e32 v16, 6, v15
	v_mov_b64_e32 v[0:1], s[70:71]
	v_or3_b32 v4, v8, v4, v16
	v_mad_i64_i32 v[2:3], s[10:11], v2, s97, v[0:1]
	v_lshlrev_b32_e32 v156, 1, v4
	v_lshlrev_b32_e32 v12, 4, v5
	v_lshl_add_u64 v[4:5], v[2:3], 0, v[156:157]
	s_barrier
	global_load_dwordx4 v[86:89], v[4:5], off
	v_cndmask_b32_e64 v17, v213, 0, vcc
	v_mad_u32_u24 v15, v15, s5, 0
	v_add_u32_e32 v17, v15, v17
	v_add3_u32 v17, v17, v9, v12
	s_movk_i32 s6, 0xf7ff
	v_ashrrev_i32_e32 v13, 7, v11
	v_bfe_u32 v10, v11, 6, 1
	v_mul_lo_u32 v14, v13, s5
	v_mov_b32_e32 v142, v17
	v_add_u32_e32 v4, 0x200, v11
	v_bfe_u32 v17, v4, 9, 2
	v_cmp_gt_u32_e32 vcc, s76, v4
	v_lshlrev_b32_e32 v5, 6, v17
	v_mul_u32_u24_e32 v17, 0x6c00, v17
	v_cndmask_b32_e32 v4, v200, v201, vcc
	v_or3_b32 v4, v5, v4, v8
	v_lshlrev_b32_e32 v156, 1, v4
	v_lshl_add_u64 v[4:5], v[2:3], 0, v[156:157]
	global_load_dwordx4 v[90:93], v[4:5], off
	v_cndmask_b32_e64 v18, v213, 0, vcc
	v_add3_u32 v17, 0, v17, v18
	v_add3_u32 v17, v17, v9, v12
	v_mov_b32_e32 v143, v17
	v_add_u32_e32 v4, 0x400, v11
	v_bfe_u32 v17, v4, 9, 2
	v_cmp_gt_u32_e32 vcc, s76, v4
	v_lshlrev_b32_e32 v5, 6, v17
	v_mul_u32_u24_e32 v17, 0x6c00, v17
	v_cndmask_b32_e32 v4, v200, v201, vcc
	v_or3_b32 v4, v5, v4, v8
	v_lshlrev_b32_e32 v156, 1, v4
	v_lshl_add_u64 v[4:5], v[2:3], 0, v[156:157]
	global_load_dwordx4 v[94:97], v[4:5], off
	v_cndmask_b32_e64 v18, v213, 0, vcc
	v_add3_u32 v17, 0, v17, v18
	v_add3_u32 v17, v17, v9, v12
	v_mov_b32_e32 v144, v17
	v_add_u32_e32 v4, 0x600, v11
	v_bfe_u32 v17, v4, 9, 2
	v_cmp_gt_u32_e32 vcc, s76, v4
	v_lshlrev_b32_e32 v5, 6, v17
	v_mul_u32_u24_e32 v17, 0x6c00, v17
	v_cndmask_b32_e32 v4, v200, v201, vcc
	v_or3_b32 v4, v5, v4, v8
	v_lshlrev_b32_e32 v156, 1, v4
	v_lshl_add_u64 v[4:5], v[2:3], 0, v[156:157]
	global_load_dwordx4 v[98:101], v[4:5], off
	v_cndmask_b32_e64 v18, v213, 0, vcc
	v_add3_u32 v17, 0, v17, v18
	v_add3_u32 v17, v17, v9, v12
	v_cmp_lt_u32_e32 vcc, s6, v11
	v_mov_b32_e32 v145, v17
	v_cndmask_b32_e32 v4, v200, v201, vcc
	v_or3_b32 v4, v8, v4, v16
	v_lshlrev_b32_e32 v156, 1, v4
	v_lshl_add_u64 v[4:5], v[2:3], 0, v[156:157]
	global_load_dwordx4 v[102:105], v[4:5], off
	v_cndmask_b32_e64 v16, v213, 0, vcc
	v_add_u32_e32 v15, v15, v16
	v_add3_u32 v15, v15, v9, v12
	v_mov_b32_e32 v146, v15
	v_add_u32_e32 v4, 0xa00, v11
	v_bfe_u32 v15, v4, 9, 2
	v_cmp_gt_u32_e32 vcc, s76, v4
	v_lshlrev_b32_e32 v5, 6, v15
	v_mul_u32_u24_e32 v15, 0x6c00, v15
	v_cndmask_b32_e32 v4, v200, v201, vcc
	v_or3_b32 v4, v5, v4, v8
	v_lshlrev_b32_e32 v156, 1, v4
	v_lshl_add_u64 v[4:5], v[2:3], 0, v[156:157]
	global_load_dwordx4 v[106:109], v[4:5], off
	v_cndmask_b32_e64 v16, v213, 0, vcc
	v_add3_u32 v15, 0, v15, v16
	v_add3_u32 v15, v15, v9, v12
	v_mov_b32_e32 v147, v15
	v_add_u32_e32 v4, 0xc00, v11
	v_bfe_u32 v15, v4, 9, 2
	v_cmp_gt_u32_e32 vcc, s76, v4
	v_lshlrev_b32_e32 v5, 6, v15
	v_mul_u32_u24_e32 v15, 0x6c00, v15
	v_cndmask_b32_e32 v4, v200, v201, vcc
	v_or3_b32 v4, v5, v4, v8
	v_lshlrev_b32_e32 v156, 1, v4
	v_lshl_add_u64 v[4:5], v[2:3], 0, v[156:157]
	global_load_dwordx4 v[110:113], v[4:5], off
	v_cndmask_b32_e64 v16, v213, 0, vcc
	v_add3_u32 v15, 0, v15, v16
	v_add3_u32 v15, v15, v9, v12
	v_mov_b32_e32 v148, v15
	v_add_u32_e32 v4, 0xe00, v11
	v_bfe_u32 v6, v4, 9, 2
	v_cmp_gt_u32_e32 vcc, s76, v4
	v_lshlrev_b32_e32 v5, 6, v6
	v_mul_u32_u24_e32 v6, 0x6c00, v6
	v_cndmask_b32_e32 v4, v200, v201, vcc
	v_or3_b32 v4, v5, v4, v8
	v_lshlrev_b32_e32 v156, 1, v4
	v_lshl_add_u64 v[2:3], v[2:3], 0, v[156:157]
	global_load_dwordx4 v[120:123], v[2:3], off
	v_cndmask_b32_e64 v7, v213, 0, vcc
	v_add3_u32 v6, 0, v6, v7
	v_add3_u32 v6, v6, v9, v12
	v_lshl_add_u32 v12, s1, 2, v13
	v_and_b32_e32 v15, 63, v11
	v_mov_b32_e32 v149, v6
	v_lshlrev_b32_e32 v2, 1, v11
	v_ashrrev_i32_e32 v3, 3, v11
	v_and_b32_e32 v2, 14, v2
	v_add_u32_e32 v4, s0, v3
	v_mad_i64_i32 v[0:1], s[0:1], v4, s97, v[0:1]
	v_lshlrev_b32_e32 v156, 1, v2
	v_lshl_add_u64 v[0:1], v[0:1], 0, v[156:157]
	v_add_co_u32_e32 v0, vcc, s33, v0
	v_lshlrev_b32_e32 v3, 6, v3
	s_nop 0
	v_addc_co_u32_e32 v1, vcc, 0, v1, vcc
	global_load_dword v1, v[0:1], off offset:2560
	v_lshlrev_b32_e32 v2, 2, v2
	v_add3_u32 v2, s98, v3, v2
	v_lshlrev_b32_e32 v156, 2, v15
	s_waitcnt vmcnt(0)
	ds_write_b128 v142, v[86:89]
	ds_write_b128 v143, v[90:93]
	ds_write_b128 v144, v[94:97]
	ds_write_b128 v145, v[98:101]
	ds_write_b128 v146, v[102:105]
	ds_write_b128 v147, v[106:109]
	ds_write_b128 v148, v[110:113]
	ds_write_b128 v149, v[120:123]
	v_lshlrev_b32_e32 v0, 16, v1
	v_and_b32_e32 v1, 0xffff0000, v1
	ds_write_b64 v2, v[0:1]
	v_lshl_or_b32 v0, v13, 6, v15
	v_ashrrev_i32_e32 v1, 31, v0
	v_lshlrev_b64 v[26:27], 2, v[0:1]
	v_lshl_add_u64 v[2:3], s[2:3], 0, v[26:27]
	v_add_co_u32_e32 v4, vcc, s33, v2
	global_load_dword v21, v[2:3], off
	global_load_dword v22, v[2:3], off offset:1024
	global_load_dword v23, v[2:3], off offset:2048
	global_load_dword v24, v[2:3], off offset:3072
	v_addc_co_u32_e32 v5, vcc, 0, v3, vcc
	v_add_co_u32_e32 v28, vcc, s88, v2
	v_lshl_add_u64 v[26:27], s[20:21], 0, v[26:27]
	s_nop 0
	v_addc_co_u32_e32 v29, vcc, 0, v3, vcc
	global_load_dword v17, v[28:29], off offset:-4096
	global_load_dword v18, v[4:5], off offset:1024
	global_load_dword v19, v[4:5], off offset:2048
	global_load_dword v20, v[4:5], off offset:3072
	global_load_dword v6, v[28:29], off
	global_load_dword v7, v[28:29], off offset:1024
	global_load_dword v8, v[28:29], off offset:2048
	global_load_dword v9, v[28:29], off offset:3072
	v_add_co_u32_e32 v28, vcc, s99, v2
	s_nop 1
	v_addc_co_u32_e32 v29, vcc, 0, v3, vcc
	global_load_dword v2, v[28:29], off
	global_load_dword v3, v[28:29], off offset:1024
	global_load_dword v4, v[28:29], off offset:2048
	global_load_dword v5, v[28:29], off offset:3072
	global_load_dword v16, v[26:27], off
	v_lshl_add_u32 v26, v10, 11, s98
	s_waitcnt lgkmcnt(0)
	s_barrier
; DI float log_sigmoid_fast(float x) { return fminf(x, 0.f) - __logf(1.0f + __expf(-fabsf(x))); }
; template <int MODE>
; DI void gla4_unit(const bf16_t* z, float* ST, float* DEC, bf16_t* Y, const float* aw_g, const float* ab_g, const float* ng, ldsp lds, int tid, int u) {
;     ...
;     float bc[32];
;     {
;         float run = 0.f;
; #pragma unroll
;         for (int i = 0; i < 32; ++i) {
;             const int t = 32 * half + i;
;             float al = ab;
; #pragma unroll
;             for (int r = 0; r < 16; ++r) al += alr[t * 16 + r] * aw[r];
;             run += log_sigmoid_fast(al) * (1.0f / 16.0f);
;             bc[i] = run;
;         }
;         tot[half * 256 + hd * 64 + d] = run;
;     }
	ds_read_b128 v[28:31], v26
	ds_read_b128 v[32:35], v26 offset:16
	ds_read_b128 v[36:39], v26 offset:32
	ds_read_b128 v[40:43], v26 offset:48
	s_waitcnt vmcnt(0) lgkmcnt(3)
	v_fma_f32 v1, v21, v28, v16
	v_fmac_f32_e32 v1, v22, v29
	v_fmac_f32_e32 v1, v23, v30
	v_fmac_f32_e32 v1, v24, v31
	s_waitcnt lgkmcnt(2)
	v_fmac_f32_e32 v1, v17, v32
	v_fmac_f32_e32 v1, v18, v33
	v_fmac_f32_e32 v1, v19, v34
	v_fmac_f32_e32 v1, v20, v35
	s_waitcnt lgkmcnt(1)
	v_fmac_f32_e32 v1, v6, v36
	v_fmac_f32_e32 v1, v7, v37
	v_fmac_f32_e32 v1, v8, v38
	v_fmac_f32_e32 v1, v9, v39
	s_waitcnt lgkmcnt(0)
	v_fmac_f32_e32 v1, v2, v40
	v_fmac_f32_e32 v1, v3, v41
	v_pk_mul_f32 v[28:29], v[4:5], v[42:43]
	s_nop 0
	v_add_f32_e32 v1, v1, v28
	v_add_f32_e32 v1, v1, v29
	v_min_f32_e32 v25, 0, v1
	v_mul_f32_e64 v1, |v1|, s46
	v_exp_f32_e32 v1, v1
	ds_read_b128 v[28:31], v26 offset:64
	v_add_f32_e32 v1, 1.0, v1
	v_cmp_gt_f32_e32 vcc, s47, v1
	s_nop 1
	v_cndmask_b32_e64 v27, 0, 32, vcc
	v_ldexp_f32 v1, v1, v27
	v_log_f32_e32 v1, v1
	s_nop 0
	v_mul_f32_e32 v27, 0x3f317217, v1
	v_fma_f32 v27, v1, s4, -v27
	v_fmac_f32_e32 v27, 0x3377d1cf, v1
	v_fmac_f32_e32 v27, 0x3f317217, v1
	v_cmp_lt_f32_e64 s[0:1], |v1|, s90
	s_nop 1
	v_cndmask_b32_e64 v1, v1, v27, s[0:1]
	v_cndmask_b32_e32 v27, 0, v203, vcc
	v_sub_f32_e32 v1, v1, v27
	v_sub_f32_e32 v1, v25, v1
	v_fma_f32 v25, v1, s79, 0
	s_waitcnt lgkmcnt(0)
	v_fma_f32 v1, v21, v28, v16
	v_fmac_f32_e32 v1, v22, v29
	v_fmac_f32_e32 v1, v23, v30
	v_fmac_f32_e32 v1, v24, v31
	ds_read_b128 v[28:31], v26 offset:80
	s_waitcnt lgkmcnt(0)
	v_fmac_f32_e32 v1, v17, v28
	v_fmac_f32_e32 v1, v18, v29
	v_fmac_f32_e32 v1, v19, v30
	v_fmac_f32_e32 v1, v20, v31
	ds_read_b128 v[28:31], v26 offset:96
	s_waitcnt lgkmcnt(0)
	v_fmac_f32_e32 v1, v6, v28
	v_fmac_f32_e32 v1, v7, v29
	v_fmac_f32_e32 v1, v8, v30
	v_fmac_f32_e32 v1, v9, v31
	ds_read_b128 v[28:31], v26 offset:112
	s_waitcnt lgkmcnt(0)
	v_fmac_f32_e32 v1, v2, v28
	v_fmac_f32_e32 v1, v3, v29
	v_pk_mul_f32 v[28:29], v[4:5], v[30:31]
	s_nop 0
	v_add_f32_e32 v1, v1, v28
	v_add_f32_e32 v1, v1, v29
	v_min_f32_e32 v27, 0, v1
	v_mul_f32_e64 v1, |v1|, s46
	v_exp_f32_e32 v1, v1
	s_nop 0
	v_add_f32_e32 v1, 1.0, v1
	v_cmp_gt_f32_e32 vcc, s47, v1
	s_nop 1
	v_cndmask_b32_e64 v28, 0, 32, vcc
	v_ldexp_f32 v1, v1, v28
	v_log_f32_e32 v1, v1
	s_nop 0
	v_mul_f32_e32 v28, 0x3f317217, v1
	v_fma_f32 v28, v1, s4, -v28
	v_fmac_f32_e32 v28, 0x3377d1cf, v1
	v_fmac_f32_e32 v28, 0x3f317217, v1
	v_cmp_lt_f32_e64 s[0:1], |v1|, s90
	s_nop 1
	v_cndmask_b32_e64 v1, v1, v28, s[0:1]
	v_cndmask_b32_e32 v28, 0, v203, vcc
	v_sub_f32_e32 v1, v1, v28
	ds_read_b128 v[28:31], v26 offset:128
	v_sub_f32_e32 v1, v27, v1
	v_fmamk_f32 v27, v1, 0x3d800000, v25
	s_waitcnt lgkmcnt(0)
	v_fma_f32 v1, v21, v28, v16
	v_fmac_f32_e32 v1, v22, v29
	v_fmac_f32_e32 v1, v23, v30
	v_fmac_f32_e32 v1, v24, v31
	ds_read_b128 v[28:31], v26 offset:144
	s_waitcnt lgkmcnt(0)
	v_fmac_f32_e32 v1, v17, v28
	v_fmac_f32_e32 v1, v18, v29
	v_fmac_f32_e32 v1, v19, v30
	v_fmac_f32_e32 v1, v20, v31
	ds_read_b128 v[28:31], v26 offset:160
	s_waitcnt lgkmcnt(0)
	v_fmac_f32_e32 v1, v6, v28
	v_fmac_f32_e32 v1, v7, v29
	v_fmac_f32_e32 v1, v8, v30
	v_fmac_f32_e32 v1, v9, v31
	ds_read_b128 v[28:31], v26 offset:176
	s_waitcnt lgkmcnt(0)
	v_pk_mul_f32 v[28:29], v[2:3], v[28:29]
	s_nop 0
	v_add_f32_e32 v1, v1, v28
	v_add_f32_e32 v1, v1, v29
	v_pk_mul_f32 v[28:29], v[4:5], v[30:31]
	ds_read_b128 v[30:33], v26 offset:192
	v_add_f32_e32 v1, v1, v28
	v_add_f32_e32 v1, v1, v29
	v_min_f32_e32 v28, 0, v1
	v_mul_f32_e64 v1, |v1|, s46
	v_exp_f32_e32 v1, v1
	s_nop 0
	v_add_f32_e32 v1, 1.0, v1
	v_cmp_gt_f32_e32 vcc, s47, v1
	s_nop 1
	v_cndmask_b32_e64 v29, 0, 32, vcc
	v_ldexp_f32 v1, v1, v29
	v_log_f32_e32 v1, v1
	s_nop 0
	v_mul_f32_e32 v29, 0x3f317217, v1
	v_fma_f32 v29, v1, s4, -v29
	v_fmac_f32_e32 v29, 0x3377d1cf, v1
	v_fmac_f32_e32 v29, 0x3f317217, v1
	v_cmp_lt_f32_e64 s[0:1], |v1|, s90
	s_nop 1
	v_cndmask_b32_e64 v1, v1, v29, s[0:1]
	v_cndmask_b32_e32 v29, 0, v203, vcc
	v_sub_f32_e32 v1, v1, v29
	v_sub_f32_e32 v1, v28, v1
	v_fmamk_f32 v28, v1, 0x3d800000, v27
	s_waitcnt lgkmcnt(0)
	v_fma_f32 v1, v21, v30, v16
	v_fmac_f32_e32 v1, v22, v31
	v_fmac_f32_e32 v1, v23, v32
	v_fmac_f32_e32 v1, v24, v33
	ds_read_b128 v[30:33], v26 offset:208
	s_waitcnt lgkmcnt(0)
	v_fmac_f32_e32 v1, v17, v30
	v_fmac_f32_e32 v1, v18, v31
	v_fmac_f32_e32 v1, v19, v32
	v_fmac_f32_e32 v1, v20, v33
	ds_read_b128 v[30:33], v26 offset:224
	s_waitcnt lgkmcnt(0)
	v_fmac_f32_e32 v1, v6, v30
	v_fmac_f32_e32 v1, v7, v31
	v_fmac_f32_e32 v1, v8, v32
	v_fmac_f32_e32 v1, v9, v33
	ds_read_b128 v[30:33], v26 offset:240
	s_waitcnt lgkmcnt(0)
	v_pk_mul_f32 v[30:31], v[2:3], v[30:31]
	s_nop 0
	v_add_f32_e32 v1, v1, v30
	v_add_f32_e32 v1, v1, v31
	v_pk_mul_f32 v[30:31], v[4:5], v[32:33]
	s_nop 0
	v_add_f32_e32 v1, v1, v30
	v_add_f32_e32 v1, v1, v31
	v_min_f32_e32 v29, 0, v1
	v_mul_f32_e64 v1, |v1|, s46
	v_exp_f32_e32 v1, v1
	s_nop 0
	v_add_f32_e32 v1, 1.0, v1
	v_cmp_gt_f32_e32 vcc, s47, v1
	s_nop 1
	v_cndmask_b32_e64 v30, 0, 32, vcc
	v_ldexp_f32 v1, v1, v30
	v_log_f32_e32 v1, v1
	s_nop 0
	v_mul_f32_e32 v30, 0x3f317217, v1
	v_fma_f32 v30, v1, s4, -v30
	v_fmac_f32_e32 v30, 0x3377d1cf, v1
	v_fmac_f32_e32 v30, 0x3f317217, v1
	v_cmp_lt_f32_e64 s[0:1], |v1|, s90
	s_nop 1
	v_cndmask_b32_e64 v1, v1, v30, s[0:1]
	v_cndmask_b32_e32 v30, 0, v203, vcc
	v_sub_f32_e32 v1, v1, v30
	ds_read_b128 v[30:33], v26 offset:256
	v_sub_f32_e32 v1, v29, v1
	v_fmamk_f32 v29, v1, 0x3d800000, v28
	s_waitcnt lgkmcnt(0)
	v_fma_f32 v1, v21, v30, v16
	v_fmac_f32_e32 v1, v22, v31
	v_fmac_f32_e32 v1, v23, v32
	v_fmac_f32_e32 v1, v24, v33
	ds_read_b128 v[30:33], v26 offset:272
	s_waitcnt lgkmcnt(0)
; DI float log_sigmoid_fast(float x) { return fminf(x, 0.f) - __logf(1.0f + __expf(-fabsf(x))); }
; template <int MODE>
; DI void gla4_unit(const bf16_t* z, float* ST, float* DEC, bf16_t* Y, const float* aw_g, const float* ab_g, const float* ng, ldsp lds, int tid, int u) {
;     ...
;         for (int i = 0; i < 32; ++i) {
;             const int t = 32 * half + i;
;             float al = ab;
; #pragma unroll
;             for (int r = 0; r < 16; ++r) al += alr[t * 16 + r] * aw[r];
;             run += log_sigmoid_fast(al) * (1.0f / 16.0f);
;             bc[i] = run;
;         }
	v_fmac_f32_e32 v1, v17, v30
	v_fmac_f32_e32 v1, v18, v31
	v_fmac_f32_e32 v1, v19, v32
	v_fmac_f32_e32 v1, v20, v33
	ds_read_b128 v[30:33], v26 offset:288
	s_waitcnt lgkmcnt(0)
	v_fmac_f32_e32 v1, v6, v30
	v_fmac_f32_e32 v1, v7, v31
	v_pk_mul_f32 v[30:31], v[8:9], v[32:33]
	s_nop 0
	v_add_f32_e32 v1, v1, v30
	v_add_f32_e32 v1, v1, v31
	ds_read_b128 v[30:33], v26 offset:304
	s_waitcnt lgkmcnt(0)
	v_pk_mul_f32 v[30:31], v[2:3], v[30:31]
	s_nop 0
	v_add_f32_e32 v1, v1, v30
	v_add_f32_e32 v1, v1, v31
	v_pk_mul_f32 v[30:31], v[4:5], v[32:33]
	ds_read_b128 v[32:35], v26 offset:320
	v_add_f32_e32 v1, v1, v30
	v_add_f32_e32 v1, v1, v31
	v_min_f32_e32 v30, 0, v1
	v_mul_f32_e64 v1, |v1|, s46
	v_exp_f32_e32 v1, v1
	s_nop 0
	v_add_f32_e32 v1, 1.0, v1
	v_cmp_gt_f32_e32 vcc, s47, v1
	s_nop 1
	v_cndmask_b32_e64 v31, 0, 32, vcc
	v_ldexp_f32 v1, v1, v31
	v_log_f32_e32 v1, v1
	s_nop 0
	v_mul_f32_e32 v31, 0x3f317217, v1
	v_fma_f32 v31, v1, s4, -v31
	v_fmac_f32_e32 v31, 0x3377d1cf, v1
	v_fmac_f32_e32 v31, 0x3f317217, v1
	v_cmp_lt_f32_e64 s[0:1], |v1|, s90
	s_nop 1
	v_cndmask_b32_e64 v1, v1, v31, s[0:1]
	v_cndmask_b32_e32 v31, 0, v203, vcc
	v_sub_f32_e32 v1, v1, v31
	v_sub_f32_e32 v1, v30, v1
	v_fmamk_f32 v30, v1, 0x3d800000, v29
	s_waitcnt lgkmcnt(0)
	v_fma_f32 v1, v21, v32, v16
	v_fmac_f32_e32 v1, v22, v33
	v_fmac_f32_e32 v1, v23, v34
	v_fmac_f32_e32 v1, v24, v35
	ds_read_b128 v[32:35], v26 offset:336
	s_waitcnt lgkmcnt(0)
	v_fmac_f32_e32 v1, v17, v32
	v_fmac_f32_e32 v1, v18, v33
	v_fmac_f32_e32 v1, v19, v34
	v_fmac_f32_e32 v1, v20, v35
	ds_read_b128 v[32:35], v26 offset:352
	s_waitcnt lgkmcnt(0)
	v_fmac_f32_e32 v1, v6, v32
	v_fmac_f32_e32 v1, v7, v33
	v_pk_mul_f32 v[32:33], v[8:9], v[34:35]
	s_nop 0
	v_add_f32_e32 v1, v1, v32
	v_add_f32_e32 v1, v1, v33
	ds_read_b128 v[32:35], v26 offset:368
	s_waitcnt lgkmcnt(0)
	v_pk_mul_f32 v[32:33], v[2:3], v[32:33]
	s_nop 0
	v_add_f32_e32 v1, v1, v32
	v_add_f32_e32 v1, v1, v33
	v_pk_mul_f32 v[32:33], v[4:5], v[34:35]
	s_nop 0
	v_add_f32_e32 v1, v1, v32
	v_add_f32_e32 v1, v1, v33
	v_min_f32_e32 v31, 0, v1
	v_mul_f32_e64 v1, |v1|, s46
	v_exp_f32_e32 v1, v1
	s_nop 0
	v_add_f32_e32 v1, 1.0, v1
	v_cmp_gt_f32_e32 vcc, s47, v1
	s_nop 1
	v_cndmask_b32_e64 v32, 0, 32, vcc
	v_ldexp_f32 v1, v1, v32
	v_log_f32_e32 v1, v1
	s_nop 0
	v_mul_f32_e32 v32, 0x3f317217, v1
	v_fma_f32 v32, v1, s4, -v32
	v_fmac_f32_e32 v32, 0x3377d1cf, v1
	v_fmac_f32_e32 v32, 0x3f317217, v1
	v_cmp_lt_f32_e64 s[0:1], |v1|, s90
	s_nop 1
	v_cndmask_b32_e64 v1, v1, v32, s[0:1]
	v_cndmask_b32_e32 v32, 0, v203, vcc
	v_sub_f32_e32 v1, v1, v32
	ds_read_b128 v[32:35], v26 offset:384
	v_sub_f32_e32 v1, v31, v1
	v_fmamk_f32 v31, v1, 0x3d800000, v30
	s_waitcnt lgkmcnt(0)
	v_fma_f32 v1, v21, v32, v16
	v_fmac_f32_e32 v1, v22, v33
	v_fmac_f32_e32 v1, v23, v34
	v_fmac_f32_e32 v1, v24, v35
	ds_read_b128 v[32:35], v26 offset:400
	s_waitcnt lgkmcnt(0)
	v_fmac_f32_e32 v1, v17, v32
	v_fmac_f32_e32 v1, v18, v33
	v_fmac_f32_e32 v1, v19, v34
	v_fmac_f32_e32 v1, v20, v35
	ds_read_b128 v[32:35], v26 offset:416
	s_waitcnt lgkmcnt(0)
	v_pk_mul_f32 v[32:33], v[6:7], v[32:33]
	s_nop 0
	v_add_f32_e32 v1, v1, v32
	v_add_f32_e32 v1, v1, v33
	v_pk_mul_f32 v[32:33], v[8:9], v[34:35]
	s_nop 0
	v_add_f32_e32 v1, v1, v32
	v_add_f32_e32 v1, v1, v33
	ds_read_b128 v[32:35], v26 offset:432
	s_waitcnt lgkmcnt(0)
	v_pk_mul_f32 v[32:33], v[2:3], v[32:33]
	s_nop 0
	v_add_f32_e32 v1, v1, v32
	v_add_f32_e32 v1, v1, v33
	v_pk_mul_f32 v[32:33], v[4:5], v[34:35]
	s_nop 0
	v_add_f32_e32 v1, v1, v32
	v_add_f32_e32 v1, v1, v33
	v_min_f32_e32 v32, 0, v1
	v_mul_f32_e64 v1, |v1|, s46
	v_exp_f32_e32 v1, v1
	s_nop 0
	v_add_f32_e32 v1, 1.0, v1
	v_cmp_gt_f32_e32 vcc, s47, v1
	s_nop 1
	v_cndmask_b32_e64 v33, 0, 32, vcc
	v_ldexp_f32 v1, v1, v33
	v_log_f32_e32 v1, v1
	s_nop 0
	v_mul_f32_e32 v33, 0x3f317217, v1
	v_fma_f32 v33, v1, s4, -v33
	v_fmac_f32_e32 v33, 0x3377d1cf, v1
	v_fmac_f32_e32 v33, 0x3f317217, v1
	v_cmp_lt_f32_e64 s[0:1], |v1|, s90
	s_nop 1
	v_cndmask_b32_e64 v1, v1, v33, s[0:1]
	v_cndmask_b32_e32 v33, 0, v203, vcc
	v_sub_f32_e32 v1, v1, v33
	v_sub_f32_e32 v1, v32, v1
	ds_read_b128 v[32:35], v26 offset:448
	v_fmamk_f32 v1, v1, 0x3d800000, v31
	s_waitcnt lgkmcnt(0)
	v_fma_f32 v36, v21, v32, v16
	v_fmac_f32_e32 v36, v22, v33
	v_fmac_f32_e32 v36, v23, v34
	v_fmac_f32_e32 v36, v24, v35
	ds_read_b128 v[32:35], v26 offset:464
	s_waitcnt lgkmcnt(0)
	v_fmac_f32_e32 v36, v17, v32
	v_fmac_f32_e32 v36, v18, v33
	v_fmac_f32_e32 v36, v19, v34
	v_fmac_f32_e32 v36, v20, v35
	ds_read_b128 v[32:35], v26 offset:480
	s_waitcnt lgkmcnt(0)
	v_fmac_f32_e32 v36, v6, v32
	v_fmac_f32_e32 v36, v7, v33
	v_fmac_f32_e32 v36, v8, v34
	v_fmac_f32_e32 v36, v9, v35
	ds_read_b128 v[32:35], v26 offset:496
	s_waitcnt lgkmcnt(0)
	v_fmac_f32_e32 v36, v2, v32
	v_fmac_f32_e32 v36, v3, v33
	v_pk_mul_f32 v[32:33], v[4:5], v[34:35]
	s_nop 0
	v_add_f32_e32 v32, v36, v32
	v_add_f32_e32 v32, v32, v33
	v_min_f32_e32 v33, 0, v32
	v_mul_f32_e64 v32, |v32|, s46
	v_exp_f32_e32 v32, v32
	s_nop 0
	v_add_f32_e32 v32, 1.0, v32
	v_cmp_gt_f32_e32 vcc, s47, v32
	s_nop 1
	v_cndmask_b32_e64 v34, 0, 32, vcc
	v_ldexp_f32 v32, v32, v34
	v_log_f32_e32 v32, v32
	s_nop 0
	v_mul_f32_e32 v34, 0x3f317217, v32
	v_fma_f32 v34, v32, s4, -v34
	v_fmac_f32_e32 v34, 0x3377d1cf, v32
	v_fmac_f32_e32 v34, 0x3f317217, v32
	v_cmp_lt_f32_e64 s[0:1], |v32|, s90
	s_nop 1
	v_cndmask_b32_e64 v32, v32, v34, s[0:1]
	v_cndmask_b32_e32 v34, 0, v203, vcc
	v_sub_f32_e32 v32, v32, v34
	ds_read_b128 v[34:37], v26 offset:512
	v_sub_f32_e32 v32, v33, v32
	v_fmamk_f32 v32, v32, 0x3d800000, v1
	s_waitcnt lgkmcnt(0)
; DI float log_sigmoid_fast(float x) { return fminf(x, 0.f) - __logf(1.0f + __expf(-fabsf(x))); }
; template <int MODE>
; DI void gla4_unit(const bf16_t* z, float* ST, float* DEC, bf16_t* Y, const float* aw_g, const float* ab_g, const float* ng, ldsp lds, int tid, int u) {
;     ...
;         for (int i = 0; i < 32; ++i) {
;             const int t = 32 * half + i;
;             float al = ab;
; #pragma unroll
;             for (int r = 0; r < 16; ++r) al += alr[t * 16 + r] * aw[r];
;             run += log_sigmoid_fast(al) * (1.0f / 16.0f);
;             bc[i] = run;
;         }
	v_fma_f32 v33, v21, v34, v16
	v_fmac_f32_e32 v33, v22, v35
	v_fmac_f32_e32 v33, v23, v36
	v_fmac_f32_e32 v33, v24, v37
	ds_read_b128 v[34:37], v26 offset:528
	s_waitcnt lgkmcnt(0)
	v_fmac_f32_e32 v33, v17, v34
	v_fmac_f32_e32 v33, v18, v35
	v_fmac_f32_e32 v33, v19, v36
	v_fmac_f32_e32 v33, v20, v37
	ds_read_b128 v[34:37], v26 offset:544
	s_waitcnt lgkmcnt(0)
	v_fmac_f32_e32 v33, v6, v34
	v_fmac_f32_e32 v33, v7, v35
	v_fmac_f32_e32 v33, v8, v36
	v_fmac_f32_e32 v33, v9, v37
	ds_read_b128 v[34:37], v26 offset:560
	s_waitcnt lgkmcnt(0)
	v_fmac_f32_e32 v33, v2, v34
	v_fmac_f32_e32 v33, v3, v35
	v_pk_mul_f32 v[34:35], v[4:5], v[36:37]
	s_nop 0
	v_add_f32_e32 v33, v33, v34
	v_add_f32_e32 v33, v33, v35
	v_min_f32_e32 v34, 0, v33
	v_mul_f32_e64 v33, |v33|, s46
	v_exp_f32_e32 v33, v33
	s_nop 0
	v_add_f32_e32 v33, 1.0, v33
	v_cmp_gt_f32_e32 vcc, s47, v33
	s_nop 1
	v_cndmask_b32_e64 v35, 0, 32, vcc
	v_ldexp_f32 v33, v33, v35
	v_log_f32_e32 v33, v33
	s_nop 0
	v_mul_f32_e32 v35, 0x3f317217, v33
	v_fma_f32 v35, v33, s4, -v35
	v_fmac_f32_e32 v35, 0x3377d1cf, v33
	v_fmac_f32_e32 v35, 0x3f317217, v33
	v_cmp_lt_f32_e64 s[0:1], |v33|, s90
	s_nop 1
	v_cndmask_b32_e64 v33, v33, v35, s[0:1]
	v_cndmask_b32_e32 v35, 0, v203, vcc
	v_sub_f32_e32 v33, v33, v35
	v_sub_f32_e32 v33, v34, v33
	ds_read_b128 v[34:37], v26 offset:576
	v_fmamk_f32 v33, v33, 0x3d800000, v32
	s_waitcnt lgkmcnt(0)
	v_fma_f32 v38, v21, v34, v16
	v_fmac_f32_e32 v38, v22, v35
	v_fmac_f32_e32 v38, v23, v36
	v_fmac_f32_e32 v38, v24, v37
	ds_read_b128 v[34:37], v26 offset:592
	s_waitcnt lgkmcnt(0)
	v_fmac_f32_e32 v38, v17, v34
	v_fmac_f32_e32 v38, v18, v35
	v_fmac_f32_e32 v38, v19, v36
	v_fmac_f32_e32 v38, v20, v37
	ds_read_b128 v[34:37], v26 offset:608
	s_waitcnt lgkmcnt(0)
	v_fmac_f32_e32 v38, v6, v34
	v_fmac_f32_e32 v38, v7, v35
	v_fmac_f32_e32 v38, v8, v36
	v_fmac_f32_e32 v38, v9, v37
	ds_read_b128 v[34:37], v26 offset:624
	s_waitcnt lgkmcnt(0)
	v_fmac_f32_e32 v38, v2, v34
	v_fmac_f32_e32 v38, v3, v35
	v_pk_mul_f32 v[34:35], v[4:5], v[36:37]
	s_nop 0
	v_add_f32_e32 v34, v38, v34
	v_add_f32_e32 v34, v34, v35
	v_min_f32_e32 v35, 0, v34
	v_mul_f32_e64 v34, |v34|, s46
	v_exp_f32_e32 v34, v34
	s_nop 0
	v_add_f32_e32 v34, 1.0, v34
	v_cmp_gt_f32_e32 vcc, s47, v34
	s_nop 1
	v_cndmask_b32_e64 v36, 0, 32, vcc
	v_ldexp_f32 v34, v34, v36
	v_log_f32_e32 v34, v34
	s_nop 0
	v_mul_f32_e32 v36, 0x3f317217, v34
	v_fma_f32 v36, v34, s4, -v36
	v_fmac_f32_e32 v36, 0x3377d1cf, v34
	v_fmac_f32_e32 v36, 0x3f317217, v34
	v_cmp_lt_f32_e64 s[0:1], |v34|, s90
	s_nop 1
	v_cndmask_b32_e64 v34, v34, v36, s[0:1]
	v_cndmask_b32_e32 v36, 0, v203, vcc
	v_sub_f32_e32 v34, v34, v36
	ds_read_b128 v[36:39], v26 offset:640
	v_sub_f32_e32 v34, v35, v34
	v_fmamk_f32 v34, v34, 0x3d800000, v33
	s_waitcnt lgkmcnt(0)
	v_fma_f32 v35, v21, v36, v16
	v_fmac_f32_e32 v35, v22, v37
	v_fmac_f32_e32 v35, v23, v38
	v_fmac_f32_e32 v35, v24, v39
	ds_read_b128 v[36:39], v26 offset:656
	s_waitcnt lgkmcnt(0)
	v_fmac_f32_e32 v35, v17, v36
	v_fmac_f32_e32 v35, v18, v37
	v_fmac_f32_e32 v35, v19, v38
	v_fmac_f32_e32 v35, v20, v39
	ds_read_b128 v[36:39], v26 offset:672
	s_waitcnt lgkmcnt(0)
	v_fmac_f32_e32 v35, v6, v36
	v_fmac_f32_e32 v35, v7, v37
	v_fmac_f32_e32 v35, v8, v38
	v_fmac_f32_e32 v35, v9, v39
	ds_read_b128 v[36:39], v26 offset:688
	s_waitcnt lgkmcnt(0)
	v_fmac_f32_e32 v35, v2, v36
	v_fmac_f32_e32 v35, v3, v37
	v_pk_mul_f32 v[36:37], v[4:5], v[38:39]
	s_nop 0
	v_add_f32_e32 v35, v35, v36
	v_add_f32_e32 v35, v35, v37
	v_min_f32_e32 v36, 0, v35
	v_mul_f32_e64 v35, |v35|, s46
	v_exp_f32_e32 v35, v35
	s_nop 0
	v_add_f32_e32 v35, 1.0, v35
	v_cmp_gt_f32_e32 vcc, s47, v35
	s_nop 1
	v_cndmask_b32_e64 v37, 0, 32, vcc
	v_ldexp_f32 v35, v35, v37
	v_log_f32_e32 v35, v35
	s_nop 0
	v_mul_f32_e32 v37, 0x3f317217, v35
	v_fma_f32 v37, v35, s4, -v37
	v_fmac_f32_e32 v37, 0x3377d1cf, v35
	v_fmac_f32_e32 v37, 0x3f317217, v35
	v_cmp_lt_f32_e64 s[0:1], |v35|, s90
	s_nop 1
	v_cndmask_b32_e64 v35, v35, v37, s[0:1]
	v_cndmask_b32_e32 v37, 0, v203, vcc
	v_sub_f32_e32 v35, v35, v37
	v_sub_f32_e32 v35, v36, v35
	ds_read_b128 v[36:39], v26 offset:704
	v_fmamk_f32 v35, v35, 0x3d800000, v34
	s_waitcnt lgkmcnt(0)
	v_fma_f32 v40, v21, v36, v16
	v_fmac_f32_e32 v40, v22, v37
	v_fmac_f32_e32 v40, v23, v38
	v_fmac_f32_e32 v40, v24, v39
	ds_read_b128 v[36:39], v26 offset:720
	s_waitcnt lgkmcnt(0)
	v_fmac_f32_e32 v40, v17, v36
	v_fmac_f32_e32 v40, v18, v37
	v_fmac_f32_e32 v40, v19, v38
	v_fmac_f32_e32 v40, v20, v39
	ds_read_b128 v[36:39], v26 offset:736
	s_waitcnt lgkmcnt(0)
	v_fmac_f32_e32 v40, v6, v36
	v_fmac_f32_e32 v40, v7, v37
	v_fmac_f32_e32 v40, v8, v38
	v_fmac_f32_e32 v40, v9, v39
	ds_read_b128 v[36:39], v26 offset:752
	s_waitcnt lgkmcnt(0)
	v_fmac_f32_e32 v40, v2, v36
	v_fmac_f32_e32 v40, v3, v37
	v_pk_mul_f32 v[36:37], v[4:5], v[38:39]
	s_nop 0
	v_add_f32_e32 v36, v40, v36
	v_add_f32_e32 v36, v36, v37
	v_min_f32_e32 v37, 0, v36
	v_mul_f32_e64 v36, |v36|, s46
	v_exp_f32_e32 v36, v36
	s_nop 0
	v_add_f32_e32 v36, 1.0, v36
	v_cmp_gt_f32_e32 vcc, s47, v36
	s_nop 1
	v_cndmask_b32_e64 v38, 0, 32, vcc
	v_ldexp_f32 v36, v36, v38
	v_log_f32_e32 v36, v36
	s_nop 0
	v_mul_f32_e32 v38, 0x3f317217, v36
	v_fma_f32 v38, v36, s4, -v38
	v_fmac_f32_e32 v38, 0x3377d1cf, v36
	v_fmac_f32_e32 v38, 0x3f317217, v36
	v_cmp_lt_f32_e64 s[0:1], |v36|, s90
	s_nop 1
	v_cndmask_b32_e64 v36, v36, v38, s[0:1]
	v_cndmask_b32_e32 v38, 0, v203, vcc
	v_sub_f32_e32 v36, v36, v38
	ds_read_b128 v[38:41], v26 offset:768
	v_sub_f32_e32 v36, v37, v36
	v_fmamk_f32 v36, v36, 0x3d800000, v35
	s_waitcnt lgkmcnt(0)
	v_fma_f32 v37, v21, v38, v16
	v_fmac_f32_e32 v37, v22, v39
	v_fmac_f32_e32 v37, v23, v40
	v_fmac_f32_e32 v37, v24, v41
	ds_read_b128 v[38:41], v26 offset:784
	s_waitcnt lgkmcnt(0)
; DI float log_sigmoid_fast(float x) { return fminf(x, 0.f) - __logf(1.0f + __expf(-fabsf(x))); }
; template <int MODE>
; DI void gla4_unit(const bf16_t* z, float* ST, float* DEC, bf16_t* Y, const float* aw_g, const float* ab_g, const float* ng, ldsp lds, int tid, int u) {
;     ...
;         for (int i = 0; i < 32; ++i) {
;             const int t = 32 * half + i;
;             float al = ab;
; #pragma unroll
;             for (int r = 0; r < 16; ++r) al += alr[t * 16 + r] * aw[r];
;             run += log_sigmoid_fast(al) * (1.0f / 16.0f);
;             bc[i] = run;
;         }
	v_fmac_f32_e32 v37, v17, v38
	v_fmac_f32_e32 v37, v18, v39
	v_fmac_f32_e32 v37, v19, v40
	v_fmac_f32_e32 v37, v20, v41
	ds_read_b128 v[38:41], v26 offset:800
	s_waitcnt lgkmcnt(0)
	v_fmac_f32_e32 v37, v6, v38
	v_fmac_f32_e32 v37, v7, v39
	v_fmac_f32_e32 v37, v8, v40
	v_fmac_f32_e32 v37, v9, v41
	ds_read_b128 v[38:41], v26 offset:816
	s_waitcnt lgkmcnt(0)
	v_fmac_f32_e32 v37, v2, v38
	v_fmac_f32_e32 v37, v3, v39
	v_pk_mul_f32 v[38:39], v[4:5], v[40:41]
	s_nop 0
	v_add_f32_e32 v37, v37, v38
	v_add_f32_e32 v37, v37, v39
	v_min_f32_e32 v38, 0, v37
	v_mul_f32_e64 v37, |v37|, s46
	v_exp_f32_e32 v37, v37
	s_nop 0
	v_add_f32_e32 v37, 1.0, v37
	v_cmp_gt_f32_e32 vcc, s47, v37
	s_nop 1
	v_cndmask_b32_e64 v39, 0, 32, vcc
	v_ldexp_f32 v37, v37, v39
	v_log_f32_e32 v37, v37
	s_nop 0
	v_mul_f32_e32 v39, 0x3f317217, v37
	v_fma_f32 v39, v37, s4, -v39
	v_fmac_f32_e32 v39, 0x3377d1cf, v37
	v_fmac_f32_e32 v39, 0x3f317217, v37
	v_cmp_lt_f32_e64 s[0:1], |v37|, s90
	s_nop 1
	v_cndmask_b32_e64 v37, v37, v39, s[0:1]
	v_cndmask_b32_e32 v39, 0, v203, vcc
	v_sub_f32_e32 v37, v37, v39
	v_sub_f32_e32 v37, v38, v37
	ds_read_b128 v[38:41], v26 offset:832
	v_fmamk_f32 v37, v37, 0x3d800000, v36
	s_waitcnt lgkmcnt(0)
	v_fma_f32 v42, v21, v38, v16
	v_fmac_f32_e32 v42, v22, v39
	v_fmac_f32_e32 v42, v23, v40
	v_fmac_f32_e32 v42, v24, v41
	ds_read_b128 v[38:41], v26 offset:848
	s_waitcnt lgkmcnt(0)
	v_fmac_f32_e32 v42, v17, v38
	v_fmac_f32_e32 v42, v18, v39
	v_fmac_f32_e32 v42, v19, v40
	v_fmac_f32_e32 v42, v20, v41
	ds_read_b128 v[38:41], v26 offset:864
	s_waitcnt lgkmcnt(0)
	v_fmac_f32_e32 v42, v6, v38
	v_fmac_f32_e32 v42, v7, v39
	v_fmac_f32_e32 v42, v8, v40
	v_fmac_f32_e32 v42, v9, v41
	ds_read_b128 v[38:41], v26 offset:880
	s_waitcnt lgkmcnt(0)
	v_fmac_f32_e32 v42, v2, v38
	v_fmac_f32_e32 v42, v3, v39
	v_pk_mul_f32 v[38:39], v[4:5], v[40:41]
	s_nop 0
	v_add_f32_e32 v38, v42, v38
	v_add_f32_e32 v38, v38, v39
	v_min_f32_e32 v39, 0, v38
	v_mul_f32_e64 v38, |v38|, s46
	v_exp_f32_e32 v38, v38
	s_nop 0
	v_add_f32_e32 v38, 1.0, v38
	v_cmp_gt_f32_e32 vcc, s47, v38
	s_nop 1
	v_cndmask_b32_e64 v40, 0, 32, vcc
	v_ldexp_f32 v38, v38, v40
	v_log_f32_e32 v38, v38
	s_nop 0
	v_mul_f32_e32 v40, 0x3f317217, v38
	v_fma_f32 v40, v38, s4, -v40
	v_fmac_f32_e32 v40, 0x3377d1cf, v38
	v_fmac_f32_e32 v40, 0x3f317217, v38
	v_cmp_lt_f32_e64 s[0:1], |v38|, s90
	s_nop 1
	v_cndmask_b32_e64 v38, v38, v40, s[0:1]
	v_cndmask_b32_e32 v40, 0, v203, vcc
	v_sub_f32_e32 v38, v38, v40
	ds_read_b128 v[40:43], v26 offset:896
	v_sub_f32_e32 v38, v39, v38
	v_fmamk_f32 v38, v38, 0x3d800000, v37
	s_waitcnt lgkmcnt(0)
	v_fma_f32 v39, v21, v40, v16
	v_fmac_f32_e32 v39, v22, v41
	v_fmac_f32_e32 v39, v23, v42
	v_fmac_f32_e32 v39, v24, v43
	ds_read_b128 v[40:43], v26 offset:912
	s_waitcnt lgkmcnt(0)
	v_fmac_f32_e32 v39, v17, v40
	v_fmac_f32_e32 v39, v18, v41
	v_fmac_f32_e32 v39, v19, v42
	v_fmac_f32_e32 v39, v20, v43
	ds_read_b128 v[40:43], v26 offset:928
	s_waitcnt lgkmcnt(0)
	v_fmac_f32_e32 v39, v6, v40
	v_fmac_f32_e32 v39, v7, v41
	v_fmac_f32_e32 v39, v8, v42
	v_fmac_f32_e32 v39, v9, v43
	ds_read_b128 v[40:43], v26 offset:944
	s_waitcnt lgkmcnt(0)
	v_fmac_f32_e32 v39, v2, v40
	v_fmac_f32_e32 v39, v3, v41
	v_pk_mul_f32 v[40:41], v[4:5], v[42:43]
	s_nop 0
	v_add_f32_e32 v39, v39, v40
	v_add_f32_e32 v39, v39, v41
	v_min_f32_e32 v40, 0, v39
	v_mul_f32_e64 v39, |v39|, s46
	v_exp_f32_e32 v39, v39
	s_nop 0
	v_add_f32_e32 v39, 1.0, v39
	v_cmp_gt_f32_e32 vcc, s47, v39
	s_nop 1
	v_cndmask_b32_e64 v41, 0, 32, vcc
	v_ldexp_f32 v39, v39, v41
	v_log_f32_e32 v39, v39
	s_nop 0
	v_mul_f32_e32 v41, 0x3f317217, v39
	v_fma_f32 v41, v39, s4, -v41
	v_fmac_f32_e32 v41, 0x3377d1cf, v39
	v_fmac_f32_e32 v41, 0x3f317217, v39
	v_cmp_lt_f32_e64 s[0:1], |v39|, s90
	s_nop 1
	v_cndmask_b32_e64 v39, v39, v41, s[0:1]
	v_cndmask_b32_e32 v41, 0, v203, vcc
	v_sub_f32_e32 v39, v39, v41
	v_sub_f32_e32 v39, v40, v39
	ds_read_b128 v[40:43], v26 offset:960
	v_fmamk_f32 v39, v39, 0x3d800000, v38
	s_waitcnt lgkmcnt(0)
	v_fma_f32 v44, v21, v40, v16
	v_fmac_f32_e32 v44, v22, v41
	v_fmac_f32_e32 v44, v23, v42
	v_fmac_f32_e32 v44, v24, v43
	ds_read_b128 v[40:43], v26 offset:976
	s_waitcnt lgkmcnt(0)
	v_fmac_f32_e32 v44, v17, v40
	v_fmac_f32_e32 v44, v18, v41
	v_fmac_f32_e32 v44, v19, v42
	v_fmac_f32_e32 v44, v20, v43
	ds_read_b128 v[40:43], v26 offset:992
	s_waitcnt lgkmcnt(0)
	v_fmac_f32_e32 v44, v6, v40
	v_fmac_f32_e32 v44, v7, v41
	v_fmac_f32_e32 v44, v8, v42
	v_fmac_f32_e32 v44, v9, v43
	ds_read_b128 v[40:43], v26 offset:1008
	s_waitcnt lgkmcnt(0)
	v_fmac_f32_e32 v44, v2, v40
	v_fmac_f32_e32 v44, v3, v41
	v_pk_mul_f32 v[40:41], v[4:5], v[42:43]
	s_nop 0
	v_add_f32_e32 v40, v44, v40
	v_add_f32_e32 v40, v40, v41
	v_min_f32_e32 v41, 0, v40
	v_mul_f32_e64 v40, |v40|, s46
	v_exp_f32_e32 v40, v40
	s_nop 0
	v_add_f32_e32 v40, 1.0, v40
	v_cmp_gt_f32_e32 vcc, s47, v40
	s_nop 1
	v_cndmask_b32_e64 v42, 0, 32, vcc
	v_ldexp_f32 v40, v40, v42
	v_log_f32_e32 v40, v40
	s_nop 0
	v_mul_f32_e32 v42, 0x3f317217, v40
	v_fma_f32 v42, v40, s4, -v42
	v_fmac_f32_e32 v42, 0x3377d1cf, v40
	v_fmac_f32_e32 v42, 0x3f317217, v40
	v_cmp_lt_f32_e64 s[0:1], |v40|, s90
	s_nop 1
	v_cndmask_b32_e64 v40, v40, v42, s[0:1]
	v_cndmask_b32_e32 v42, 0, v203, vcc
	v_sub_f32_e32 v40, v40, v42
	ds_read_b128 v[42:45], v26 offset:1024
	v_sub_f32_e32 v40, v41, v40
	v_fmamk_f32 v40, v40, 0x3d800000, v39
	s_waitcnt lgkmcnt(0)
	v_fma_f32 v41, v21, v42, v16
	v_fmac_f32_e32 v41, v22, v43
	v_fmac_f32_e32 v41, v23, v44
	v_fmac_f32_e32 v41, v24, v45
	ds_read_b128 v[42:45], v26 offset:1040
	s_waitcnt lgkmcnt(0)
	v_fmac_f32_e32 v41, v17, v42
	v_fmac_f32_e32 v41, v18, v43
	v_fmac_f32_e32 v41, v19, v44
	v_fmac_f32_e32 v41, v20, v45
	ds_read_b128 v[42:45], v26 offset:1056
	s_waitcnt lgkmcnt(0)
; DI float log_sigmoid_fast(float x) { return fminf(x, 0.f) - __logf(1.0f + __expf(-fabsf(x))); }
; template <int MODE>
; DI void gla4_unit(const bf16_t* z, float* ST, float* DEC, bf16_t* Y, const float* aw_g, const float* ab_g, const float* ng, ldsp lds, int tid, int u) {
;     ...
;         for (int i = 0; i < 32; ++i) {
;             const int t = 32 * half + i;
;             float al = ab;
; #pragma unroll
;             for (int r = 0; r < 16; ++r) al += alr[t * 16 + r] * aw[r];
;             run += log_sigmoid_fast(al) * (1.0f / 16.0f);
;             bc[i] = run;
;         }
	v_fmac_f32_e32 v41, v6, v42
	v_fmac_f32_e32 v41, v7, v43
	v_fmac_f32_e32 v41, v8, v44
	v_fmac_f32_e32 v41, v9, v45
	ds_read_b128 v[42:45], v26 offset:1072
	s_waitcnt lgkmcnt(0)
	v_fmac_f32_e32 v41, v2, v42
	v_fmac_f32_e32 v41, v3, v43
	v_pk_mul_f32 v[42:43], v[4:5], v[44:45]
	s_nop 0
	v_add_f32_e32 v41, v41, v42
	v_add_f32_e32 v41, v41, v43
	v_min_f32_e32 v42, 0, v41
	v_mul_f32_e64 v41, |v41|, s46
	v_exp_f32_e32 v41, v41
	s_nop 0
	v_add_f32_e32 v41, 1.0, v41
	v_cmp_gt_f32_e32 vcc, s47, v41
	s_nop 1
	v_cndmask_b32_e64 v43, 0, 32, vcc
	v_ldexp_f32 v41, v41, v43
	v_log_f32_e32 v41, v41
	s_nop 0
	v_mul_f32_e32 v43, 0x3f317217, v41
	v_fma_f32 v43, v41, s4, -v43
	v_fmac_f32_e32 v43, 0x3377d1cf, v41
	v_fmac_f32_e32 v43, 0x3f317217, v41
	v_cmp_lt_f32_e64 s[0:1], |v41|, s90
	s_nop 1
	v_cndmask_b32_e64 v41, v41, v43, s[0:1]
	v_cndmask_b32_e32 v43, 0, v203, vcc
	v_sub_f32_e32 v41, v41, v43
	v_sub_f32_e32 v41, v42, v41
	ds_read_b128 v[42:45], v26 offset:1088
	v_fmamk_f32 v41, v41, 0x3d800000, v40
	s_waitcnt lgkmcnt(0)
	v_fma_f32 v46, v21, v42, v16
	v_fmac_f32_e32 v46, v22, v43
	v_fmac_f32_e32 v46, v23, v44
	v_fmac_f32_e32 v46, v24, v45
	ds_read_b128 v[42:45], v26 offset:1104
	s_waitcnt lgkmcnt(0)
	v_fmac_f32_e32 v46, v17, v42
	v_fmac_f32_e32 v46, v18, v43
	v_fmac_f32_e32 v46, v19, v44
	v_fmac_f32_e32 v46, v20, v45
	ds_read_b128 v[42:45], v26 offset:1120
	s_waitcnt lgkmcnt(0)
	v_fmac_f32_e32 v46, v6, v42
	v_fmac_f32_e32 v46, v7, v43
	v_fmac_f32_e32 v46, v8, v44
	v_fmac_f32_e32 v46, v9, v45
	ds_read_b128 v[42:45], v26 offset:1136
	s_waitcnt lgkmcnt(0)
	v_fmac_f32_e32 v46, v2, v42
	v_fmac_f32_e32 v46, v3, v43
	v_pk_mul_f32 v[42:43], v[4:5], v[44:45]
	s_nop 0
	v_add_f32_e32 v42, v46, v42
	v_add_f32_e32 v42, v42, v43
	v_min_f32_e32 v43, 0, v42
	v_mul_f32_e64 v42, |v42|, s46
	v_exp_f32_e32 v42, v42
	s_nop 0
	v_add_f32_e32 v42, 1.0, v42
	v_cmp_gt_f32_e32 vcc, s47, v42
	s_nop 1
	v_cndmask_b32_e64 v44, 0, 32, vcc
	v_ldexp_f32 v42, v42, v44
	v_log_f32_e32 v42, v42
	s_nop 0
	v_mul_f32_e32 v44, 0x3f317217, v42
	v_fma_f32 v44, v42, s4, -v44
	v_fmac_f32_e32 v44, 0x3377d1cf, v42
	v_fmac_f32_e32 v44, 0x3f317217, v42
	v_cmp_lt_f32_e64 s[0:1], |v42|, s90
	s_nop 1
	v_cndmask_b32_e64 v42, v42, v44, s[0:1]
	v_cndmask_b32_e32 v44, 0, v203, vcc
	v_sub_f32_e32 v42, v42, v44
	ds_read_b128 v[44:47], v26 offset:1152
	v_sub_f32_e32 v42, v43, v42
	v_fmamk_f32 v42, v42, 0x3d800000, v41
	s_waitcnt lgkmcnt(0)
	v_fma_f32 v43, v21, v44, v16
	v_fmac_f32_e32 v43, v22, v45
	v_fmac_f32_e32 v43, v23, v46
	v_fmac_f32_e32 v43, v24, v47
	ds_read_b128 v[44:47], v26 offset:1168
	s_waitcnt lgkmcnt(0)
	v_fmac_f32_e32 v43, v17, v44
	v_fmac_f32_e32 v43, v18, v45
	v_fmac_f32_e32 v43, v19, v46
	v_fmac_f32_e32 v43, v20, v47
	ds_read_b128 v[44:47], v26 offset:1184
	s_waitcnt lgkmcnt(0)
	v_fmac_f32_e32 v43, v6, v44
	v_fmac_f32_e32 v43, v7, v45
	v_fmac_f32_e32 v43, v8, v46
	v_fmac_f32_e32 v43, v9, v47
	ds_read_b128 v[44:47], v26 offset:1200
	s_waitcnt lgkmcnt(0)
	v_fmac_f32_e32 v43, v2, v44
	v_fmac_f32_e32 v43, v3, v45
	v_pk_mul_f32 v[44:45], v[4:5], v[46:47]
	s_nop 0
	v_add_f32_e32 v43, v43, v44
	v_add_f32_e32 v43, v43, v45
	v_min_f32_e32 v44, 0, v43
	v_mul_f32_e64 v43, |v43|, s46
	v_exp_f32_e32 v43, v43
	s_nop 0
	v_add_f32_e32 v43, 1.0, v43
	v_cmp_gt_f32_e32 vcc, s47, v43
	s_nop 1
	v_cndmask_b32_e64 v45, 0, 32, vcc
	v_ldexp_f32 v43, v43, v45
	v_log_f32_e32 v43, v43
	s_nop 0
	v_mul_f32_e32 v45, 0x3f317217, v43
	v_fma_f32 v45, v43, s4, -v45
	v_fmac_f32_e32 v45, 0x3377d1cf, v43
	v_fmac_f32_e32 v45, 0x3f317217, v43
	v_cmp_lt_f32_e64 s[0:1], |v43|, s90
	s_nop 1
	v_cndmask_b32_e64 v43, v43, v45, s[0:1]
	v_cndmask_b32_e32 v45, 0, v203, vcc
	v_sub_f32_e32 v43, v43, v45
	v_sub_f32_e32 v43, v44, v43
	ds_read_b128 v[44:47], v26 offset:1216
	v_fmamk_f32 v43, v43, 0x3d800000, v42
	s_waitcnt lgkmcnt(0)
	v_fma_f32 v48, v21, v44, v16
	v_fmac_f32_e32 v48, v22, v45
	v_fmac_f32_e32 v48, v23, v46
	v_fmac_f32_e32 v48, v24, v47
	ds_read_b128 v[44:47], v26 offset:1232
	s_waitcnt lgkmcnt(0)
	v_fmac_f32_e32 v48, v17, v44
	v_fmac_f32_e32 v48, v18, v45
	v_fmac_f32_e32 v48, v19, v46
	v_fmac_f32_e32 v48, v20, v47
	ds_read_b128 v[44:47], v26 offset:1248
	s_waitcnt lgkmcnt(0)
	v_fmac_f32_e32 v48, v6, v44
	v_fmac_f32_e32 v48, v7, v45
	v_fmac_f32_e32 v48, v8, v46
	v_fmac_f32_e32 v48, v9, v47
	ds_read_b128 v[44:47], v26 offset:1264
	s_waitcnt lgkmcnt(0)
	v_fmac_f32_e32 v48, v2, v44
	v_fmac_f32_e32 v48, v3, v45
	v_pk_mul_f32 v[44:45], v[4:5], v[46:47]
	s_nop 0
	v_add_f32_e32 v44, v48, v44
	v_add_f32_e32 v44, v44, v45
	v_min_f32_e32 v45, 0, v44
	v_mul_f32_e64 v44, |v44|, s46
	v_exp_f32_e32 v44, v44
	s_nop 0
	v_add_f32_e32 v44, 1.0, v44
	v_cmp_gt_f32_e32 vcc, s47, v44
	s_nop 1
	v_cndmask_b32_e64 v46, 0, 32, vcc
	v_ldexp_f32 v44, v44, v46
	v_log_f32_e32 v44, v44
	s_nop 0
	v_mul_f32_e32 v46, 0x3f317217, v44
	v_fma_f32 v46, v44, s4, -v46
	v_fmac_f32_e32 v46, 0x3377d1cf, v44
	v_fmac_f32_e32 v46, 0x3f317217, v44
	v_cmp_lt_f32_e64 s[0:1], |v44|, s90
	s_nop 1
	v_cndmask_b32_e64 v44, v44, v46, s[0:1]
	v_cndmask_b32_e32 v46, 0, v203, vcc
	v_sub_f32_e32 v44, v44, v46
	ds_read_b128 v[46:49], v26 offset:1280
	v_sub_f32_e32 v44, v45, v44
	v_fmamk_f32 v44, v44, 0x3d800000, v43
	s_waitcnt lgkmcnt(0)
	v_fma_f32 v45, v21, v46, v16
	v_fmac_f32_e32 v45, v22, v47
	v_fmac_f32_e32 v45, v23, v48
	v_fmac_f32_e32 v45, v24, v49
	ds_read_b128 v[46:49], v26 offset:1296
	s_waitcnt lgkmcnt(0)
	v_fmac_f32_e32 v45, v17, v46
	v_fmac_f32_e32 v45, v18, v47
	v_fmac_f32_e32 v45, v19, v48
	v_fmac_f32_e32 v45, v20, v49
	ds_read_b128 v[46:49], v26 offset:1312
	s_waitcnt lgkmcnt(0)
	v_fmac_f32_e32 v45, v6, v46
	v_fmac_f32_e32 v45, v7, v47
	v_fmac_f32_e32 v45, v8, v48
	v_fmac_f32_e32 v45, v9, v49
	ds_read_b128 v[46:49], v26 offset:1328
	s_waitcnt lgkmcnt(0)
; DI float log_sigmoid_fast(float x) { return fminf(x, 0.f) - __logf(1.0f + __expf(-fabsf(x))); }
; template <int MODE>
; DI void gla4_unit(const bf16_t* z, float* ST, float* DEC, bf16_t* Y, const float* aw_g, const float* ab_g, const float* ng, ldsp lds, int tid, int u) {
;     ...
;         for (int i = 0; i < 32; ++i) {
;             const int t = 32 * half + i;
;             float al = ab;
; #pragma unroll
;             for (int r = 0; r < 16; ++r) al += alr[t * 16 + r] * aw[r];
;             run += log_sigmoid_fast(al) * (1.0f / 16.0f);
;             bc[i] = run;
;         }
	v_fmac_f32_e32 v45, v2, v46
	v_fmac_f32_e32 v45, v3, v47
	v_pk_mul_f32 v[46:47], v[4:5], v[48:49]
	s_nop 0
	v_add_f32_e32 v45, v45, v46
	v_add_f32_e32 v45, v45, v47
	v_min_f32_e32 v46, 0, v45
	v_mul_f32_e64 v45, |v45|, s46
	v_exp_f32_e32 v45, v45
	s_nop 0
	v_add_f32_e32 v45, 1.0, v45
	v_cmp_gt_f32_e32 vcc, s47, v45
	s_nop 1
	v_cndmask_b32_e64 v47, 0, 32, vcc
	v_ldexp_f32 v45, v45, v47
	v_log_f32_e32 v45, v45
	s_nop 0
	v_mul_f32_e32 v47, 0x3f317217, v45
	v_fma_f32 v47, v45, s4, -v47
	v_fmac_f32_e32 v47, 0x3377d1cf, v45
	v_fmac_f32_e32 v47, 0x3f317217, v45
	v_cmp_lt_f32_e64 s[0:1], |v45|, s90
	s_nop 1
	v_cndmask_b32_e64 v45, v45, v47, s[0:1]
	v_cndmask_b32_e32 v47, 0, v203, vcc
	v_sub_f32_e32 v45, v45, v47
	v_sub_f32_e32 v45, v46, v45
	ds_read_b128 v[46:49], v26 offset:1344
	v_fmamk_f32 v45, v45, 0x3d800000, v44
	s_waitcnt lgkmcnt(0)
	v_fma_f32 v50, v21, v46, v16
	v_fmac_f32_e32 v50, v22, v47
	v_fmac_f32_e32 v50, v23, v48
	v_fmac_f32_e32 v50, v24, v49
	ds_read_b128 v[46:49], v26 offset:1360
	s_waitcnt lgkmcnt(0)
	v_fmac_f32_e32 v50, v17, v46
	v_fmac_f32_e32 v50, v18, v47
	v_fmac_f32_e32 v50, v19, v48
	v_fmac_f32_e32 v50, v20, v49
	ds_read_b128 v[46:49], v26 offset:1376
	s_waitcnt lgkmcnt(0)
	v_fmac_f32_e32 v50, v6, v46
	v_fmac_f32_e32 v50, v7, v47
	v_fmac_f32_e32 v50, v8, v48
	v_fmac_f32_e32 v50, v9, v49
	ds_read_b128 v[46:49], v26 offset:1392
	s_waitcnt lgkmcnt(0)
	v_fmac_f32_e32 v50, v2, v46
	v_fmac_f32_e32 v50, v3, v47
	v_pk_mul_f32 v[46:47], v[4:5], v[48:49]
	s_nop 0
	v_add_f32_e32 v46, v50, v46
	v_add_f32_e32 v46, v46, v47
	v_min_f32_e32 v47, 0, v46
	v_mul_f32_e64 v46, |v46|, s46
	v_exp_f32_e32 v46, v46
	s_nop 0
	v_add_f32_e32 v46, 1.0, v46
	v_cmp_gt_f32_e32 vcc, s47, v46
	s_nop 1
	v_cndmask_b32_e64 v48, 0, 32, vcc
	v_ldexp_f32 v46, v46, v48
	v_log_f32_e32 v46, v46
	s_nop 0
	v_mul_f32_e32 v48, 0x3f317217, v46
	v_fma_f32 v48, v46, s4, -v48
	v_fmac_f32_e32 v48, 0x3377d1cf, v46
	v_fmac_f32_e32 v48, 0x3f317217, v46
	v_cmp_lt_f32_e64 s[0:1], |v46|, s90
	s_nop 1
	v_cndmask_b32_e64 v46, v46, v48, s[0:1]
	v_cndmask_b32_e32 v48, 0, v203, vcc
	v_sub_f32_e32 v46, v46, v48
	ds_read_b128 v[48:51], v26 offset:1408
	v_sub_f32_e32 v46, v47, v46
	v_fmamk_f32 v46, v46, 0x3d800000, v45
	s_waitcnt lgkmcnt(0)
	v_fma_f32 v47, v21, v48, v16
	v_fmac_f32_e32 v47, v22, v49
	v_fmac_f32_e32 v47, v23, v50
	v_fmac_f32_e32 v47, v24, v51
	ds_read_b128 v[48:51], v26 offset:1424
	s_waitcnt lgkmcnt(0)
	v_fmac_f32_e32 v47, v17, v48
	v_fmac_f32_e32 v47, v18, v49
	v_fmac_f32_e32 v47, v19, v50
	v_fmac_f32_e32 v47, v20, v51
	ds_read_b128 v[48:51], v26 offset:1440
	s_waitcnt lgkmcnt(0)
	v_fmac_f32_e32 v47, v6, v48
	v_fmac_f32_e32 v47, v7, v49
	v_fmac_f32_e32 v47, v8, v50
	v_fmac_f32_e32 v47, v9, v51
	ds_read_b128 v[48:51], v26 offset:1456
	s_waitcnt lgkmcnt(0)
	v_fmac_f32_e32 v47, v2, v48
	v_fmac_f32_e32 v47, v3, v49
	v_pk_mul_f32 v[48:49], v[4:5], v[50:51]
	s_nop 0
	v_add_f32_e32 v47, v47, v48
	v_add_f32_e32 v47, v47, v49
	v_min_f32_e32 v48, 0, v47
	v_mul_f32_e64 v47, |v47|, s46
	v_exp_f32_e32 v47, v47
	s_nop 0
	v_add_f32_e32 v47, 1.0, v47
	v_cmp_gt_f32_e32 vcc, s47, v47
	s_nop 1
	v_cndmask_b32_e64 v49, 0, 32, vcc
	v_ldexp_f32 v47, v47, v49
	v_log_f32_e32 v47, v47
	s_nop 0
	v_mul_f32_e32 v49, 0x3f317217, v47
	v_fma_f32 v49, v47, s4, -v49
	v_fmac_f32_e32 v49, 0x3377d1cf, v47
	v_fmac_f32_e32 v49, 0x3f317217, v47
	v_cmp_lt_f32_e64 s[0:1], |v47|, s90
	s_nop 1
	v_cndmask_b32_e64 v47, v47, v49, s[0:1]
	v_cndmask_b32_e32 v49, 0, v203, vcc
	v_sub_f32_e32 v47, v47, v49
	v_sub_f32_e32 v47, v48, v47
	ds_read_b128 v[48:51], v26 offset:1472
	v_fmamk_f32 v47, v47, 0x3d800000, v46
	s_waitcnt lgkmcnt(0)
	v_fma_f32 v52, v21, v48, v16
	v_fmac_f32_e32 v52, v22, v49
	v_fmac_f32_e32 v52, v23, v50
	v_fmac_f32_e32 v52, v24, v51
	ds_read_b128 v[48:51], v26 offset:1488
	s_waitcnt lgkmcnt(0)
	v_fmac_f32_e32 v52, v17, v48
	v_fmac_f32_e32 v52, v18, v49
	v_fmac_f32_e32 v52, v19, v50
	v_fmac_f32_e32 v52, v20, v51
	ds_read_b128 v[48:51], v26 offset:1504
	s_waitcnt lgkmcnt(0)
	v_fmac_f32_e32 v52, v6, v48
	v_fmac_f32_e32 v52, v7, v49
	v_fmac_f32_e32 v52, v8, v50
	v_fmac_f32_e32 v52, v9, v51
	ds_read_b128 v[48:51], v26 offset:1520
	s_waitcnt lgkmcnt(0)
	v_fmac_f32_e32 v52, v2, v48
	v_fmac_f32_e32 v52, v3, v49
	v_pk_mul_f32 v[48:49], v[4:5], v[50:51]
	s_nop 0
	v_add_f32_e32 v48, v52, v48
	v_add_f32_e32 v48, v48, v49
	v_min_f32_e32 v49, 0, v48
	v_mul_f32_e64 v48, |v48|, s46
	v_exp_f32_e32 v48, v48
	s_nop 0
	v_add_f32_e32 v48, 1.0, v48
	v_cmp_gt_f32_e32 vcc, s47, v48
	s_nop 1
	v_cndmask_b32_e64 v50, 0, 32, vcc
	v_ldexp_f32 v48, v48, v50
	v_log_f32_e32 v48, v48
	s_nop 0
	v_mul_f32_e32 v50, 0x3f317217, v48
	v_fma_f32 v50, v48, s4, -v50
	v_fmac_f32_e32 v50, 0x3377d1cf, v48
	v_fmac_f32_e32 v50, 0x3f317217, v48
	v_cmp_lt_f32_e64 s[0:1], |v48|, s90
	s_nop 1
	v_cndmask_b32_e64 v48, v48, v50, s[0:1]
	v_cndmask_b32_e32 v50, 0, v203, vcc
	v_sub_f32_e32 v48, v48, v50
	ds_read_b128 v[50:53], v26 offset:1536
	v_sub_f32_e32 v48, v49, v48
	v_fmamk_f32 v48, v48, 0x3d800000, v47
	s_waitcnt lgkmcnt(0)
	v_fma_f32 v49, v21, v50, v16
	v_fmac_f32_e32 v49, v22, v51
	v_fmac_f32_e32 v49, v23, v52
	v_fmac_f32_e32 v49, v24, v53
	ds_read_b128 v[50:53], v26 offset:1552
	s_waitcnt lgkmcnt(0)
	v_fmac_f32_e32 v49, v17, v50
	v_fmac_f32_e32 v49, v18, v51
	v_fmac_f32_e32 v49, v19, v52
	v_fmac_f32_e32 v49, v20, v53
	ds_read_b128 v[50:53], v26 offset:1568
	s_waitcnt lgkmcnt(0)
	v_fmac_f32_e32 v49, v6, v50
	v_fmac_f32_e32 v49, v7, v51
	v_fmac_f32_e32 v49, v8, v52
	v_fmac_f32_e32 v49, v9, v53
	ds_read_b128 v[50:53], v26 offset:1584
	s_waitcnt lgkmcnt(0)
; DI float log_sigmoid_fast(float x) { return fminf(x, 0.f) - __logf(1.0f + __expf(-fabsf(x))); }
; template <int MODE>
; DI void gla4_unit(const bf16_t* z, float* ST, float* DEC, bf16_t* Y, const float* aw_g, const float* ab_g, const float* ng, ldsp lds, int tid, int u) {
;     ...
;         for (int i = 0; i < 32; ++i) {
;             const int t = 32 * half + i;
;             float al = ab;
; #pragma unroll
;             for (int r = 0; r < 16; ++r) al += alr[t * 16 + r] * aw[r];
;             run += log_sigmoid_fast(al) * (1.0f / 16.0f);
;             bc[i] = run;
;         }
	v_fmac_f32_e32 v49, v2, v50
	v_fmac_f32_e32 v49, v3, v51
	v_pk_mul_f32 v[50:51], v[4:5], v[52:53]
	s_nop 0
	v_add_f32_e32 v49, v49, v50
	v_add_f32_e32 v49, v49, v51
	v_min_f32_e32 v50, 0, v49
	v_mul_f32_e64 v49, |v49|, s46
	v_exp_f32_e32 v49, v49
	s_nop 0
	v_add_f32_e32 v49, 1.0, v49
	v_cmp_gt_f32_e32 vcc, s47, v49
	s_nop 1
	v_cndmask_b32_e64 v51, 0, 32, vcc
	v_ldexp_f32 v49, v49, v51
	v_log_f32_e32 v49, v49
	s_nop 0
	v_mul_f32_e32 v51, 0x3f317217, v49
	v_fma_f32 v51, v49, s4, -v51
	v_fmac_f32_e32 v51, 0x3377d1cf, v49
	v_fmac_f32_e32 v51, 0x3f317217, v49
	v_cmp_lt_f32_e64 s[0:1], |v49|, s90
	s_nop 1
	v_cndmask_b32_e64 v49, v49, v51, s[0:1]
	v_cndmask_b32_e32 v51, 0, v203, vcc
	v_sub_f32_e32 v49, v49, v51
	v_sub_f32_e32 v49, v50, v49
	ds_read_b128 v[50:53], v26 offset:1600
	v_fmamk_f32 v49, v49, 0x3d800000, v48
	s_waitcnt lgkmcnt(0)
	v_fma_f32 v54, v21, v50, v16
	v_fmac_f32_e32 v54, v22, v51
	v_fmac_f32_e32 v54, v23, v52
	v_fmac_f32_e32 v54, v24, v53
	ds_read_b128 v[50:53], v26 offset:1616
	s_waitcnt lgkmcnt(0)
	v_fmac_f32_e32 v54, v17, v50
	v_fmac_f32_e32 v54, v18, v51
	v_fmac_f32_e32 v54, v19, v52
	v_fmac_f32_e32 v54, v20, v53
	ds_read_b128 v[50:53], v26 offset:1632
	s_waitcnt lgkmcnt(0)
	v_fmac_f32_e32 v54, v6, v50
	v_fmac_f32_e32 v54, v7, v51
	v_fmac_f32_e32 v54, v8, v52
	v_fmac_f32_e32 v54, v9, v53
	ds_read_b128 v[50:53], v26 offset:1648
	s_waitcnt lgkmcnt(0)
	v_fmac_f32_e32 v54, v2, v50
	v_fmac_f32_e32 v54, v3, v51
	v_pk_mul_f32 v[50:51], v[4:5], v[52:53]
	s_nop 0
	v_add_f32_e32 v50, v54, v50
	v_add_f32_e32 v50, v50, v51
	v_min_f32_e32 v51, 0, v50
	v_mul_f32_e64 v50, |v50|, s46
	v_exp_f32_e32 v50, v50
	s_nop 0
	v_add_f32_e32 v50, 1.0, v50
	v_cmp_gt_f32_e32 vcc, s47, v50
	s_nop 1
	v_cndmask_b32_e64 v52, 0, 32, vcc
	v_ldexp_f32 v50, v50, v52
	v_log_f32_e32 v50, v50
	s_nop 0
	v_mul_f32_e32 v52, 0x3f317217, v50
	v_fma_f32 v52, v50, s4, -v52
	v_fmac_f32_e32 v52, 0x3377d1cf, v50
	v_fmac_f32_e32 v52, 0x3f317217, v50
	v_cmp_lt_f32_e64 s[0:1], |v50|, s90
	s_nop 1
	v_cndmask_b32_e64 v50, v50, v52, s[0:1]
	v_cndmask_b32_e32 v52, 0, v203, vcc
	v_sub_f32_e32 v50, v50, v52
	ds_read_b128 v[52:55], v26 offset:1664
	v_sub_f32_e32 v50, v51, v50
	v_fmamk_f32 v50, v50, 0x3d800000, v49
	s_waitcnt lgkmcnt(0)
	v_fma_f32 v51, v21, v52, v16
	v_fmac_f32_e32 v51, v22, v53
	v_fmac_f32_e32 v51, v23, v54
	v_fmac_f32_e32 v51, v24, v55
	ds_read_b128 v[52:55], v26 offset:1680
	s_waitcnt lgkmcnt(0)
	v_fmac_f32_e32 v51, v17, v52
	v_fmac_f32_e32 v51, v18, v53
	v_fmac_f32_e32 v51, v19, v54
	v_fmac_f32_e32 v51, v20, v55
	ds_read_b128 v[52:55], v26 offset:1696
	s_waitcnt lgkmcnt(0)
	v_fmac_f32_e32 v51, v6, v52
	v_fmac_f32_e32 v51, v7, v53
	v_fmac_f32_e32 v51, v8, v54
	v_fmac_f32_e32 v51, v9, v55
	ds_read_b128 v[52:55], v26 offset:1712
	s_waitcnt lgkmcnt(0)
	v_fmac_f32_e32 v51, v2, v52
	v_fmac_f32_e32 v51, v3, v53
	v_pk_mul_f32 v[52:53], v[4:5], v[54:55]
	s_nop 0
	v_add_f32_e32 v51, v51, v52
	v_add_f32_e32 v51, v51, v53
	v_min_f32_e32 v52, 0, v51
	v_mul_f32_e64 v51, |v51|, s46
	v_exp_f32_e32 v51, v51
	s_nop 0
	v_add_f32_e32 v51, 1.0, v51
	v_cmp_gt_f32_e32 vcc, s47, v51
	s_nop 1
	v_cndmask_b32_e64 v53, 0, 32, vcc
	v_ldexp_f32 v51, v51, v53
	v_log_f32_e32 v51, v51
	s_nop 0
	v_mul_f32_e32 v53, 0x3f317217, v51
	v_fma_f32 v53, v51, s4, -v53
	v_fmac_f32_e32 v53, 0x3377d1cf, v51
	v_fmac_f32_e32 v53, 0x3f317217, v51
	v_cmp_lt_f32_e64 s[0:1], |v51|, s90
	s_nop 1
	v_cndmask_b32_e64 v51, v51, v53, s[0:1]
	v_cndmask_b32_e32 v53, 0, v203, vcc
	v_sub_f32_e32 v51, v51, v53
	v_sub_f32_e32 v51, v52, v51
	ds_read_b128 v[52:55], v26 offset:1728
	v_fmamk_f32 v51, v51, 0x3d800000, v50
	s_waitcnt lgkmcnt(0)
	v_fma_f32 v56, v21, v52, v16
	v_fmac_f32_e32 v56, v22, v53
	v_fmac_f32_e32 v56, v23, v54
	v_fmac_f32_e32 v56, v24, v55
	ds_read_b128 v[52:55], v26 offset:1744
	s_waitcnt lgkmcnt(0)
	v_fmac_f32_e32 v56, v17, v52
	v_fmac_f32_e32 v56, v18, v53
	v_fmac_f32_e32 v56, v19, v54
	v_fmac_f32_e32 v56, v20, v55
	ds_read_b128 v[52:55], v26 offset:1760
	s_waitcnt lgkmcnt(0)
	v_fmac_f32_e32 v56, v6, v52
	v_fmac_f32_e32 v56, v7, v53
	v_fmac_f32_e32 v56, v8, v54
	v_fmac_f32_e32 v56, v9, v55
	ds_read_b128 v[52:55], v26 offset:1776
	s_waitcnt lgkmcnt(0)
	v_fmac_f32_e32 v56, v2, v52
	v_fmac_f32_e32 v56, v3, v53
	v_pk_mul_f32 v[52:53], v[4:5], v[54:55]
	s_nop 0
	v_add_f32_e32 v52, v56, v52
	v_add_f32_e32 v52, v52, v53
	v_min_f32_e32 v53, 0, v52
	v_mul_f32_e64 v52, |v52|, s46
	v_exp_f32_e32 v52, v52
	s_nop 0
	v_add_f32_e32 v52, 1.0, v52
	v_cmp_gt_f32_e32 vcc, s47, v52
	s_nop 1
	v_cndmask_b32_e64 v54, 0, 32, vcc
	v_ldexp_f32 v52, v52, v54
	v_log_f32_e32 v52, v52
	s_nop 0
	v_mul_f32_e32 v54, 0x3f317217, v52
	v_fma_f32 v54, v52, s4, -v54
	v_fmac_f32_e32 v54, 0x3377d1cf, v52
	v_fmac_f32_e32 v54, 0x3f317217, v52
	v_cmp_lt_f32_e64 s[0:1], |v52|, s90
	s_nop 1
	v_cndmask_b32_e64 v52, v52, v54, s[0:1]
	v_cndmask_b32_e32 v54, 0, v203, vcc
	v_sub_f32_e32 v52, v52, v54
	ds_read_b128 v[54:57], v26 offset:1792
	v_sub_f32_e32 v52, v53, v52
	v_fmamk_f32 v52, v52, 0x3d800000, v51
	s_waitcnt lgkmcnt(0)
	v_fma_f32 v53, v21, v54, v16
	v_fmac_f32_e32 v53, v22, v55
	v_fmac_f32_e32 v53, v23, v56
	v_fmac_f32_e32 v53, v24, v57
	ds_read_b128 v[54:57], v26 offset:1808
	s_waitcnt lgkmcnt(0)
	v_fmac_f32_e32 v53, v17, v54
	v_fmac_f32_e32 v53, v18, v55
	v_fmac_f32_e32 v53, v19, v56
	v_fmac_f32_e32 v53, v20, v57
	ds_read_b128 v[54:57], v26 offset:1824
	s_waitcnt lgkmcnt(0)
	v_fmac_f32_e32 v53, v6, v54
	v_fmac_f32_e32 v53, v7, v55
	v_fmac_f32_e32 v53, v8, v56
	v_fmac_f32_e32 v53, v9, v57
	ds_read_b128 v[54:57], v26 offset:1840
	s_waitcnt lgkmcnt(0)
; DI float log_sigmoid_fast(float x) { return fminf(x, 0.f) - __logf(1.0f + __expf(-fabsf(x))); }
; template <int MODE>
; DI void gla4_unit(const bf16_t* z, float* ST, float* DEC, bf16_t* Y, const float* aw_g, const float* ab_g, const float* ng, ldsp lds, int tid, int u) {
;     ...
;     float bc[32];
;     {
;         float run = 0.f;
; #pragma unroll
;         for (int i = 0; i < 32; ++i) {
;             const int t = 32 * half + i;
;             float al = ab;
; #pragma unroll
;             for (int r = 0; r < 16; ++r) al += alr[t * 16 + r] * aw[r];
;             run += log_sigmoid_fast(al) * (1.0f / 16.0f);
;             bc[i] = run;
;         }
;         tot[half * 256 + hd * 64 + d] = run;
;     }
;     __syncthreads();
	v_fmac_f32_e32 v53, v2, v54
	v_fmac_f32_e32 v53, v3, v55
	v_pk_mul_f32 v[54:55], v[4:5], v[56:57]
	s_nop 0
	v_add_f32_e32 v53, v53, v54
	v_add_f32_e32 v53, v53, v55
	v_min_f32_e32 v54, 0, v53
	v_mul_f32_e64 v53, |v53|, s46
	v_exp_f32_e32 v53, v53
	s_nop 0
	v_add_f32_e32 v53, 1.0, v53
	v_cmp_gt_f32_e32 vcc, s47, v53
	s_nop 1
	v_cndmask_b32_e64 v55, 0, 32, vcc
	v_ldexp_f32 v53, v53, v55
	v_log_f32_e32 v53, v53
	s_nop 0
	v_mul_f32_e32 v55, 0x3f317217, v53
	v_fma_f32 v55, v53, s4, -v55
	v_fmac_f32_e32 v55, 0x3377d1cf, v53
	v_fmac_f32_e32 v55, 0x3f317217, v53
	v_cmp_lt_f32_e64 s[0:1], |v53|, s90
	s_nop 1
	v_cndmask_b32_e64 v53, v53, v55, s[0:1]
	v_cndmask_b32_e32 v55, 0, v203, vcc
	v_sub_f32_e32 v53, v53, v55
	v_sub_f32_e32 v53, v54, v53
	ds_read_b128 v[54:57], v26 offset:1856
	v_fmamk_f32 v53, v53, 0x3d800000, v52
	s_waitcnt lgkmcnt(0)
	v_fma_f32 v58, v21, v54, v16
	v_fmac_f32_e32 v58, v22, v55
	v_fmac_f32_e32 v58, v23, v56
	v_fmac_f32_e32 v58, v24, v57
	ds_read_b128 v[54:57], v26 offset:1872
	s_waitcnt lgkmcnt(0)
	v_fmac_f32_e32 v58, v17, v54
	v_fmac_f32_e32 v58, v18, v55
	v_fmac_f32_e32 v58, v19, v56
	v_fmac_f32_e32 v58, v20, v57
	ds_read_b128 v[54:57], v26 offset:1888
	s_waitcnt lgkmcnt(0)
	v_fmac_f32_e32 v58, v6, v54
	v_fmac_f32_e32 v58, v7, v55
	v_fmac_f32_e32 v58, v8, v56
	v_fmac_f32_e32 v58, v9, v57
	ds_read_b128 v[54:57], v26 offset:1904
	s_waitcnt lgkmcnt(0)
	v_fmac_f32_e32 v58, v2, v54
	v_fmac_f32_e32 v58, v3, v55
	v_pk_mul_f32 v[54:55], v[4:5], v[56:57]
	s_nop 0
	v_add_f32_e32 v54, v58, v54
	v_add_f32_e32 v54, v54, v55
	v_min_f32_e32 v55, 0, v54
	v_mul_f32_e64 v54, |v54|, s46
	v_exp_f32_e32 v54, v54
	s_nop 0
	v_add_f32_e32 v54, 1.0, v54
	v_cmp_gt_f32_e32 vcc, s47, v54
	s_nop 1
	v_cndmask_b32_e64 v56, 0, 32, vcc
	v_ldexp_f32 v54, v54, v56
	v_log_f32_e32 v54, v54
	s_nop 0
	v_mul_f32_e32 v56, 0x3f317217, v54
	v_fma_f32 v56, v54, s4, -v56
	v_fmac_f32_e32 v56, 0x3377d1cf, v54
	v_fmac_f32_e32 v56, 0x3f317217, v54
	v_cmp_lt_f32_e64 s[0:1], |v54|, s90
	s_nop 1
	v_cndmask_b32_e64 v54, v54, v56, s[0:1]
	v_cndmask_b32_e32 v56, 0, v203, vcc
	v_sub_f32_e32 v54, v54, v56
	ds_read_b128 v[56:59], v26 offset:1920
	v_sub_f32_e32 v54, v55, v54
	v_fmamk_f32 v54, v54, 0x3d800000, v53
	s_waitcnt lgkmcnt(0)
	v_fma_f32 v55, v21, v56, v16
	v_fmac_f32_e32 v55, v22, v57
	v_fmac_f32_e32 v55, v23, v58
	v_fmac_f32_e32 v55, v24, v59
	ds_read_b128 v[56:59], v26 offset:1936
	s_waitcnt lgkmcnt(0)
	v_fmac_f32_e32 v55, v17, v56
	v_fmac_f32_e32 v55, v18, v57
	v_fmac_f32_e32 v55, v19, v58
	v_fmac_f32_e32 v55, v20, v59
	ds_read_b128 v[56:59], v26 offset:1952
	s_waitcnt lgkmcnt(0)
	v_fmac_f32_e32 v55, v6, v56
	v_fmac_f32_e32 v55, v7, v57
	v_fmac_f32_e32 v55, v8, v58
	v_fmac_f32_e32 v55, v9, v59
	ds_read_b128 v[56:59], v26 offset:1968
	s_waitcnt lgkmcnt(0)
	v_fmac_f32_e32 v55, v2, v56
	v_fmac_f32_e32 v55, v3, v57
	v_pk_mul_f32 v[56:57], v[4:5], v[58:59]
	s_nop 0
	v_add_f32_e32 v55, v55, v56
	v_add_f32_e32 v55, v55, v57
	v_min_f32_e32 v56, 0, v55
	v_mul_f32_e64 v55, |v55|, s46
	v_exp_f32_e32 v55, v55
	s_nop 0
	v_add_f32_e32 v55, 1.0, v55
	v_cmp_gt_f32_e32 vcc, s47, v55
	s_nop 1
	v_cndmask_b32_e64 v57, 0, 32, vcc
	v_ldexp_f32 v55, v55, v57
	v_log_f32_e32 v55, v55
	s_nop 0
	v_mul_f32_e32 v57, 0x3f317217, v55
	v_fma_f32 v57, v55, s4, -v57
	v_fmac_f32_e32 v57, 0x3377d1cf, v55
	v_fmac_f32_e32 v57, 0x3f317217, v55
	v_cmp_lt_f32_e64 s[0:1], |v55|, s90
	s_nop 1
	v_cndmask_b32_e64 v55, v55, v57, s[0:1]
	v_cndmask_b32_e32 v57, 0, v203, vcc
	v_sub_f32_e32 v55, v55, v57
	v_sub_f32_e32 v55, v56, v55
	ds_read_b128 v[56:59], v26 offset:1984
	v_fmamk_f32 v55, v55, 0x3d800000, v54
	s_waitcnt lgkmcnt(0)
	v_fmac_f32_e32 v16, v21, v56
	v_fmac_f32_e32 v16, v22, v57
	v_fmac_f32_e32 v16, v23, v58
	v_fmac_f32_e32 v16, v24, v59
	ds_read_b128 v[56:59], v26 offset:2000
	s_waitcnt lgkmcnt(0)
	v_fmac_f32_e32 v16, v17, v56
	v_fmac_f32_e32 v16, v18, v57
	v_fmac_f32_e32 v16, v19, v58
	v_fmac_f32_e32 v16, v20, v59
	ds_read_b128 v[18:21], v26 offset:2016
	s_waitcnt lgkmcnt(0)
	v_fmac_f32_e32 v16, v6, v18
	v_fmac_f32_e32 v16, v7, v19
	v_fmac_f32_e32 v16, v8, v20
	v_fmac_f32_e32 v16, v9, v21
	ds_read_b128 v[6:9], v26 offset:2032
	s_waitcnt lgkmcnt(0)
	v_fmac_f32_e32 v16, v2, v6
	v_fmac_f32_e32 v16, v3, v7
	v_pk_mul_f32 v[2:3], v[4:5], v[8:9]
	v_lshlrev_b32_e32 v7, 6, v10
	v_add_f32_e32 v2, v16, v2
	v_add_f32_e32 v2, v2, v3
	v_min_f32_e32 v3, 0, v2
	v_mul_f32_e64 v2, |v2|, s46
	v_exp_f32_e32 v2, v2
	v_lshlrev_b32_e32 v6, 1, v15
	v_add_f32_e32 v2, 1.0, v2
	v_cmp_gt_f32_e32 vcc, s47, v2
	s_nop 1
	v_cndmask_b32_e64 v4, 0, 32, vcc
	v_ldexp_f32 v2, v2, v4
	v_log_f32_e32 v2, v2
	s_nop 0
	v_mul_f32_e32 v4, 0x3f317217, v2
	v_fma_f32 v4, v2, s4, -v4
	v_fmac_f32_e32 v4, 0x3377d1cf, v2
	v_fmac_f32_e32 v4, 0x3f317217, v2
	v_cmp_lt_f32_e64 s[0:1], |v2|, s90
	s_nop 1
	v_cndmask_b32_e64 v2, v2, v4, s[0:1]
	v_cndmask_b32_e32 v4, 0, v203, vcc
	v_sub_f32_e32 v2, v2, v4
	v_sub_f32_e32 v2, v3, v2
	v_fmamk_f32 v8, v2, 0x3d800000, v55
	s_add_i32 s0, 0, 0x1c000
	v_lshlrev_b32_e32 v2, 8, v13
	v_add3_u32 v2, s0, v2, v156
	v_lshl_add_u32 v3, v10, 10, v2
	v_lshl_add_u32 v0, v0, 2, s0
	ds_write_b32 v3, v8
	s_waitcnt lgkmcnt(0)
	s_barrier
; #define LAS __attribute__((address_space(3)))
; #define LAS __attribute__((address_space(3)))
; DI float bf1(bf16_t v) { return __uint_as_float((unsigned)v << 16); }
; DI u32x4 pack8(const float (&f)[8]) { u32x4 o; o.x = pk(f[0], f[1]); o.y = pk(f[2], f[3]); o.z = pk(f[4], f[5]); o.w = pk(f[6], f[7]); return o; }
; template <int MODE>
; DI void gla4_unit(const bf16_t* z, float* ST, float* DEC, bf16_t* Y, const float* aw_g, const float* ab_g, const float* ng, ldsp lds, int tid, int u) {
;     ...
;     const float t0 = tot[hd * 64 + d], t1 = tot[256 + hd * 64 + d];
;     const float pre = half ? t0 : 0.f, blast = t0 + t1;
;     if (MODE == 0) {
; #pragma unroll
;         for (int j = 0; j < 4; ++j) {
;             float f[8];
; #pragma unroll
;             for (int k = 0; k < 8; ++k) { const int i = 8 * j + k; f[k] = bf1(*(LAS bf16_t*)(hr + (32 * half + i) * 144 + d * 2)) * __expf(blast - (bc[i] + pre)); }
;             *(LAS u32x4*)(hr + G4_R1 + d * 144 + (32 * half + 8 * j) * 2) = pack8(f);
	ds_read_b32 v0, v0
	ds_read_b32 v2, v2 offset:1024
	v_add_u32_e32 v4, 0, v14
	v_and_b32_e32 v3, 64, v11
	v_cmp_ne_u32_e32 vcc, 0, v3
	v_mad_u32_u24 v5, v15, s89, v4
	v_add_u32_e32 v5, v5, v7
	s_waitcnt lgkmcnt(1)
	v_cndmask_b32_e32 v3, 0, v0, vcc
	v_mul_u32_u24_e32 v7, 0x1200, v10
	v_add3_u32 v9, v4, v6, v7
	v_add_f32_e32 v14, v25, v3
	s_waitcnt lgkmcnt(0)
	v_pk_add_f32 v[0:1], v[0:1], v[2:3]
	ds_read_u16 v13, v9
	ds_read_u16 v15, v9 offset:144
	ds_read_u16 v17, v9 offset:288
	ds_read_u16 v19, v9 offset:432
	ds_read_u16 v21, v9 offset:576
	ds_read_u16 v23, v9 offset:720
	ds_read_u16 v25, v9 offset:864
	v_sub_f32_e32 v2, v0, v14
	v_mul_f32_e32 v2, 0x3fb8aa3b, v2
	v_exp_f32_e32 v2, v2
	s_waitcnt lgkmcnt(6)
	v_lshlrev_b32_e32 v13, 16, v13
	v_add_f32_e32 v16, v27, v3
	v_add_f32_e32 v18, v28, v3
	v_mul_f32_e32 v2, v2, v13
	v_sub_f32_e32 v13, v0, v16
	v_sub_f32_e32 v14, v0, v18
	v_mul_f32_e32 v13, 0x3fb8aa3b, v13
	v_mul_f32_e32 v14, 0x3fb8aa3b, v14
	v_exp_f32_e32 v13, v13
	v_exp_f32_e32 v14, v14
	s_waitcnt lgkmcnt(5)
	v_lshlrev_b32_e32 v15, 16, v15
	s_waitcnt lgkmcnt(4)
	v_lshlrev_b32_e32 v17, 16, v17
	v_add_f32_e32 v20, v29, v3
	v_mul_f32_e32 v13, v13, v15
	v_mul_f32_e32 v15, v14, v17
	v_sub_f32_e32 v14, v0, v20
	v_mul_f32_e32 v14, 0x3fb8aa3b, v14
	v_exp_f32_e32 v14, v14
	s_waitcnt lgkmcnt(3)
	v_lshlrev_b32_e32 v19, 16, v19
	v_add_f32_e32 v22, v30, v3
	s_waitcnt lgkmcnt(2)
	v_lshlrev_b32_e32 v21, 16, v21
	v_mul_f32_e32 v16, v14, v19
	v_sub_f32_e32 v14, v0, v22
	v_mul_f32_e32 v14, 0x3fb8aa3b, v14
	v_exp_f32_e32 v14, v14
	v_add_f32_e32 v24, v31, v3
	s_waitcnt lgkmcnt(1)
	v_lshlrev_b32_e32 v23, 16, v23
	v_add_f32_e32 v19, v32, v3
	v_mul_f32_e32 v17, v14, v21
	v_sub_f32_e32 v14, v0, v24
	v_mul_f32_e32 v14, 0x3fb8aa3b, v14
	v_exp_f32_e32 v14, v14
	v_sub_f32_e32 v1, v0, v1
	v_sub_f32_e32 v19, v0, v19
	v_mul_f32_e32 v1, 0x3fb8aa3b, v1
	v_mul_f32_e32 v18, v14, v23
	ds_read_u16 v14, v9 offset:1008
	v_mul_f32_e32 v19, 0x3fb8aa3b, v19
	v_exp_f32_e32 v1, v1
	v_exp_f32_e32 v19, v19
	s_waitcnt lgkmcnt(1)
	v_lshlrev_b32_e32 v25, 16, v25
	s_waitcnt lgkmcnt(0)
	v_lshlrev_b32_e32 v14, 16, v14
	v_mul_f32_e32 v1, v1, v25
	v_mul_f32_e32 v19, v19, v14
	v_cvt_pk_bf16_f32 v14, v2, v13
	v_cvt_pk_bf16_f32 v15, v15, v16
	v_cvt_pk_bf16_f32 v16, v17, v18
	v_cvt_pk_bf16_f32 v17, v1, v19
	ds_write_b128 v5, v[14:17] offset:9216
	v_add_f32_e32 v2, v33, v3
	ds_read_u16 v1, v9 offset:1152
	v_sub_f32_e32 v2, v0, v2
	v_mul_f32_e32 v2, 0x3fb8aa3b, v2
	v_exp_f32_e32 v2, v2
	v_add_f32_e32 v13, v34, v3
	s_waitcnt lgkmcnt(0)
	v_lshlrev_b32_e32 v1, 16, v1
	v_sub_f32_e32 v13, v0, v13
	v_mul_f32_e32 v1, v2, v1
	ds_read_u16 v2, v9 offset:1296
	v_mul_f32_e32 v13, 0x3fb8aa3b, v13
	v_exp_f32_e32 v13, v13
	v_add_f32_e32 v14, v35, v3
	v_sub_f32_e32 v14, v0, v14
	s_waitcnt lgkmcnt(0)
	v_lshlrev_b32_e32 v2, 16, v2
	v_mul_f32_e32 v2, v13, v2
	ds_read_u16 v13, v9 offset:1440
	v_mul_f32_e32 v14, 0x3fb8aa3b, v14
	v_exp_f32_e32 v14, v14
	v_add_f32_e32 v15, v36, v3
	v_sub_f32_e32 v15, v0, v15
	s_waitcnt lgkmcnt(0)
	v_lshlrev_b32_e32 v13, 16, v13
	v_mul_f32_e32 v13, v14, v13
	ds_read_u16 v14, v9 offset:1584
	v_mul_f32_e32 v15, 0x3fb8aa3b, v15
	v_exp_f32_e32 v15, v15
	v_add_f32_e32 v16, v37, v3
	v_sub_f32_e32 v16, v0, v16
	s_waitcnt lgkmcnt(0)
	v_lshlrev_b32_e32 v14, 16, v14
	v_mul_f32_e32 v15, v15, v14
	ds_read_u16 v14, v9 offset:1728
	v_mul_f32_e32 v16, 0x3fb8aa3b, v16
	v_exp_f32_e32 v16, v16
	v_add_f32_e32 v17, v38, v3
	v_sub_f32_e32 v17, v0, v17
	s_waitcnt lgkmcnt(0)
	v_lshlrev_b32_e32 v14, 16, v14
	v_mul_f32_e32 v16, v16, v14
	ds_read_u16 v14, v9 offset:1872
	v_mul_f32_e32 v17, 0x3fb8aa3b, v17
	v_exp_f32_e32 v17, v17
	v_add_f32_e32 v18, v39, v3
	v_sub_f32_e32 v18, v0, v18
	s_waitcnt lgkmcnt(0)
	v_lshlrev_b32_e32 v14, 16, v14
	v_mul_f32_e32 v17, v17, v14
	ds_read_u16 v14, v9 offset:2016
	v_mul_f32_e32 v18, 0x3fb8aa3b, v18
	v_exp_f32_e32 v18, v18
	v_add_f32_e32 v19, v40, v3
	v_sub_f32_e32 v19, v0, v19
	s_waitcnt lgkmcnt(0)
	v_lshlrev_b32_e32 v14, 16, v14
	v_mul_f32_e32 v18, v18, v14
	ds_read_u16 v14, v9 offset:2160
	v_mul_f32_e32 v19, 0x3fb8aa3b, v19
	v_exp_f32_e32 v19, v19
	s_waitcnt lgkmcnt(0)
	v_lshlrev_b32_e32 v14, 16, v14
	v_mul_f32_e32 v19, v19, v14
	v_cvt_pk_bf16_f32 v14, v1, v2
	v_cvt_pk_bf16_f32 v15, v13, v15
	v_cvt_pk_bf16_f32 v16, v16, v17
	v_cvt_pk_bf16_f32 v17, v18, v19
	ds_write_b128 v5, v[14:17] offset:9232
	v_add_f32_e32 v2, v41, v3
	ds_read_u16 v1, v9 offset:2304
	v_sub_f32_e32 v2, v0, v2
	v_mul_f32_e32 v2, 0x3fb8aa3b, v2
	v_exp_f32_e32 v2, v2
	v_add_f32_e32 v13, v42, v3
	s_waitcnt lgkmcnt(0)
; #define LAS __attribute__((address_space(3)))
; #define LAS __attribute__((address_space(3)))
; DI float bf1(bf16_t v) { return __uint_as_float((unsigned)v << 16); }
; DI u32x4 pack8(const float (&f)[8]) { u32x4 o; o.x = pk(f[0], f[1]); o.y = pk(f[2], f[3]); o.z = pk(f[4], f[5]); o.w = pk(f[6], f[7]); return o; }
; template <int MODE>
; DI void gla4_unit(const bf16_t* z, float* ST, float* DEC, bf16_t* Y, const float* aw_g, const float* ab_g, const float* ng, ldsp lds, int tid, int u) {
;     ...
;     if (MODE == 0) {
; #pragma unroll
;         for (int j = 0; j < 4; ++j) {
;             float f[8];
; #pragma unroll
;             for (int k = 0; k < 8; ++k) { const int i = 8 * j + k; f[k] = bf1(*(LAS bf16_t*)(hr + (32 * half + i) * 144 + d * 2)) * __expf(blast - (bc[i] + pre)); }
;             *(LAS u32x4*)(hr + G4_R1 + d * 144 + (32 * half + 8 * j) * 2) = pack8(f);
;         }
;         if (half == 0) DEC[(size_t)(p * 128 + c) * 64 + d] = __expf(blast);
	v_lshlrev_b32_e32 v1, 16, v1
	v_sub_f32_e32 v13, v0, v13
	v_mul_f32_e32 v1, v2, v1
	ds_read_u16 v2, v9 offset:2448
	v_mul_f32_e32 v13, 0x3fb8aa3b, v13
	v_exp_f32_e32 v13, v13
	v_add_f32_e32 v14, v43, v3
	v_sub_f32_e32 v14, v0, v14
	s_waitcnt lgkmcnt(0)
	v_lshlrev_b32_e32 v2, 16, v2
	v_mul_f32_e32 v2, v13, v2
	ds_read_u16 v13, v9 offset:2592
	v_mul_f32_e32 v14, 0x3fb8aa3b, v14
	v_exp_f32_e32 v14, v14
	v_add_f32_e32 v15, v44, v3
	v_sub_f32_e32 v15, v0, v15
	s_waitcnt lgkmcnt(0)
	v_lshlrev_b32_e32 v13, 16, v13
	v_mul_f32_e32 v13, v14, v13
	ds_read_u16 v14, v9 offset:2736
	v_mul_f32_e32 v15, 0x3fb8aa3b, v15
	v_exp_f32_e32 v15, v15
	v_add_f32_e32 v16, v45, v3
	v_sub_f32_e32 v16, v0, v16
	s_waitcnt lgkmcnt(0)
	v_lshlrev_b32_e32 v14, 16, v14
	v_mul_f32_e32 v15, v15, v14
	ds_read_u16 v14, v9 offset:2880
	v_mul_f32_e32 v16, 0x3fb8aa3b, v16
	v_exp_f32_e32 v16, v16
	v_add_f32_e32 v17, v46, v3
	v_sub_f32_e32 v17, v0, v17
	s_waitcnt lgkmcnt(0)
	v_lshlrev_b32_e32 v14, 16, v14
	v_mul_f32_e32 v16, v16, v14
	ds_read_u16 v14, v9 offset:3024
	v_mul_f32_e32 v17, 0x3fb8aa3b, v17
	v_exp_f32_e32 v17, v17
	v_add_f32_e32 v18, v47, v3
	v_sub_f32_e32 v18, v0, v18
	s_waitcnt lgkmcnt(0)
	v_lshlrev_b32_e32 v14, 16, v14
	v_mul_f32_e32 v17, v17, v14
	ds_read_u16 v14, v9 offset:3168
	v_mul_f32_e32 v18, 0x3fb8aa3b, v18
	v_exp_f32_e32 v18, v18
	v_add_f32_e32 v19, v48, v3
	v_sub_f32_e32 v19, v0, v19
	s_waitcnt lgkmcnt(0)
	v_lshlrev_b32_e32 v14, 16, v14
	v_mul_f32_e32 v18, v18, v14
	ds_read_u16 v14, v9 offset:3312
	v_mul_f32_e32 v19, 0x3fb8aa3b, v19
	v_exp_f32_e32 v19, v19
	s_waitcnt lgkmcnt(0)
	v_lshlrev_b32_e32 v14, 16, v14
	v_mul_f32_e32 v19, v19, v14
	v_cvt_pk_bf16_f32 v14, v1, v2
	v_cvt_pk_bf16_f32 v15, v13, v15
	v_cvt_pk_bf16_f32 v16, v16, v17
	v_cvt_pk_bf16_f32 v17, v18, v19
	ds_write_b128 v5, v[14:17] offset:9248
	v_add_f32_e32 v2, v49, v3
	ds_read_u16 v1, v9 offset:3456
	v_sub_f32_e32 v2, v0, v2
	v_mul_f32_e32 v2, 0x3fb8aa3b, v2
	v_exp_f32_e32 v2, v2
	v_add_f32_e32 v13, v50, v3
	s_waitcnt lgkmcnt(0)
	v_lshlrev_b32_e32 v1, 16, v1
	v_sub_f32_e32 v13, v0, v13
	v_mul_f32_e32 v1, v2, v1
	ds_read_u16 v2, v9 offset:3600
	v_mul_f32_e32 v13, 0x3fb8aa3b, v13
	v_exp_f32_e32 v13, v13
	v_add_f32_e32 v14, v51, v3
	v_sub_f32_e32 v14, v0, v14
	s_waitcnt lgkmcnt(0)
	v_lshlrev_b32_e32 v2, 16, v2
	v_mul_f32_e32 v2, v13, v2
	ds_read_u16 v13, v9 offset:3744
	v_mul_f32_e32 v14, 0x3fb8aa3b, v14
	v_exp_f32_e32 v14, v14
	v_add_f32_e32 v15, v52, v3
	v_sub_f32_e32 v15, v0, v15
	s_waitcnt lgkmcnt(0)
	v_lshlrev_b32_e32 v13, 16, v13
	v_mul_f32_e32 v13, v14, v13
	ds_read_u16 v14, v9 offset:3888
	v_mul_f32_e32 v15, 0x3fb8aa3b, v15
	v_exp_f32_e32 v15, v15
	v_add_f32_e32 v16, v53, v3
	v_sub_f32_e32 v16, v0, v16
	s_waitcnt lgkmcnt(0)
	v_lshlrev_b32_e32 v14, 16, v14
	v_mul_f32_e32 v15, v15, v14
	ds_read_u16 v14, v9 offset:4032
	v_mul_f32_e32 v16, 0x3fb8aa3b, v16
	v_exp_f32_e32 v16, v16
	v_add_f32_e32 v17, v54, v3
	v_sub_f32_e32 v17, v0, v17
	s_waitcnt lgkmcnt(0)
	v_lshlrev_b32_e32 v14, 16, v14
	v_mul_f32_e32 v16, v16, v14
	ds_read_u16 v14, v9 offset:4176
	v_mul_f32_e32 v17, 0x3fb8aa3b, v17
	v_exp_f32_e32 v17, v17
	v_add_f32_e32 v18, v55, v3
	v_add_f32_e32 v3, v3, v8
	s_waitcnt lgkmcnt(0)
	v_lshlrev_b32_e32 v14, 16, v14
	v_mul_f32_e32 v17, v17, v14
	ds_read_u16 v14, v9 offset:4320
	ds_read_u16 v9, v9 offset:4464
	v_sub_f32_e32 v3, v0, v3
	v_sub_f32_e32 v18, v0, v18
	v_mul_f32_e32 v3, 0x3fb8aa3b, v3
	v_mul_f32_e32 v18, 0x3fb8aa3b, v18
	v_exp_f32_e32 v3, v3
	v_exp_f32_e32 v18, v18
	s_waitcnt lgkmcnt(0)
	v_lshlrev_b32_e32 v9, 16, v9
	v_lshlrev_b32_e32 v14, 16, v14
	v_mul_f32_e32 v3, v3, v9
	v_mul_f32_e32 v18, v18, v14
	v_cvt_pk_bf16_f32 v14, v1, v2
	v_cvt_pk_bf16_f32 v15, v13, v15
	v_cvt_pk_bf16_f32 v16, v16, v17
	v_cvt_pk_bf16_f32 v17, v18, v3
	v_lshl_or_b32 v2, v12, 7, s24
	ds_write_b128 v5, v[14:17] offset:9264
	s_and_saveexec_b64 s[0:1], vcc
	s_xor_b64 s[0:1], exec, s[0:1]
	v_ashrrev_i32_e32 v3, 31, v2
	s_andn2_saveexec_b64 s[0:1], s[0:1]
	s_cbranch_execz .LBB0_450
	v_mul_f32_e32 v0, 0x3fb8aa3b, v0
	v_exp_f32_e32 v8, v0
	v_ashrrev_i32_e32 v3, 31, v2
	v_lshlrev_b64 v[0:1], 8, v[2:3]
	v_lshl_add_u64 v[0:1], s[66:67], 0, v[0:1]
	v_lshl_add_u64 v[0:1], v[0:1], 0, v[156:157]
	global_store_dword v[0:1], v8, off
	s_branch .LBB0_450
